# GEMM MFMA-cluster priority flips at level 2 instead of 1 (byte-neutral A/B)
# speedup vs baseline: 1.0005x; 1.0005x over previous
; #define WAIT_L(n) asm volatile("s_waitcnt lgkmcnt(" #n ")" ::: "memory")
; #define BAR __builtin_amdgcn_s_barrier()
; #define SCHED __builtin_amdgcn_sched_barrier(0)
; #define STAGEA(P, BASE, kt) do { const size_t SS_ = ssA; STAGE(P, BASE, kt); } while (0)
; #define STAGEB(P, BASE, kt) do { const size_t SS_ = ssB; STAGE(P, BASE, kt); } while (0)
; #define LDA(dst, b, h) _Pragma("unroll") for (int m = 0; m < 4; ++m) _Pragma("unroll") for (int k = 0; k < 2; ++k) \
;     dst[m][k] = *(const s16x8*)(smem + a_rdo + ((b) * 2 + (h)) * 16384 + m * 2048 + k * 1024)
; #define LDB(dst, b, h) _Pragma("unroll") for (int n = 0; n < 2; ++n) _Pragma("unroll") for (int k = 0; k < 2; ++k) \
;     dst[n][k] = *(const s16x8*)(smem + b_rdo + ((b) * 2 + (h)) * 16384 + n * 2048 + k * 1024)
; #define MMA(ai, bj, Ax, Bx) do { __builtin_amdgcn_s_setprio(1); \
;     _Pragma("unroll") for (int m = 0; m < 4; ++m) _Pragma("unroll") for (int n = 0; n < 2; ++n) _Pragma("unroll") for (int k = 0; k < 2; ++k) \
;       acc[ai][bj][m][n] = MFMA16(Bx[n][k], Ax[m][k], acc[ai][bj][m][n]); \
;     __builtin_amdgcn_s_setprio(0); } while (0)
; template <int EPI>
; __device__ void gemm8(const bf16* A, const bf16* Bt, const int K, const int ntN, const int ntTot, const EpiArgs ea, char* smem) {
;     ...
;       LDB(B0, 0, 0); SCHED; LDA(At, 0, 0); STAGEA(SA(1, 1), A1, t + 1);
;       WAIT_L(8); BAR; WAIT_L(0); MMA(0, 0, At, B0); BAR; SCHED;
;       LDB(B1, 0, 1); STAGEB(SB(0, 0), B0g, t + 2);
;       BAR; WAIT_L(0); MMA(0, 1, At, B1); BAR;
;       LDA(At, 0, 1); STAGEA(SA(0, 0), A0, t + 2);
;       BAR; WAIT_L(0); MMA(1, 0, At, B0); BAR; SCHED;
.LBB0_176:
	s_nop 0
	v_add_u32_e32 v218, 0, v133
	ds_read_b128 v[134:137], v218
	ds_read_b128 v[138:141], v218 offset:1024
	ds_read_b128 v[142:145], v218 offset:2048
	ds_read_b128 v[162:165], v218 offset:3072
	v_lshl_add_u64 v[152:153], s[16:17], 0, v[150:151]
	s_add_i32 s30, s23, 0xc000
	v_add_u32_e32 v219, 0, v132
	v_lshl_add_u64 v[198:199], v[152:153], 0, s[72:73]
	s_mov_b32 m0, s30
	s_add_i32 s1, s23, 0xe000
	ds_read_b128 v[166:169], v219
	ds_read_b128 v[170:173], v219 offset:1024
	ds_read_b128 v[174:177], v219 offset:2048
	ds_read_b128 v[178:181], v219 offset:3072
	ds_read_b128 v[182:185], v219 offset:4096
	ds_read_b128 v[186:189], v219 offset:5120
	ds_read_b128 v[190:193], v219 offset:6144
	ds_read_b128 v[194:197], v219 offset:7168
	global_load_lds_dwordx4 v[198:199], off
	v_lshl_add_u64 v[198:199], v[152:153], 0, s[74:75]
	s_mov_b32 m0, s1
	s_nop 0
	global_load_lds_dwordx4 v[198:199], off
	s_waitcnt lgkmcnt(8)
	s_barrier
	s_waitcnt lgkmcnt(0)
	s_setprio 2
	s_waitcnt lgkmcnt(0)
	v_mfma_f32_16x16x32_bf16 v[126:129], v[134:137], v[166:169], v[126:129]
	v_mfma_f32_16x16x32_bf16 v[122:125], v[142:145], v[166:169], v[122:125]
	v_mfma_f32_16x16x32_bf16 v[118:121], v[134:137], v[174:177], v[118:121]
	v_mfma_f32_16x16x32_bf16 v[114:117], v[142:145], v[174:177], v[114:117]
	v_mfma_f32_16x16x32_bf16 v[106:109], v[134:137], v[182:185], v[106:109]
	v_mfma_f32_16x16x32_bf16 v[90:93], v[142:145], v[182:185], v[90:93]
	v_mfma_f32_16x16x32_bf16 v[74:77], v[134:137], v[190:193], v[74:77]
	v_mfma_f32_16x16x32_bf16 v[54:57], v[142:145], v[190:193], v[54:57]
	v_mfma_f32_16x16x32_bf16 v[126:129], v[138:141], v[170:173], v[126:129]
	v_mfma_f32_16x16x32_bf16 v[122:125], v[162:165], v[170:173], v[122:125]
	v_mfma_f32_16x16x32_bf16 v[118:121], v[138:141], v[178:181], v[118:121]
	v_mfma_f32_16x16x32_bf16 v[114:117], v[162:165], v[178:181], v[114:117]
	v_mfma_f32_16x16x32_bf16 v[106:109], v[138:141], v[186:189], v[106:109]
	v_mfma_f32_16x16x32_bf16 v[90:93], v[162:165], v[186:189], v[90:93]
	v_mfma_f32_16x16x32_bf16 v[74:77], v[138:141], v[194:197], v[74:77]
	v_mfma_f32_16x16x32_bf16 v[54:57], v[162:165], v[194:197], v[54:57]
	s_setprio 0
	s_barrier
	v_lshl_add_u64 v[214:215], s[4:5], 0, v[150:151]
	s_mov_b64 s[50:51], 0xc0000
	s_mov_b32 m0, s11
	v_lshl_add_u64 v[216:217], v[214:215], 0, s[50:51]
	s_mov_b64 s[50:51], 0xc2000
	ds_read_b128 v[198:201], v218 offset:16384
	ds_read_b128 v[202:205], v218 offset:17408
	ds_read_b128 v[206:209], v218 offset:18432
	ds_read_b128 v[210:213], v218 offset:19456
	global_load_lds_dwordx4 v[216:217], off
	v_lshl_add_u64 v[216:217], v[214:215], 0, s[50:51]
	s_mov_b32 m0, s35
	s_nop 0
	global_load_lds_dwordx4 v[216:217], off
	s_barrier
	s_waitcnt lgkmcnt(0)
	s_setprio 2
	s_waitcnt lgkmcnt(0)
	v_mfma_f32_16x16x32_bf16 v[30:33], v[198:201], v[166:169], v[30:33]
	v_mfma_f32_16x16x32_bf16 v[26:29], v[206:209], v[166:169], v[26:29]
	v_mfma_f32_16x16x32_bf16 v[22:25], v[198:201], v[174:177], v[22:25]
	v_mfma_f32_16x16x32_bf16 v[18:21], v[206:209], v[174:177], v[18:21]
	v_mfma_f32_16x16x32_bf16 v[14:17], v[198:201], v[182:185], v[14:17]
	v_mfma_f32_16x16x32_bf16 v[10:13], v[206:209], v[182:185], v[10:13]
	v_mfma_f32_16x16x32_bf16 v[6:9], v[198:201], v[190:193], v[6:9]
	v_mfma_f32_16x16x32_bf16 v[2:5], v[206:209], v[190:193], v[2:5]
	v_mfma_f32_16x16x32_bf16 v[30:33], v[202:205], v[170:173], v[30:33]
	v_mfma_f32_16x16x32_bf16 v[26:29], v[210:213], v[170:173], v[26:29]
	v_mfma_f32_16x16x32_bf16 v[22:25], v[202:205], v[178:181], v[22:25]
	v_mfma_f32_16x16x32_bf16 v[18:21], v[210:213], v[178:181], v[18:21]
	v_mfma_f32_16x16x32_bf16 v[14:17], v[202:205], v[186:189], v[14:17]
	v_mfma_f32_16x16x32_bf16 v[10:13], v[210:213], v[186:189], v[10:13]
	v_mfma_f32_16x16x32_bf16 v[6:9], v[202:205], v[194:197], v[6:9]
	v_mfma_f32_16x16x32_bf16 v[2:5], v[210:213], v[194:197], v[2:5]
	s_setprio 0
	s_mov_b32 m0, s23
	v_lshl_add_u64 v[216:217], v[152:153], 0, s[76:77]
	s_barrier
	ds_read_b128 v[166:169], v219 offset:16384
	ds_read_b128 v[170:173], v219 offset:17408
	ds_read_b128 v[174:177], v219 offset:18432
	ds_read_b128 v[178:181], v219 offset:19456
	ds_read_b128 v[182:185], v219 offset:20480
	ds_read_b128 v[186:189], v219 offset:21504
	ds_read_b128 v[190:193], v219 offset:22528
	ds_read_b128 v[194:197], v219 offset:23552
	global_load_lds_dwordx4 v[216:217], off
	v_lshl_add_u64 v[216:217], v[152:153], 0, s[78:79]
	s_mov_b32 m0, s40
	s_nop 0
	global_load_lds_dwordx4 v[216:217], off
	s_barrier
	s_waitcnt lgkmcnt(0)
	s_setprio 2
	s_waitcnt lgkmcnt(0)
	v_mfma_f32_16x16x32_bf16 v[34:37], v[134:137], v[166:169], v[34:37]
	v_mfma_f32_16x16x32_bf16 v[38:41], v[142:145], v[166:169], v[38:41]
	v_mfma_f32_16x16x32_bf16 v[42:45], v[134:137], v[174:177], v[42:45]
	v_mfma_f32_16x16x32_bf16 v[46:49], v[142:145], v[174:177], v[46:49]
	v_mfma_f32_16x16x32_bf16 v[50:53], v[134:137], v[182:185], v[50:53]
	v_mfma_f32_16x16x32_bf16 v[58:61], v[142:145], v[182:185], v[58:61]
	v_mfma_f32_16x16x32_bf16 v[62:65], v[134:137], v[190:193], v[62:65]
	v_mfma_f32_16x16x32_bf16 v[66:69], v[142:145], v[190:193], v[66:69]
	v_mfma_f32_16x16x32_bf16 v[34:37], v[138:141], v[170:173], v[34:37]
	v_mfma_f32_16x16x32_bf16 v[38:41], v[162:165], v[170:173], v[38:41]
	v_mfma_f32_16x16x32_bf16 v[42:45], v[138:141], v[178:181], v[42:45]
	v_mfma_f32_16x16x32_bf16 v[46:49], v[162:165], v[178:181], v[46:49]
	v_mfma_f32_16x16x32_bf16 v[50:53], v[138:141], v[186:189], v[50:53]
	v_mfma_f32_16x16x32_bf16 v[58:61], v[162:165], v[186:189], v[58:61]
	v_mfma_f32_16x16x32_bf16 v[62:65], v[138:141], v[194:197], v[62:65]
	v_mfma_f32_16x16x32_bf16 v[66:69], v[162:165], v[194:197], v[66:69]
	s_setprio 0
	s_barrier
; #define WAIT_V(n) asm volatile("s_waitcnt vmcnt(" #n ")" ::: "memory")
; #define WAIT_L(n) asm volatile("s_waitcnt lgkmcnt(" #n ")" ::: "memory")
; #define BAR __builtin_amdgcn_s_barrier()
; #define SCHED __builtin_amdgcn_sched_barrier(0)
; #define STAGEA(P, BASE, kt) do { const size_t SS_ = ssA; STAGE(P, BASE, kt); } while (0)
; #define STAGEB(P, BASE, kt) do { const size_t SS_ = ssB; STAGE(P, BASE, kt); } while (0)
; #define LDA(dst, b, h) _Pragma("unroll") for (int m = 0; m < 4; ++m) _Pragma("unroll") for (int k = 0; k < 2; ++k) \
;     dst[m][k] = *(const s16x8*)(smem + a_rdo + ((b) * 2 + (h)) * 16384 + m * 2048 + k * 1024)
; #define LDB(dst, b, h) _Pragma("unroll") for (int n = 0; n < 2; ++n) _Pragma("unroll") for (int k = 0; k < 2; ++k) \
;     dst[n][k] = *(const s16x8*)(smem + b_rdo + ((b) * 2 + (h)) * 16384 + n * 2048 + k * 1024)
; #define MMA(ai, bj, Ax, Bx) do { __builtin_amdgcn_s_setprio(1); \
;     _Pragma("unroll") for (int m = 0; m < 4; ++m) _Pragma("unroll") for (int n = 0; n < 2; ++n) _Pragma("unroll") for (int k = 0; k < 2; ++k) \
;       acc[ai][bj][m][n] = MFMA16(Bx[n][k], Ax[m][k], acc[ai][bj][m][n]); \
;     __builtin_amdgcn_s_setprio(0); } while (0)
; template <int EPI>
; __device__ void gemm8(const bf16* A, const bf16* Bt, const int K, const int ntN, const int ntTot, const EpiArgs ea, char* smem) {
;     ...
;       STAGEB(SB(0, 1), B1g, t + 2);
;       WAIT_V(6); BAR; MMA(1, 1, At, B1); BAR;
;       LDB(B0, 1, 0); SCHED; LDA(At, 1, 0); STAGEA(SA(0, 1), A1, t + 2);
;       WAIT_L(8); BAR; WAIT_L(0); MMA(0, 0, At, B0); BAR; SCHED;
;       LDB(B1, 1, 1); STAGEB(SB(1, 0), B0g, t + 3);
;       BAR; WAIT_L(0); MMA(0, 1, At, B1); BAR;
;       LDA(At, 1, 1); STAGEA(SA(1, 0), A0, t + 3);
	s_mov_b64 s[50:51], 0xc4000
	s_mov_b32 m0, s41
	v_lshl_add_u64 v[134:135], v[214:215], 0, s[50:51]
	s_mov_b64 s[50:51], 0xc6000
	global_load_lds_dwordx4 v[134:135], off
	v_lshl_add_u64 v[134:135], v[214:215], 0, s[50:51]
	s_mov_b32 m0, s43
	s_nop 0
	global_load_lds_dwordx4 v[134:135], off
	s_waitcnt vmcnt(6)
	s_barrier
	s_setprio 2
	v_mfma_f32_16x16x32_bf16 v[70:73], v[198:201], v[166:169], v[70:73]
	v_mfma_f32_16x16x32_bf16 v[78:81], v[206:209], v[166:169], v[78:81]
	v_mfma_f32_16x16x32_bf16 v[82:85], v[198:201], v[174:177], v[82:85]
	v_mfma_f32_16x16x32_bf16 v[86:89], v[206:209], v[174:177], v[86:89]
	v_mfma_f32_16x16x32_bf16 v[94:97], v[198:201], v[182:185], v[94:97]
	v_mfma_f32_16x16x32_bf16 v[98:101], v[206:209], v[182:185], v[98:101]
	v_mfma_f32_16x16x32_bf16 v[102:105], v[198:201], v[190:193], v[102:105]
	v_mfma_f32_16x16x32_bf16 v[110:113], v[206:209], v[190:193], v[110:113]
	v_mfma_f32_16x16x32_bf16 v[70:73], v[202:205], v[170:173], v[70:73]
	v_mfma_f32_16x16x32_bf16 v[78:81], v[210:213], v[170:173], v[78:81]
	v_mfma_f32_16x16x32_bf16 v[82:85], v[202:205], v[178:181], v[82:85]
	v_mfma_f32_16x16x32_bf16 v[86:89], v[210:213], v[178:181], v[86:89]
	v_mfma_f32_16x16x32_bf16 v[94:97], v[202:205], v[186:189], v[94:97]
	v_mfma_f32_16x16x32_bf16 v[98:101], v[210:213], v[186:189], v[98:101]
	v_mfma_f32_16x16x32_bf16 v[102:105], v[202:205], v[194:197], v[102:105]
	v_mfma_f32_16x16x32_bf16 v[110:113], v[210:213], v[194:197], v[110:113]
	s_setprio 0
	s_barrier
	ds_read_b128 v[134:137], v218 offset:32768
	ds_read_b128 v[138:141], v218 offset:33792
	ds_read_b128 v[142:145], v218 offset:34816
	ds_read_b128 v[162:165], v218 offset:35840
	s_mov_b32 m0, s44
	v_lshl_add_u64 v[198:199], v[152:153], 0, s[80:81]
	ds_read_b128 v[166:169], v219 offset:32768
	ds_read_b128 v[170:173], v219 offset:33792
	ds_read_b128 v[174:177], v219 offset:34816
	ds_read_b128 v[178:181], v219 offset:35840
	ds_read_b128 v[182:185], v219 offset:36864
	ds_read_b128 v[186:189], v219 offset:37888
	ds_read_b128 v[190:193], v219 offset:38912
	ds_read_b128 v[194:197], v219 offset:39936
	global_load_lds_dwordx4 v[198:199], off
	v_lshl_add_u64 v[198:199], v[152:153], 0, s[82:83]
	s_mov_b32 m0, s45
	s_nop 0
	global_load_lds_dwordx4 v[198:199], off
	s_waitcnt lgkmcnt(8)
	s_barrier
	s_waitcnt lgkmcnt(0)
	s_setprio 2
	s_waitcnt lgkmcnt(0)
	v_mfma_f32_16x16x32_bf16 v[126:129], v[134:137], v[166:169], v[126:129]
	v_mfma_f32_16x16x32_bf16 v[122:125], v[142:145], v[166:169], v[122:125]
	v_mfma_f32_16x16x32_bf16 v[118:121], v[134:137], v[174:177], v[118:121]
	v_mfma_f32_16x16x32_bf16 v[114:117], v[142:145], v[174:177], v[114:117]
	v_mfma_f32_16x16x32_bf16 v[106:109], v[134:137], v[182:185], v[106:109]
	v_mfma_f32_16x16x32_bf16 v[90:93], v[142:145], v[182:185], v[90:93]
	v_mfma_f32_16x16x32_bf16 v[74:77], v[134:137], v[190:193], v[74:77]
	v_mfma_f32_16x16x32_bf16 v[54:57], v[142:145], v[190:193], v[54:57]
	v_mfma_f32_16x16x32_bf16 v[126:129], v[138:141], v[170:173], v[126:129]
	v_mfma_f32_16x16x32_bf16 v[122:125], v[162:165], v[170:173], v[122:125]
	v_mfma_f32_16x16x32_bf16 v[118:121], v[138:141], v[178:181], v[118:121]
	v_mfma_f32_16x16x32_bf16 v[114:117], v[162:165], v[178:181], v[114:117]
	v_mfma_f32_16x16x32_bf16 v[106:109], v[138:141], v[186:189], v[106:109]
	v_mfma_f32_16x16x32_bf16 v[90:93], v[162:165], v[186:189], v[90:93]
	v_mfma_f32_16x16x32_bf16 v[74:77], v[138:141], v[194:197], v[74:77]
	v_mfma_f32_16x16x32_bf16 v[54:57], v[162:165], v[194:197], v[54:57]
	s_setprio 0
	s_barrier
	s_mov_b64 s[50:51], 0x120000
	s_mov_b32 m0, s2
	v_lshl_add_u64 v[216:217], v[214:215], 0, s[50:51]
	s_mov_b64 s[50:51], 0x122000
	ds_read_b128 v[198:201], v218 offset:49152
	ds_read_b128 v[202:205], v218 offset:50176
	ds_read_b128 v[206:209], v218 offset:51200
	ds_read_b128 v[210:213], v218 offset:52224
	global_load_lds_dwordx4 v[216:217], off
	v_lshl_add_u64 v[216:217], v[214:215], 0, s[50:51]
	s_mov_b32 m0, s3
	s_nop 0
	global_load_lds_dwordx4 v[216:217], off
	s_barrier
	s_waitcnt lgkmcnt(0)
	s_setprio 2
	s_waitcnt lgkmcnt(0)
	v_mfma_f32_16x16x32_bf16 v[30:33], v[198:201], v[166:169], v[30:33]
	v_mfma_f32_16x16x32_bf16 v[26:29], v[206:209], v[166:169], v[26:29]
	v_mfma_f32_16x16x32_bf16 v[22:25], v[198:201], v[174:177], v[22:25]
	v_mfma_f32_16x16x32_bf16 v[18:21], v[206:209], v[174:177], v[18:21]
	v_mfma_f32_16x16x32_bf16 v[14:17], v[198:201], v[182:185], v[14:17]
	v_mfma_f32_16x16x32_bf16 v[10:13], v[206:209], v[182:185], v[10:13]
	v_mfma_f32_16x16x32_bf16 v[6:9], v[198:201], v[190:193], v[6:9]
	v_mfma_f32_16x16x32_bf16 v[2:5], v[206:209], v[190:193], v[2:5]
	v_mfma_f32_16x16x32_bf16 v[30:33], v[202:205], v[170:173], v[30:33]
	v_mfma_f32_16x16x32_bf16 v[26:29], v[210:213], v[170:173], v[26:29]
	v_mfma_f32_16x16x32_bf16 v[22:25], v[202:205], v[178:181], v[22:25]
	v_mfma_f32_16x16x32_bf16 v[18:21], v[210:213], v[178:181], v[18:21]
	v_mfma_f32_16x16x32_bf16 v[14:17], v[202:205], v[186:189], v[14:17]
	v_mfma_f32_16x16x32_bf16 v[10:13], v[210:213], v[186:189], v[10:13]
	v_mfma_f32_16x16x32_bf16 v[6:9], v[202:205], v[194:197], v[6:9]
	v_mfma_f32_16x16x32_bf16 v[2:5], v[210:213], v[194:197], v[2:5]
	s_setprio 0
	s_mov_b32 m0, s46
	v_lshl_add_u64 v[216:217], v[152:153], 0, s[84:85]
	s_barrier
	ds_read_b128 v[166:169], v219 offset:49152
	ds_read_b128 v[170:173], v219 offset:50176
	ds_read_b128 v[174:177], v219 offset:51200
	ds_read_b128 v[178:181], v219 offset:52224
	ds_read_b128 v[182:185], v219 offset:53248
	ds_read_b128 v[186:189], v219 offset:54272
	ds_read_b128 v[190:193], v219 offset:55296
	ds_read_b128 v[194:197], v219 offset:56320
	global_load_lds_dwordx4 v[216:217], off
	v_lshl_add_u64 v[152:153], v[152:153], 0, s[86:87]
	s_mov_b32 m0, s47
	s_nop 0
	global_load_lds_dwordx4 v[152:153], off
	s_barrier
; #define WAIT_V(n) asm volatile("s_waitcnt vmcnt(" #n ")" ::: "memory")
; #define WAIT_L(n) asm volatile("s_waitcnt lgkmcnt(" #n ")" ::: "memory")
; #define BAR __builtin_amdgcn_s_barrier()
; #define SCHED __builtin_amdgcn_sched_barrier(0)
; #define STAGEA(P, BASE, kt) do { const size_t SS_ = ssA; STAGE(P, BASE, kt); } while (0)
; #define STAGEB(P, BASE, kt) do { const size_t SS_ = ssB; STAGE(P, BASE, kt); } while (0)
; #define LDA(dst, b, h) _Pragma("unroll") for (int m = 0; m < 4; ++m) _Pragma("unroll") for (int k = 0; k < 2; ++k) \
;     dst[m][k] = *(const s16x8*)(smem + a_rdo + ((b) * 2 + (h)) * 16384 + m * 2048 + k * 1024)
; #define LDB(dst, b, h) _Pragma("unroll") for (int n = 0; n < 2; ++n) _Pragma("unroll") for (int k = 0; k < 2; ++k) \
;     dst[n][k] = *(const s16x8*)(smem + b_rdo + ((b) * 2 + (h)) * 16384 + n * 2048 + k * 1024)
; #define MMA(ai, bj, Ax, Bx) do { __builtin_amdgcn_s_setprio(1); \
;     _Pragma("unroll") for (int m = 0; m < 4; ++m) _Pragma("unroll") for (int n = 0; n < 2; ++n) _Pragma("unroll") for (int k = 0; k < 2; ++k) \
;       acc[ai][bj][m][n] = MFMA16(Bx[n][k], Ax[m][k], acc[ai][bj][m][n]); \
;     __builtin_amdgcn_s_setprio(0); } while (0)
; template <int EPI>
; __device__ void gemm8(const bf16* A, const bf16* Bt, const int K, const int ntN, const int ntTot, const EpiArgs ea, char* smem) {
;     ...
;       BAR; WAIT_L(0); MMA(1, 0, At, B0); BAR; SCHED;
;       STAGEB(SB(1, 1), B1g, t + 3);
;       WAIT_V(6); BAR; MMA(1, 1, At, B1); BAR;
;     }
;     asm volatile("" : "+v"(a_rdo), "+v"(b_rdo));
;     { LDB(B0, 0, 0); LDA(At, 0, 0); STAGEA(SA(1, 1), A1, nt - 1);
;       BAR; WAIT_L(0); MMA(0, 0, At, B0); BAR;
;       LDB(B1, 0, 1); BAR; WAIT_L(0); MMA(0, 1, At, B1); BAR;
	s_waitcnt lgkmcnt(0)
	s_setprio 2
	s_waitcnt lgkmcnt(0)
	v_mfma_f32_16x16x32_bf16 v[34:37], v[134:137], v[166:169], v[34:37]
	v_mfma_f32_16x16x32_bf16 v[38:41], v[142:145], v[166:169], v[38:41]
	v_mfma_f32_16x16x32_bf16 v[42:45], v[134:137], v[174:177], v[42:45]
	v_mfma_f32_16x16x32_bf16 v[46:49], v[142:145], v[174:177], v[46:49]
	v_mfma_f32_16x16x32_bf16 v[50:53], v[134:137], v[182:185], v[50:53]
	v_mfma_f32_16x16x32_bf16 v[58:61], v[142:145], v[182:185], v[58:61]
	v_mfma_f32_16x16x32_bf16 v[62:65], v[134:137], v[190:193], v[62:65]
	v_mfma_f32_16x16x32_bf16 v[66:69], v[142:145], v[190:193], v[66:69]
	v_mfma_f32_16x16x32_bf16 v[34:37], v[138:141], v[170:173], v[34:37]
	v_mfma_f32_16x16x32_bf16 v[38:41], v[162:165], v[170:173], v[38:41]
	v_mfma_f32_16x16x32_bf16 v[42:45], v[138:141], v[178:181], v[42:45]
	v_mfma_f32_16x16x32_bf16 v[46:49], v[162:165], v[178:181], v[46:49]
	v_mfma_f32_16x16x32_bf16 v[50:53], v[138:141], v[186:189], v[50:53]
	v_mfma_f32_16x16x32_bf16 v[58:61], v[162:165], v[186:189], v[58:61]
	v_mfma_f32_16x16x32_bf16 v[62:65], v[138:141], v[194:197], v[62:65]
	v_mfma_f32_16x16x32_bf16 v[66:69], v[162:165], v[194:197], v[66:69]
	s_setprio 0
	s_barrier
	s_mov_b64 s[50:51], 0x124000
	s_mov_b32 m0, s48
	v_lshl_add_u64 v[134:135], v[214:215], 0, s[50:51]
	s_mov_b64 s[50:51], 0x126000
	global_load_lds_dwordx4 v[134:135], off
	v_lshl_add_u64 v[134:135], v[214:215], 0, s[50:51]
	s_mov_b32 m0, s49
	s_nop 0
	global_load_lds_dwordx4 v[134:135], off
	s_waitcnt vmcnt(6)
	s_barrier
	s_setprio 2
	v_mfma_f32_16x16x32_bf16 v[70:73], v[198:201], v[166:169], v[70:73]
	v_mfma_f32_16x16x32_bf16 v[78:81], v[206:209], v[166:169], v[78:81]
	v_mfma_f32_16x16x32_bf16 v[82:85], v[198:201], v[174:177], v[82:85]
	v_mfma_f32_16x16x32_bf16 v[86:89], v[206:209], v[174:177], v[86:89]
	v_mfma_f32_16x16x32_bf16 v[94:97], v[198:201], v[182:185], v[94:97]
	v_mfma_f32_16x16x32_bf16 v[98:101], v[206:209], v[182:185], v[98:101]
	v_mfma_f32_16x16x32_bf16 v[102:105], v[198:201], v[190:193], v[102:105]
	v_mfma_f32_16x16x32_bf16 v[110:113], v[206:209], v[190:193], v[110:113]
	v_mfma_f32_16x16x32_bf16 v[70:73], v[202:205], v[170:173], v[70:73]
	v_mfma_f32_16x16x32_bf16 v[78:81], v[210:213], v[170:173], v[78:81]
	v_mfma_f32_16x16x32_bf16 v[82:85], v[202:205], v[178:181], v[82:85]
	v_mfma_f32_16x16x32_bf16 v[86:89], v[210:213], v[178:181], v[86:89]
	v_mfma_f32_16x16x32_bf16 v[94:97], v[202:205], v[186:189], v[94:97]
	v_mfma_f32_16x16x32_bf16 v[98:101], v[210:213], v[186:189], v[98:101]
	v_mfma_f32_16x16x32_bf16 v[102:105], v[202:205], v[194:197], v[102:105]
	v_mfma_f32_16x16x32_bf16 v[110:113], v[210:213], v[194:197], v[110:113]
	s_setprio 0
	s_add_i32 s0, s0, 2
	s_add_u32 s16, s16, 0x400000
	s_addc_u32 s17, s17, 0
	s_add_u32 s4, s4, 0xc0000
	s_addc_u32 s5, s5, 0
	s_cmp_gt_u32 s0, 11
	s_barrier
	s_cbranch_scc0 .LBB0_176
	s_mov_b64 s[2:3], 0x1e04000
	s_mov_b32 m0, s30
	v_add_u32_e32 v152, 0, v133
	v_add_u32_e32 v153, 0, v132
	v_lshl_add_u64 v[132:133], v[130:131], 0, s[2:3]
	s_mov_b64 s[2:3], 0x1e06000
	ds_read_b128 v[134:137], v152
	ds_read_b128 v[138:141], v152 offset:1024
	ds_read_b128 v[142:145], v152 offset:2048
	ds_read_b128 v[162:165], v152 offset:3072
	ds_read_b128 v[166:169], v153
	ds_read_b128 v[170:173], v153 offset:1024
	ds_read_b128 v[174:177], v153 offset:2048
	ds_read_b128 v[178:181], v153 offset:3072
	ds_read_b128 v[182:185], v153 offset:4096
	ds_read_b128 v[186:189], v153 offset:5120
	ds_read_b128 v[190:193], v153 offset:6144
	ds_read_b128 v[194:197], v153 offset:7168
	global_load_lds_dwordx4 v[132:133], off
	v_lshl_add_u64 v[130:131], v[130:131], 0, s[2:3]
	s_mov_b32 m0, s1
	s_nop 0
	global_load_lds_dwordx4 v[130:131], off
	s_barrier
	s_waitcnt lgkmcnt(0)
	s_setprio 2
	s_waitcnt lgkmcnt(0)
	v_mfma_f32_16x16x32_bf16 v[126:129], v[134:137], v[166:169], v[126:129]
	v_mfma_f32_16x16x32_bf16 v[122:125], v[142:145], v[166:169], v[122:125]
	v_mfma_f32_16x16x32_bf16 v[106:109], v[134:137], v[182:185], v[106:109]
	v_mfma_f32_16x16x32_bf16 v[90:93], v[142:145], v[182:185], v[90:93]
	v_mfma_f32_16x16x32_bf16 v[74:77], v[134:137], v[190:193], v[74:77]
	v_mfma_f32_16x16x32_bf16 v[54:57], v[142:145], v[190:193], v[54:57]
	v_mfma_f32_16x16x32_bf16 v[126:129], v[138:141], v[170:173], v[126:129]
	v_mfma_f32_16x16x32_bf16 v[122:125], v[162:165], v[170:173], v[122:125]
	v_mfma_f32_16x16x32_bf16 v[118:121], v[134:137], v[174:177], v[118:121]
	v_mfma_f32_16x16x32_bf16 v[114:117], v[142:145], v[174:177], v[114:117]
	v_mfma_f32_16x16x32_bf16 v[106:109], v[138:141], v[186:189], v[106:109]
	v_mfma_f32_16x16x32_bf16 v[90:93], v[162:165], v[186:189], v[90:93]
	v_mfma_f32_16x16x32_bf16 v[74:77], v[138:141], v[194:197], v[74:77]
	v_mfma_f32_16x16x32_bf16 v[54:57], v[162:165], v[194:197], v[54:57]
	v_mfma_f32_16x16x32_bf16 v[130:133], v[138:141], v[178:181], v[118:121]
	v_mfma_f32_16x16x32_bf16 v[198:201], v[162:165], v[178:181], v[114:117]
	s_setprio 0
	s_barrier
	s_nop 0
	ds_read_b128 v[114:117], v152 offset:16384
	ds_read_b128 v[118:121], v152 offset:17408
	ds_read_b128 v[202:205], v152 offset:18432
	ds_read_b128 v[206:209], v152 offset:19456
	s_barrier
; #define WAIT_V(n) asm volatile("s_waitcnt vmcnt(" #n ")" ::: "memory")
; #define WAIT_L(n) asm volatile("s_waitcnt lgkmcnt(" #n ")" ::: "memory")
; #define BAR __builtin_amdgcn_s_barrier()
; #define LDA(dst, b, h) _Pragma("unroll") for (int m = 0; m < 4; ++m) _Pragma("unroll") for (int k = 0; k < 2; ++k) \
;     dst[m][k] = *(const s16x8*)(smem + a_rdo + ((b) * 2 + (h)) * 16384 + m * 2048 + k * 1024)
; #define LDB(dst, b, h) _Pragma("unroll") for (int n = 0; n < 2; ++n) _Pragma("unroll") for (int k = 0; k < 2; ++k) \
;     dst[n][k] = *(const s16x8*)(smem + b_rdo + ((b) * 2 + (h)) * 16384 + n * 2048 + k * 1024)
; #define MMA(ai, bj, Ax, Bx) do { __builtin_amdgcn_s_setprio(1); \
;     _Pragma("unroll") for (int m = 0; m < 4; ++m) _Pragma("unroll") for (int n = 0; n < 2; ++n) _Pragma("unroll") for (int k = 0; k < 2; ++k) \
;       acc[ai][bj][m][n] = MFMA16(Bx[n][k], Ax[m][k], acc[ai][bj][m][n]); \
;     __builtin_amdgcn_s_setprio(0); } while (0)
; template <int EPI>
; __device__ void gemm8(const bf16* A, const bf16* Bt, const int K, const int ntN, const int ntTot, const EpiArgs ea, char* smem) {
;     ...
;       LDB(B1, 0, 1); BAR; WAIT_L(0); MMA(0, 1, At, B1); BAR;
;       LDA(At, 0, 1); WAIT_V(4); BAR; WAIT_L(0); MMA(1, 0, At, B0); MMA(1, 1, At, B1); BAR; }
;     { LDB(B0, 1, 0); LDA(At, 1, 0); WAIT_V(2); BAR; WAIT_L(0); MMA(0, 0, At, B0); BAR;
	s_waitcnt lgkmcnt(0)
	s_setprio 2
	s_waitcnt lgkmcnt(0)
	v_mfma_f32_16x16x32_bf16 v[30:33], v[114:117], v[166:169], v[30:33]
	v_mfma_f32_16x16x32_bf16 v[26:29], v[202:205], v[166:169], v[26:29]
	v_mfma_f32_16x16x32_bf16 v[22:25], v[114:117], v[174:177], v[22:25]
	v_mfma_f32_16x16x32_bf16 v[18:21], v[202:205], v[174:177], v[18:21]
	v_mfma_f32_16x16x32_bf16 v[14:17], v[114:117], v[182:185], v[14:17]
	v_mfma_f32_16x16x32_bf16 v[10:13], v[202:205], v[182:185], v[10:13]
	v_mfma_f32_16x16x32_bf16 v[6:9], v[114:117], v[190:193], v[6:9]
	v_mfma_f32_16x16x32_bf16 v[2:5], v[202:205], v[190:193], v[2:5]
	v_mfma_f32_16x16x32_bf16 v[30:33], v[118:121], v[170:173], v[30:33]
	v_mfma_f32_16x16x32_bf16 v[26:29], v[206:209], v[170:173], v[26:29]
	v_mfma_f32_16x16x32_bf16 v[22:25], v[118:121], v[178:181], v[22:25]
	v_mfma_f32_16x16x32_bf16 v[18:21], v[206:209], v[178:181], v[18:21]
	v_mfma_f32_16x16x32_bf16 v[14:17], v[118:121], v[186:189], v[14:17]
	v_mfma_f32_16x16x32_bf16 v[10:13], v[206:209], v[186:189], v[10:13]
	v_mfma_f32_16x16x32_bf16 v[6:9], v[118:121], v[194:197], v[6:9]
	v_mfma_f32_16x16x32_bf16 v[2:5], v[206:209], v[194:197], v[2:5]
	s_setprio 0
	s_barrier
	ds_read_b128 v[166:169], v153 offset:16384
	ds_read_b128 v[170:173], v153 offset:17408
	ds_read_b128 v[174:177], v153 offset:18432
	ds_read_b128 v[178:181], v153 offset:19456
	ds_read_b128 v[182:185], v153 offset:20480
	ds_read_b128 v[186:189], v153 offset:21504
	ds_read_b128 v[190:193], v153 offset:22528
	ds_read_b128 v[194:197], v153 offset:23552
	s_waitcnt vmcnt(4)
	s_barrier
	s_waitcnt lgkmcnt(0)
	s_setprio 2
	s_waitcnt lgkmcnt(0)
	v_mfma_f32_16x16x32_bf16 v[50:53], v[134:137], v[182:185], v[50:53]
	v_mfma_f32_16x16x32_bf16 v[210:213], v[138:141], v[186:189], v[50:53]
	v_mfma_f32_16x16x32_bf16 v[50:53], v[142:145], v[182:185], v[58:61]
	v_mfma_f32_16x16x32_bf16 v[34:37], v[134:137], v[166:169], v[34:37]
	v_mfma_f32_16x16x32_bf16 v[38:41], v[142:145], v[166:169], v[38:41]
	v_mfma_f32_16x16x32_bf16 v[42:45], v[134:137], v[174:177], v[42:45]
	v_mfma_f32_16x16x32_bf16 v[46:49], v[142:145], v[174:177], v[46:49]
	v_mfma_f32_16x16x32_bf16 v[58:61], v[162:165], v[186:189], v[50:53]
	v_mfma_f32_16x16x32_bf16 v[50:53], v[134:137], v[190:193], v[62:65]
	v_mfma_f32_16x16x32_bf16 v[34:37], v[138:141], v[170:173], v[34:37]
	v_mfma_f32_16x16x32_bf16 v[38:41], v[162:165], v[170:173], v[38:41]
	v_mfma_f32_16x16x32_bf16 v[42:45], v[138:141], v[178:181], v[42:45]
	v_mfma_f32_16x16x32_bf16 v[46:49], v[162:165], v[178:181], v[46:49]
	v_mfma_f32_16x16x32_bf16 v[62:65], v[138:141], v[194:197], v[50:53]
	v_mfma_f32_16x16x32_bf16 v[50:53], v[142:145], v[190:193], v[66:69]
	v_mfma_f32_16x16x32_bf16 v[134:137], v[162:165], v[194:197], v[50:53]
	s_setprio 0
	s_setprio 2
	v_mfma_f32_16x16x32_bf16 v[50:53], v[114:117], v[166:169], v[70:73]
	v_mfma_f32_16x16x32_bf16 v[138:141], v[118:121], v[170:173], v[50:53]
	v_mfma_f32_16x16x32_bf16 v[50:53], v[202:205], v[166:169], v[78:81]
	v_mfma_f32_16x16x32_bf16 v[142:145], v[206:209], v[170:173], v[50:53]
	v_mfma_f32_16x16x32_bf16 v[50:53], v[114:117], v[174:177], v[82:85]
	v_mfma_f32_16x16x32_bf16 v[162:165], v[118:121], v[178:181], v[50:53]
	v_mfma_f32_16x16x32_bf16 v[50:53], v[202:205], v[174:177], v[86:89]
	v_mfma_f32_16x16x32_bf16 v[166:169], v[206:209], v[178:181], v[50:53]
	v_mfma_f32_16x16x32_bf16 v[50:53], v[114:117], v[182:185], v[94:97]
	v_mfma_f32_16x16x32_bf16 v[170:173], v[118:121], v[186:189], v[50:53]
	v_mfma_f32_16x16x32_bf16 v[50:53], v[202:205], v[182:185], v[98:101]
	v_mfma_f32_16x16x32_bf16 v[174:177], v[206:209], v[186:189], v[50:53]
	v_mfma_f32_16x16x32_bf16 v[50:53], v[114:117], v[190:193], v[102:105]
	v_mfma_f32_16x16x32_bf16 v[178:181], v[118:121], v[194:197], v[50:53]
	v_mfma_f32_16x16x32_bf16 v[50:53], v[202:205], v[190:193], v[110:113]
	v_mfma_f32_16x16x32_bf16 v[182:185], v[206:209], v[194:197], v[50:53]
	s_setprio 0
	s_barrier
	ds_read_b128 v[186:189], v152 offset:32768
	ds_read_b128 v[190:193], v152 offset:33792
	ds_read_b128 v[194:197], v152 offset:34816
	ds_read_b128 v[202:205], v152 offset:35840
	s_nop 0
	ds_read_b128 v[50:53], v153 offset:32768
	ds_read_b128 v[78:81], v153 offset:33792
	ds_read_b128 v[94:97], v153 offset:34816
	ds_read_b128 v[206:209], v153 offset:35840
	ds_read_b128 v[214:217], v153 offset:36864
	ds_read_b128 v[218:221], v153 offset:37888
	ds_read_b128 v[222:225], v153 offset:38912
	ds_read_b128 v[238:241], v153 offset:39936
	s_waitcnt vmcnt(2)
	s_barrier
; #define WAIT_V(n) asm volatile("s_waitcnt vmcnt(" #n ")" ::: "memory")
; #define WAIT_L(n) asm volatile("s_waitcnt lgkmcnt(" #n ")" ::: "memory")
; #define BAR __builtin_amdgcn_s_barrier()
; #define LDA(dst, b, h) _Pragma("unroll") for (int m = 0; m < 4; ++m) _Pragma("unroll") for (int k = 0; k < 2; ++k) \
;     dst[m][k] = *(const s16x8*)(smem + a_rdo + ((b) * 2 + (h)) * 16384 + m * 2048 + k * 1024)
; #define LDB(dst, b, h) _Pragma("unroll") for (int n = 0; n < 2; ++n) _Pragma("unroll") for (int k = 0; k < 2; ++k) \
;     dst[n][k] = *(const s16x8*)(smem + b_rdo + ((b) * 2 + (h)) * 16384 + n * 2048 + k * 1024)
; #define MMA(ai, bj, Ax, Bx) do { __builtin_amdgcn_s_setprio(1); \
;     _Pragma("unroll") for (int m = 0; m < 4; ++m) _Pragma("unroll") for (int n = 0; n < 2; ++n) _Pragma("unroll") for (int k = 0; k < 2; ++k) \
;       acc[ai][bj][m][n] = MFMA16(Bx[n][k], Ax[m][k], acc[ai][bj][m][n]); \
;     __builtin_amdgcn_s_setprio(0); } while (0)
; template <int EPI>
; __device__ void gemm8(const bf16* A, const bf16* Bt, const int K, const int ntN, const int ntTot, const EpiArgs ea, char* smem) {
;     ...
;     { LDB(B0, 1, 0); LDA(At, 1, 0); WAIT_V(2); BAR; WAIT_L(0); MMA(0, 0, At, B0); BAR;
;       LDB(B1, 1, 1); WAIT_V(0); BAR; WAIT_L(0); MMA(0, 1, At, B1); BAR;
;       LDA(At, 1, 1); BAR; WAIT_L(0); MMA(1, 0, At, B0); MMA(1, 1, At, B1); BAR; }
;     if (wr == 0) BAR;
	s_waitcnt lgkmcnt(0)
	s_setprio 2
	s_waitcnt lgkmcnt(0)
	v_mfma_f32_16x16x32_bf16 v[66:69], v[186:189], v[50:53], v[126:129]
	v_mfma_f32_16x16x32_bf16 v[118:121], v[190:193], v[78:81], v[66:69]
	v_mfma_f32_16x16x32_bf16 v[66:69], v[194:197], v[50:53], v[122:125]
	v_mfma_f32_16x16x32_bf16 v[114:117], v[202:205], v[78:81], v[66:69]
	v_mfma_f32_16x16x32_bf16 v[66:69], v[186:189], v[94:97], v[130:133]
	v_mfma_f32_16x16x32_bf16 v[102:105], v[190:193], v[206:209], v[66:69]
	v_mfma_f32_16x16x32_bf16 v[66:69], v[194:197], v[94:97], v[198:201]
	v_mfma_f32_16x16x32_bf16 v[98:101], v[202:205], v[206:209], v[66:69]
	v_mfma_f32_16x16x32_bf16 v[66:69], v[186:189], v[214:217], v[106:109]
	v_mfma_f32_16x16x32_bf16 v[86:89], v[190:193], v[218:221], v[66:69]
	v_mfma_f32_16x16x32_bf16 v[66:69], v[194:197], v[214:217], v[90:93]
	v_mfma_f32_16x16x32_bf16 v[82:85], v[202:205], v[218:221], v[66:69]
	v_mfma_f32_16x16x32_bf16 v[66:69], v[186:189], v[222:225], v[74:77]
	v_mfma_f32_16x16x32_bf16 v[54:57], v[194:197], v[222:225], v[54:57]
	v_mfma_f32_16x16x32_bf16 v[70:73], v[190:193], v[238:241], v[66:69]
	v_mfma_f32_16x16x32_bf16 v[66:69], v[202:205], v[238:241], v[54:57]
	s_setprio 0
	s_barrier
	ds_read_b128 v[130:133], v152 offset:49152
	ds_read_b128 v[198:201], v152 offset:50176
	ds_read_b128 v[242:245], v152 offset:51200
	ds_read_b128 v[246:249], v152 offset:52224
	s_waitcnt vmcnt(0)
	s_barrier
	s_waitcnt lgkmcnt(0)
	s_setprio 2
	s_waitcnt lgkmcnt(0)
	v_mfma_f32_16x16x32_bf16 v[30:33], v[130:133], v[50:53], v[30:33]
	v_mfma_f32_16x16x32_bf16 v[26:29], v[242:245], v[50:53], v[26:29]
	v_mfma_f32_16x16x32_bf16 v[22:25], v[130:133], v[94:97], v[22:25]
	v_mfma_f32_16x16x32_bf16 v[18:21], v[242:245], v[94:97], v[18:21]
	v_mfma_f32_16x16x32_bf16 v[14:17], v[130:133], v[214:217], v[14:17]
	v_mfma_f32_16x16x32_bf16 v[10:13], v[242:245], v[214:217], v[10:13]
	v_mfma_f32_16x16x32_bf16 v[6:9], v[130:133], v[222:225], v[6:9]
	v_mfma_f32_16x16x32_bf16 v[2:5], v[242:245], v[222:225], v[2:5]
	v_mfma_f32_16x16x32_bf16 v[126:129], v[198:201], v[78:81], v[30:33]
	v_mfma_f32_16x16x32_bf16 v[122:125], v[246:249], v[78:81], v[26:29]
	v_mfma_f32_16x16x32_bf16 v[110:113], v[198:201], v[206:209], v[22:25]
	v_mfma_f32_16x16x32_bf16 v[106:109], v[246:249], v[206:209], v[18:21]
	v_mfma_f32_16x16x32_bf16 v[94:97], v[198:201], v[218:221], v[14:17]
	v_mfma_f32_16x16x32_bf16 v[90:93], v[246:249], v[218:221], v[10:13]
	v_mfma_f32_16x16x32_bf16 v[78:81], v[198:201], v[238:241], v[6:9]
	v_mfma_f32_16x16x32_bf16 v[74:77], v[246:249], v[238:241], v[2:5]
	s_setprio 0
	s_barrier
	ds_read_b128 v[10:13], v153 offset:49152
	ds_read_b128 v[14:17], v153 offset:50176
	ds_read_b128 v[26:29], v153 offset:51200
	ds_read_b128 v[30:33], v153 offset:52224
	ds_read_b128 v[206:209], v153 offset:53248
	ds_read_b128 v[214:217], v153 offset:54272
	ds_read_b128 v[218:221], v153 offset:55296
	ds_read_b128 v[222:225], v153 offset:56320
	s_barrier
	s_waitcnt lgkmcnt(0)
	s_setprio 2
	s_waitcnt lgkmcnt(0)
	v_mfma_f32_16x16x32_bf16 v[2:5], v[186:189], v[10:13], v[34:37]
	v_mfma_f32_16x16x32_bf16 v[54:57], v[190:193], v[14:17], v[2:5]
	v_mfma_f32_16x16x32_bf16 v[2:5], v[194:197], v[10:13], v[38:41]
	v_mfma_f32_16x16x32_bf16 v[50:53], v[202:205], v[14:17], v[2:5]
	v_mfma_f32_16x16x32_bf16 v[2:5], v[186:189], v[26:29], v[42:45]
	v_mfma_f32_16x16x32_bf16 v[38:41], v[190:193], v[30:33], v[2:5]
	v_mfma_f32_16x16x32_bf16 v[2:5], v[194:197], v[26:29], v[46:49]
	v_mfma_f32_16x16x32_bf16 v[34:37], v[202:205], v[30:33], v[2:5]
	v_mfma_f32_16x16x32_bf16 v[2:5], v[186:189], v[206:209], v[210:213]
	v_mfma_f32_16x16x32_bf16 v[22:25], v[190:193], v[214:217], v[2:5]
	v_mfma_f32_16x16x32_bf16 v[2:5], v[194:197], v[206:209], v[58:61]
	v_mfma_f32_16x16x32_bf16 v[18:21], v[202:205], v[214:217], v[2:5]
	v_mfma_f32_16x16x32_bf16 v[2:5], v[186:189], v[218:221], v[62:65]
	v_mfma_f32_16x16x32_bf16 v[6:9], v[190:193], v[222:225], v[2:5]
	v_mfma_f32_16x16x32_bf16 v[2:5], v[194:197], v[218:221], v[134:137]
	v_mfma_f32_16x16x32_bf16 v[2:5], v[202:205], v[222:225], v[2:5]
	s_setprio 0
	s_setprio 2
	v_mfma_f32_16x16x32_bf16 v[42:45], v[130:133], v[10:13], v[138:141]
	v_mfma_f32_16x16x32_bf16 v[10:13], v[242:245], v[10:13], v[142:145]
	v_mfma_f32_16x16x32_bf16 v[58:61], v[246:249], v[14:17], v[10:13]
	v_mfma_f32_16x16x32_bf16 v[10:13], v[130:133], v[26:29], v[162:165]
	v_mfma_f32_16x16x32_bf16 v[46:49], v[198:201], v[30:33], v[10:13]
	v_mfma_f32_16x16x32_bf16 v[10:13], v[242:245], v[26:29], v[166:169]
	v_mfma_f32_16x16x32_bf16 v[62:65], v[198:201], v[14:17], v[42:45]
	v_mfma_f32_16x16x32_bf16 v[42:45], v[246:249], v[30:33], v[10:13]
	v_mfma_f32_16x16x32_bf16 v[10:13], v[130:133], v[206:209], v[170:173]
	v_mfma_f32_16x16x32_bf16 v[30:33], v[198:201], v[214:217], v[10:13]
	v_mfma_f32_16x16x32_bf16 v[10:13], v[242:245], v[206:209], v[174:177]
	v_mfma_f32_16x16x32_bf16 v[26:29], v[246:249], v[214:217], v[10:13]
	v_mfma_f32_16x16x32_bf16 v[10:13], v[130:133], v[218:221], v[178:181]
	v_mfma_f32_16x16x32_bf16 v[14:17], v[198:201], v[222:225], v[10:13]
	v_mfma_f32_16x16x32_bf16 v[10:13], v[242:245], v[218:221], v[182:185]
	v_mfma_f32_16x16x32_bf16 v[10:13], v[246:249], v[222:225], v[10:13]
	s_setprio 0
	s_barrier
	s_and_saveexec_b64 s[0:1], s[38:39]
	s_cbranch_execz .LBB0_179
	s_barrier

; #define WAIT_L(n) asm volatile("s_waitcnt lgkmcnt(" #n ")" ::: "memory")
; #define BAR __builtin_amdgcn_s_barrier()
; #define SCHED __builtin_amdgcn_sched_barrier(0)
; #define STAGEA(P, BASE, kt) do { const size_t SS_ = ssA; STAGE(P, BASE, kt); } while (0)
; #define STAGEB(P, BASE, kt) do { const size_t SS_ = ssB; STAGE(P, BASE, kt); } while (0)
; #define LDA(dst, b, h) _Pragma("unroll") for (int m = 0; m < 4; ++m) _Pragma("unroll") for (int k = 0; k < 2; ++k) \
;     dst[m][k] = *(const s16x8*)(smem + a_rdo + ((b) * 2 + (h)) * 16384 + m * 2048 + k * 1024)
; #define LDB(dst, b, h) _Pragma("unroll") for (int n = 0; n < 2; ++n) _Pragma("unroll") for (int k = 0; k < 2; ++k) \
;     dst[n][k] = *(const s16x8*)(smem + b_rdo + ((b) * 2 + (h)) * 16384 + n * 2048 + k * 1024)
; #define MMA(ai, bj, Ax, Bx) do { __builtin_amdgcn_s_setprio(1); \
;     _Pragma("unroll") for (int m = 0; m < 4; ++m) _Pragma("unroll") for (int n = 0; n < 2; ++n) _Pragma("unroll") for (int k = 0; k < 2; ++k) \
;       acc[ai][bj][m][n] = MFMA16(Bx[n][k], Ax[m][k], acc[ai][bj][m][n]); \
;     __builtin_amdgcn_s_setprio(0); } while (0)
; template <int EPI>
; __device__ void gemm8(const bf16* A, const bf16* Bt, const int K, const int ntN, const int ntTot, const EpiArgs ea, char* smem) {
;     ...
;       LDB(B0, 0, 0); SCHED; LDA(At, 0, 0); STAGEA(SA(1, 1), A1, t + 1);
;       WAIT_L(8); BAR; WAIT_L(0); MMA(0, 0, At, B0); BAR; SCHED;
;       LDB(B1, 0, 1); STAGEB(SB(0, 0), B0g, t + 2);
;       BAR; WAIT_L(0); MMA(0, 1, At, B1); BAR;
;       LDA(At, 0, 1); STAGEA(SA(0, 0), A0, t + 2);
;       BAR; WAIT_L(0); MMA(1, 0, At, B0); BAR; SCHED;
.LBB0_800:
	s_nop 0
	v_add_u32_e32 v133, 0, v132
	ds_read_b128 v[134:137], v133
	ds_read_b128 v[138:141], v133 offset:1024
	ds_read_b128 v[142:145], v133 offset:2048
	ds_read_b128 v[146:149], v133 offset:3072
	v_lshl_add_u64 v[212:213], s[14:15], 0, v[192:193]
	s_mov_b64 s[2:3], 0xcc34000
	v_lshl_add_u64 v[182:183], v[212:213], 0, s[2:3]
	s_add_i32 s2, s23, 0xc000
	v_add_u32_e32 v218, 0, v0
	s_mov_b32 m0, s2
	s_mov_b64 s[30:31], 0xcc36000
	s_add_i32 s1, s23, 0xe000
	ds_read_b128 v[150:153], v218
	ds_read_b128 v[154:157], v218 offset:1024
	ds_read_b128 v[158:161], v218 offset:2048
	ds_read_b128 v[162:165], v218 offset:3072
	ds_read_b128 v[166:169], v218 offset:4096
	ds_read_b128 v[170:173], v218 offset:5120
	ds_read_b128 v[174:177], v218 offset:6144
	ds_read_b128 v[178:181], v218 offset:7168
	global_load_lds_dwordx4 v[182:183], off
	v_lshl_add_u64 v[182:183], v[212:213], 0, s[30:31]
	s_mov_b32 m0, s1
	s_nop 0
	global_load_lds_dwordx4 v[182:183], off
	s_waitcnt lgkmcnt(8)
	s_barrier
	s_waitcnt lgkmcnt(0)
	s_setprio 2
	s_waitcnt lgkmcnt(0)
	v_mfma_f32_16x16x32_bf16 v[126:129], v[134:137], v[150:153], v[126:129]
	v_mfma_f32_16x16x32_bf16 v[122:125], v[142:145], v[150:153], v[122:125]
	v_mfma_f32_16x16x32_bf16 v[118:121], v[134:137], v[158:161], v[118:121]
	v_mfma_f32_16x16x32_bf16 v[114:117], v[142:145], v[158:161], v[114:117]
	v_mfma_f32_16x16x32_bf16 v[106:109], v[134:137], v[166:169], v[106:109]
	v_mfma_f32_16x16x32_bf16 v[90:93], v[142:145], v[166:169], v[90:93]
	v_mfma_f32_16x16x32_bf16 v[74:77], v[134:137], v[174:177], v[74:77]
	v_mfma_f32_16x16x32_bf16 v[54:57], v[142:145], v[174:177], v[54:57]
	v_mfma_f32_16x16x32_bf16 v[126:129], v[138:141], v[154:157], v[126:129]
	v_mfma_f32_16x16x32_bf16 v[122:125], v[146:149], v[154:157], v[122:125]
	v_mfma_f32_16x16x32_bf16 v[118:121], v[138:141], v[162:165], v[118:121]
	v_mfma_f32_16x16x32_bf16 v[114:117], v[146:149], v[162:165], v[114:117]
	v_mfma_f32_16x16x32_bf16 v[106:109], v[138:141], v[170:173], v[106:109]
	v_mfma_f32_16x16x32_bf16 v[90:93], v[146:149], v[170:173], v[90:93]
	v_mfma_f32_16x16x32_bf16 v[74:77], v[138:141], v[178:181], v[74:77]
	v_mfma_f32_16x16x32_bf16 v[54:57], v[146:149], v[178:181], v[54:57]
	s_setprio 0
	s_barrier
	v_lshl_add_u64 v[214:215], s[16:17], 0, v[192:193]
	s_mov_b64 s[30:31], 0xc40000
	s_mov_b32 m0, s5
	v_lshl_add_u64 v[216:217], v[214:215], 0, s[30:31]
	s_mov_b64 s[30:31], 0xc42000
	ds_read_b128 v[182:185], v133 offset:16384
	ds_read_b128 v[194:197], v133 offset:17408
	ds_read_b128 v[198:201], v133 offset:18432
	ds_read_b128 v[202:205], v133 offset:19456
	global_load_lds_dwordx4 v[216:217], off
	v_lshl_add_u64 v[216:217], v[214:215], 0, s[30:31]
	s_mov_b32 m0, s7
	s_nop 0
	global_load_lds_dwordx4 v[216:217], off
	s_barrier
	s_waitcnt lgkmcnt(0)
	s_setprio 2
	s_waitcnt lgkmcnt(0)
	v_mfma_f32_16x16x32_bf16 v[30:33], v[182:185], v[150:153], v[30:33]
	v_mfma_f32_16x16x32_bf16 v[26:29], v[198:201], v[150:153], v[26:29]
	v_mfma_f32_16x16x32_bf16 v[22:25], v[182:185], v[158:161], v[22:25]
	v_mfma_f32_16x16x32_bf16 v[18:21], v[198:201], v[158:161], v[18:21]
	v_mfma_f32_16x16x32_bf16 v[14:17], v[182:185], v[166:169], v[14:17]
	v_mfma_f32_16x16x32_bf16 v[10:13], v[198:201], v[166:169], v[10:13]
	v_mfma_f32_16x16x32_bf16 v[6:9], v[182:185], v[174:177], v[6:9]
	v_mfma_f32_16x16x32_bf16 v[2:5], v[198:201], v[174:177], v[2:5]
	v_mfma_f32_16x16x32_bf16 v[30:33], v[194:197], v[154:157], v[30:33]
	v_mfma_f32_16x16x32_bf16 v[26:29], v[202:205], v[154:157], v[26:29]
	v_mfma_f32_16x16x32_bf16 v[22:25], v[194:197], v[162:165], v[22:25]
	v_mfma_f32_16x16x32_bf16 v[18:21], v[202:205], v[162:165], v[18:21]
	v_mfma_f32_16x16x32_bf16 v[14:17], v[194:197], v[170:173], v[14:17]
	v_mfma_f32_16x16x32_bf16 v[10:13], v[202:205], v[170:173], v[10:13]
	v_mfma_f32_16x16x32_bf16 v[6:9], v[194:197], v[178:181], v[6:9]
	v_mfma_f32_16x16x32_bf16 v[2:5], v[202:205], v[178:181], v[2:5]
	s_setprio 0
	s_mov_b64 s[30:31], 0xce30000
	s_mov_b32 m0, s23
	v_lshl_add_u64 v[216:217], v[212:213], 0, s[30:31]
	s_mov_b64 s[30:31], 0xce32000
	s_barrier
	ds_read_b128 v[150:153], v218 offset:16384
	ds_read_b128 v[154:157], v218 offset:17408
	ds_read_b128 v[158:161], v218 offset:18432
	ds_read_b128 v[162:165], v218 offset:19456
	ds_read_b128 v[166:169], v218 offset:20480
	ds_read_b128 v[170:173], v218 offset:21504
	ds_read_b128 v[174:177], v218 offset:22528
	ds_read_b128 v[178:181], v218 offset:23552
	global_load_lds_dwordx4 v[216:217], off
	v_lshl_add_u64 v[216:217], v[212:213], 0, s[30:31]
	s_mov_b32 m0, s9
	s_nop 0
	global_load_lds_dwordx4 v[216:217], off
	s_barrier
	s_waitcnt lgkmcnt(0)
	s_setprio 2
	s_waitcnt lgkmcnt(0)
	v_mfma_f32_16x16x32_bf16 v[34:37], v[134:137], v[150:153], v[34:37]
	v_mfma_f32_16x16x32_bf16 v[38:41], v[142:145], v[150:153], v[38:41]
	v_mfma_f32_16x16x32_bf16 v[42:45], v[134:137], v[158:161], v[42:45]
	v_mfma_f32_16x16x32_bf16 v[46:49], v[142:145], v[158:161], v[46:49]
	v_mfma_f32_16x16x32_bf16 v[50:53], v[134:137], v[166:169], v[50:53]
	v_mfma_f32_16x16x32_bf16 v[58:61], v[142:145], v[166:169], v[58:61]
	v_mfma_f32_16x16x32_bf16 v[62:65], v[134:137], v[174:177], v[62:65]
	v_mfma_f32_16x16x32_bf16 v[66:69], v[142:145], v[174:177], v[66:69]
	v_mfma_f32_16x16x32_bf16 v[34:37], v[138:141], v[154:157], v[34:37]
	v_mfma_f32_16x16x32_bf16 v[38:41], v[146:149], v[154:157], v[38:41]
	v_mfma_f32_16x16x32_bf16 v[42:45], v[138:141], v[162:165], v[42:45]
	v_mfma_f32_16x16x32_bf16 v[46:49], v[146:149], v[162:165], v[46:49]
	v_mfma_f32_16x16x32_bf16 v[50:53], v[138:141], v[170:173], v[50:53]
	v_mfma_f32_16x16x32_bf16 v[58:61], v[146:149], v[170:173], v[58:61]
	v_mfma_f32_16x16x32_bf16 v[62:65], v[138:141], v[178:181], v[62:65]
	v_mfma_f32_16x16x32_bf16 v[66:69], v[146:149], v[178:181], v[66:69]
	s_setprio 0
	s_barrier
; #define WAIT_V(n) asm volatile("s_waitcnt vmcnt(" #n ")" ::: "memory")
; #define WAIT_L(n) asm volatile("s_waitcnt lgkmcnt(" #n ")" ::: "memory")
; #define BAR __builtin_amdgcn_s_barrier()
; #define SCHED __builtin_amdgcn_sched_barrier(0)
; #define STAGEA(P, BASE, kt) do { const size_t SS_ = ssA; STAGE(P, BASE, kt); } while (0)
; #define STAGEB(P, BASE, kt) do { const size_t SS_ = ssB; STAGE(P, BASE, kt); } while (0)
; #define LDA(dst, b, h) _Pragma("unroll") for (int m = 0; m < 4; ++m) _Pragma("unroll") for (int k = 0; k < 2; ++k) \
;     dst[m][k] = *(const s16x8*)(smem + a_rdo + ((b) * 2 + (h)) * 16384 + m * 2048 + k * 1024)
; #define LDB(dst, b, h) _Pragma("unroll") for (int n = 0; n < 2; ++n) _Pragma("unroll") for (int k = 0; k < 2; ++k) \
;     dst[n][k] = *(const s16x8*)(smem + b_rdo + ((b) * 2 + (h)) * 16384 + n * 2048 + k * 1024)
; #define MMA(ai, bj, Ax, Bx) do { __builtin_amdgcn_s_setprio(1); \
;     _Pragma("unroll") for (int m = 0; m < 4; ++m) _Pragma("unroll") for (int n = 0; n < 2; ++n) _Pragma("unroll") for (int k = 0; k < 2; ++k) \
;       acc[ai][bj][m][n] = MFMA16(Bx[n][k], Ax[m][k], acc[ai][bj][m][n]); \
;     __builtin_amdgcn_s_setprio(0); } while (0)
; template <int EPI>
; __device__ void gemm8(const bf16* A, const bf16* Bt, const int K, const int ntN, const int ntTot, const EpiArgs ea, char* smem) {
;     ...
;       STAGEB(SB(0, 1), B1g, t + 2);
;       WAIT_V(6); BAR; MMA(1, 1, At, B1); BAR;
;       LDB(B0, 1, 0); SCHED; LDA(At, 1, 0); STAGEA(SA(0, 1), A1, t + 2);
;       WAIT_L(8); BAR; WAIT_L(0); MMA(0, 0, At, B0); BAR; SCHED;
;       LDB(B1, 1, 1); STAGEB(SB(1, 0), B0g, t + 3);
;       BAR; WAIT_L(0); MMA(0, 1, At, B1); BAR;
;       LDA(At, 1, 1); STAGEA(SA(1, 0), A0, t + 3);
	s_mov_b64 s[30:31], 0xc44000
	s_mov_b32 m0, s27
	v_lshl_add_u64 v[134:135], v[214:215], 0, s[30:31]
	s_mov_b64 s[30:31], 0xc46000
	global_load_lds_dwordx4 v[134:135], off
	v_lshl_add_u64 v[134:135], v[214:215], 0, s[30:31]
	s_mov_b32 m0, s34
	s_nop 0
	global_load_lds_dwordx4 v[134:135], off
	s_waitcnt vmcnt(6)
	s_barrier
	s_setprio 2
	v_mfma_f32_16x16x32_bf16 v[70:73], v[182:185], v[150:153], v[70:73]
	v_mfma_f32_16x16x32_bf16 v[78:81], v[198:201], v[150:153], v[78:81]
	v_mfma_f32_16x16x32_bf16 v[82:85], v[182:185], v[158:161], v[82:85]
	v_mfma_f32_16x16x32_bf16 v[86:89], v[198:201], v[158:161], v[86:89]
	v_mfma_f32_16x16x32_bf16 v[94:97], v[182:185], v[166:169], v[94:97]
	v_mfma_f32_16x16x32_bf16 v[98:101], v[198:201], v[166:169], v[98:101]
	v_mfma_f32_16x16x32_bf16 v[102:105], v[182:185], v[174:177], v[102:105]
	v_mfma_f32_16x16x32_bf16 v[110:113], v[198:201], v[174:177], v[110:113]
	v_mfma_f32_16x16x32_bf16 v[70:73], v[194:197], v[154:157], v[70:73]
	v_mfma_f32_16x16x32_bf16 v[78:81], v[202:205], v[154:157], v[78:81]
	v_mfma_f32_16x16x32_bf16 v[82:85], v[194:197], v[162:165], v[82:85]
	v_mfma_f32_16x16x32_bf16 v[86:89], v[202:205], v[162:165], v[86:89]
	v_mfma_f32_16x16x32_bf16 v[94:97], v[194:197], v[170:173], v[94:97]
	v_mfma_f32_16x16x32_bf16 v[98:101], v[202:205], v[170:173], v[98:101]
	v_mfma_f32_16x16x32_bf16 v[102:105], v[194:197], v[178:181], v[102:105]
	v_mfma_f32_16x16x32_bf16 v[110:113], v[202:205], v[178:181], v[110:113]
	s_setprio 0
	s_barrier
	ds_read_b128 v[134:137], v133 offset:32768
	ds_read_b128 v[138:141], v133 offset:33792
	ds_read_b128 v[142:145], v133 offset:34816
	ds_read_b128 v[146:149], v133 offset:35840
	s_mov_b64 s[30:31], 0xce34000
	s_mov_b32 m0, s35
	v_lshl_add_u64 v[182:183], v[212:213], 0, s[30:31]
	s_mov_b64 s[30:31], 0xce36000
	ds_read_b128 v[150:153], v218 offset:32768
	ds_read_b128 v[154:157], v218 offset:33792
	ds_read_b128 v[158:161], v218 offset:34816
	ds_read_b128 v[162:165], v218 offset:35840
	ds_read_b128 v[166:169], v218 offset:36864
	ds_read_b128 v[170:173], v218 offset:37888
	ds_read_b128 v[174:177], v218 offset:38912
	ds_read_b128 v[178:181], v218 offset:39936
	global_load_lds_dwordx4 v[182:183], off
	v_lshl_add_u64 v[182:183], v[212:213], 0, s[30:31]
	s_mov_b32 m0, s42
	s_nop 0
	global_load_lds_dwordx4 v[182:183], off
	s_waitcnt lgkmcnt(8)
	s_barrier
	s_waitcnt lgkmcnt(0)
	s_setprio 2
	s_waitcnt lgkmcnt(0)
	v_mfma_f32_16x16x32_bf16 v[126:129], v[134:137], v[150:153], v[126:129]
	v_mfma_f32_16x16x32_bf16 v[122:125], v[142:145], v[150:153], v[122:125]
	v_mfma_f32_16x16x32_bf16 v[118:121], v[134:137], v[158:161], v[118:121]
	v_mfma_f32_16x16x32_bf16 v[114:117], v[142:145], v[158:161], v[114:117]
	v_mfma_f32_16x16x32_bf16 v[106:109], v[134:137], v[166:169], v[106:109]
	v_mfma_f32_16x16x32_bf16 v[90:93], v[142:145], v[166:169], v[90:93]
	v_mfma_f32_16x16x32_bf16 v[74:77], v[134:137], v[174:177], v[74:77]
	v_mfma_f32_16x16x32_bf16 v[54:57], v[142:145], v[174:177], v[54:57]
	v_mfma_f32_16x16x32_bf16 v[126:129], v[138:141], v[154:157], v[126:129]
	v_mfma_f32_16x16x32_bf16 v[122:125], v[146:149], v[154:157], v[122:125]
	v_mfma_f32_16x16x32_bf16 v[118:121], v[138:141], v[162:165], v[118:121]
	v_mfma_f32_16x16x32_bf16 v[114:117], v[146:149], v[162:165], v[114:117]
	v_mfma_f32_16x16x32_bf16 v[106:109], v[138:141], v[170:173], v[106:109]
	v_mfma_f32_16x16x32_bf16 v[90:93], v[146:149], v[170:173], v[90:93]
	v_mfma_f32_16x16x32_bf16 v[74:77], v[138:141], v[178:181], v[74:77]
	v_mfma_f32_16x16x32_bf16 v[54:57], v[146:149], v[178:181], v[54:57]
	s_setprio 0
	s_barrier
	s_mov_b64 s[30:31], 0xc60000
	s_mov_b32 m0, s10
	v_lshl_add_u64 v[216:217], v[214:215], 0, s[30:31]
	s_mov_b64 s[30:31], 0xc62000
	ds_read_b128 v[182:185], v133 offset:49152
	ds_read_b128 v[194:197], v133 offset:50176
	ds_read_b128 v[198:201], v133 offset:51200
	ds_read_b128 v[202:205], v133 offset:52224
	global_load_lds_dwordx4 v[216:217], off
	v_lshl_add_u64 v[216:217], v[214:215], 0, s[30:31]
	s_mov_b32 m0, s11
	s_nop 0
	global_load_lds_dwordx4 v[216:217], off
	s_barrier
	s_waitcnt lgkmcnt(0)
	s_setprio 2
	s_waitcnt lgkmcnt(0)
	v_mfma_f32_16x16x32_bf16 v[30:33], v[182:185], v[150:153], v[30:33]
	v_mfma_f32_16x16x32_bf16 v[26:29], v[198:201], v[150:153], v[26:29]
	v_mfma_f32_16x16x32_bf16 v[22:25], v[182:185], v[158:161], v[22:25]
	v_mfma_f32_16x16x32_bf16 v[18:21], v[198:201], v[158:161], v[18:21]
	v_mfma_f32_16x16x32_bf16 v[14:17], v[182:185], v[166:169], v[14:17]
	v_mfma_f32_16x16x32_bf16 v[10:13], v[198:201], v[166:169], v[10:13]
	v_mfma_f32_16x16x32_bf16 v[6:9], v[182:185], v[174:177], v[6:9]
	v_mfma_f32_16x16x32_bf16 v[2:5], v[198:201], v[174:177], v[2:5]
	v_mfma_f32_16x16x32_bf16 v[30:33], v[194:197], v[154:157], v[30:33]
	v_mfma_f32_16x16x32_bf16 v[26:29], v[202:205], v[154:157], v[26:29]
	v_mfma_f32_16x16x32_bf16 v[22:25], v[194:197], v[162:165], v[22:25]
	v_mfma_f32_16x16x32_bf16 v[18:21], v[202:205], v[162:165], v[18:21]
	v_mfma_f32_16x16x32_bf16 v[14:17], v[194:197], v[170:173], v[14:17]
	v_mfma_f32_16x16x32_bf16 v[10:13], v[202:205], v[170:173], v[10:13]
	v_mfma_f32_16x16x32_bf16 v[6:9], v[194:197], v[178:181], v[6:9]
	v_mfma_f32_16x16x32_bf16 v[2:5], v[202:205], v[178:181], v[2:5]
	s_setprio 0
	s_mov_b64 s[30:31], 0xd030000
	s_mov_b32 m0, s43
	v_lshl_add_u64 v[216:217], v[212:213], 0, s[30:31]
	s_mov_b64 s[30:31], 0xd032000
	s_barrier
	ds_read_b128 v[150:153], v218 offset:49152
	ds_read_b128 v[154:157], v218 offset:50176
	ds_read_b128 v[158:161], v218 offset:51200
	ds_read_b128 v[162:165], v218 offset:52224
	ds_read_b128 v[166:169], v218 offset:53248
	ds_read_b128 v[170:173], v218 offset:54272
	ds_read_b128 v[174:177], v218 offset:55296
	ds_read_b128 v[178:181], v218 offset:56320
	global_load_lds_dwordx4 v[216:217], off
	v_lshl_add_u64 v[212:213], v[212:213], 0, s[30:31]
	s_mov_b32 m0, s44
	s_nop 0
	global_load_lds_dwordx4 v[212:213], off
	s_barrier
; #define WAIT_V(n) asm volatile("s_waitcnt vmcnt(" #n ")" ::: "memory")
; #define WAIT_L(n) asm volatile("s_waitcnt lgkmcnt(" #n ")" ::: "memory")
; #define BAR __builtin_amdgcn_s_barrier()
; #define SCHED __builtin_amdgcn_sched_barrier(0)
; #define STAGEA(P, BASE, kt) do { const size_t SS_ = ssA; STAGE(P, BASE, kt); } while (0)
; #define STAGEB(P, BASE, kt) do { const size_t SS_ = ssB; STAGE(P, BASE, kt); } while (0)
; #define LDA(dst, b, h) _Pragma("unroll") for (int m = 0; m < 4; ++m) _Pragma("unroll") for (int k = 0; k < 2; ++k) \
;     dst[m][k] = *(const s16x8*)(smem + a_rdo + ((b) * 2 + (h)) * 16384 + m * 2048 + k * 1024)
; #define LDB(dst, b, h) _Pragma("unroll") for (int n = 0; n < 2; ++n) _Pragma("unroll") for (int k = 0; k < 2; ++k) \
;     dst[n][k] = *(const s16x8*)(smem + b_rdo + ((b) * 2 + (h)) * 16384 + n * 2048 + k * 1024)
; #define MMA(ai, bj, Ax, Bx) do { __builtin_amdgcn_s_setprio(1); \
;     _Pragma("unroll") for (int m = 0; m < 4; ++m) _Pragma("unroll") for (int n = 0; n < 2; ++n) _Pragma("unroll") for (int k = 0; k < 2; ++k) \
;       acc[ai][bj][m][n] = MFMA16(Bx[n][k], Ax[m][k], acc[ai][bj][m][n]); \
;     __builtin_amdgcn_s_setprio(0); } while (0)
; template <int EPI>
; __device__ void gemm8(const bf16* A, const bf16* Bt, const int K, const int ntN, const int ntTot, const EpiArgs ea, char* smem) {
;     ...
;       BAR; WAIT_L(0); MMA(1, 0, At, B0); BAR; SCHED;
;       STAGEB(SB(1, 1), B1g, t + 3);
;       WAIT_V(6); BAR; MMA(1, 1, At, B1); BAR;
;     }
;     asm volatile("" : "+v"(a_rdo), "+v"(b_rdo));
;     { LDB(B0, 0, 0); LDA(At, 0, 0); STAGEA(SA(1, 1), A1, nt - 1);
;       BAR; WAIT_L(0); MMA(0, 0, At, B0); BAR;
;       LDB(B1, 0, 1); BAR; WAIT_L(0); MMA(0, 1, At, B1); BAR;
	s_waitcnt lgkmcnt(0)
	s_setprio 2
	s_waitcnt lgkmcnt(0)
	v_mfma_f32_16x16x32_bf16 v[34:37], v[134:137], v[150:153], v[34:37]
	v_mfma_f32_16x16x32_bf16 v[38:41], v[142:145], v[150:153], v[38:41]
	v_mfma_f32_16x16x32_bf16 v[42:45], v[134:137], v[158:161], v[42:45]
	v_mfma_f32_16x16x32_bf16 v[46:49], v[142:145], v[158:161], v[46:49]
	v_mfma_f32_16x16x32_bf16 v[50:53], v[134:137], v[166:169], v[50:53]
	v_mfma_f32_16x16x32_bf16 v[58:61], v[142:145], v[166:169], v[58:61]
	v_mfma_f32_16x16x32_bf16 v[62:65], v[134:137], v[174:177], v[62:65]
	v_mfma_f32_16x16x32_bf16 v[66:69], v[142:145], v[174:177], v[66:69]
	v_mfma_f32_16x16x32_bf16 v[34:37], v[138:141], v[154:157], v[34:37]
	v_mfma_f32_16x16x32_bf16 v[38:41], v[146:149], v[154:157], v[38:41]
	v_mfma_f32_16x16x32_bf16 v[42:45], v[138:141], v[162:165], v[42:45]
	v_mfma_f32_16x16x32_bf16 v[46:49], v[146:149], v[162:165], v[46:49]
	v_mfma_f32_16x16x32_bf16 v[50:53], v[138:141], v[170:173], v[50:53]
	v_mfma_f32_16x16x32_bf16 v[58:61], v[146:149], v[170:173], v[58:61]
	v_mfma_f32_16x16x32_bf16 v[62:65], v[138:141], v[178:181], v[62:65]
	v_mfma_f32_16x16x32_bf16 v[66:69], v[146:149], v[178:181], v[66:69]
	s_setprio 0
	s_barrier
	s_mov_b64 s[30:31], 0xc64000
	s_mov_b32 m0, s45
	v_lshl_add_u64 v[134:135], v[214:215], 0, s[30:31]
	s_mov_b64 s[30:31], 0xc66000
	global_load_lds_dwordx4 v[134:135], off
	v_lshl_add_u64 v[134:135], v[214:215], 0, s[30:31]
	s_mov_b32 m0, s46
	s_nop 0
	global_load_lds_dwordx4 v[134:135], off
	s_waitcnt vmcnt(6)
	s_barrier
	s_setprio 2
	v_mfma_f32_16x16x32_bf16 v[70:73], v[182:185], v[150:153], v[70:73]
	v_mfma_f32_16x16x32_bf16 v[78:81], v[198:201], v[150:153], v[78:81]
	v_mfma_f32_16x16x32_bf16 v[82:85], v[182:185], v[158:161], v[82:85]
	v_mfma_f32_16x16x32_bf16 v[86:89], v[198:201], v[158:161], v[86:89]
	v_mfma_f32_16x16x32_bf16 v[94:97], v[182:185], v[166:169], v[94:97]
	v_mfma_f32_16x16x32_bf16 v[98:101], v[198:201], v[166:169], v[98:101]
	v_mfma_f32_16x16x32_bf16 v[102:105], v[182:185], v[174:177], v[102:105]
	v_mfma_f32_16x16x32_bf16 v[110:113], v[198:201], v[174:177], v[110:113]
	v_mfma_f32_16x16x32_bf16 v[70:73], v[194:197], v[154:157], v[70:73]
	v_mfma_f32_16x16x32_bf16 v[78:81], v[202:205], v[154:157], v[78:81]
	v_mfma_f32_16x16x32_bf16 v[82:85], v[194:197], v[162:165], v[82:85]
	v_mfma_f32_16x16x32_bf16 v[86:89], v[202:205], v[162:165], v[86:89]
	v_mfma_f32_16x16x32_bf16 v[94:97], v[194:197], v[170:173], v[94:97]
	v_mfma_f32_16x16x32_bf16 v[98:101], v[202:205], v[170:173], v[98:101]
	v_mfma_f32_16x16x32_bf16 v[102:105], v[194:197], v[178:181], v[102:105]
	v_mfma_f32_16x16x32_bf16 v[110:113], v[202:205], v[178:181], v[110:113]
	s_setprio 0
	s_add_i32 s0, s0, 2
	s_add_u32 s14, s14, 0x400000
	s_addc_u32 s15, s15, 0
	s_add_u32 s16, s16, 0x40000
	s_addc_u32 s17, s17, 0
	s_cmp_gt_u32 s0, 7
	s_barrier
	s_cbranch_scc0 .LBB0_800
	s_mov_b32 m0, s2
	s_mov_b64 s[2:3], 0x1604000
	v_add_u32_e32 v212, 0, v132
	v_add_u32_e32 v0, 0, v0
	v_lshl_add_u64 v[180:181], v[130:131], 0, s[2:3]
	s_mov_b64 s[2:3], 0x1606000
	ds_read_b128 v[132:135], v212
	ds_read_b128 v[136:139], v212 offset:1024
	ds_read_b128 v[140:143], v212 offset:2048
	ds_read_b128 v[144:147], v212 offset:3072
	ds_read_b128 v[148:151], v0
	ds_read_b128 v[152:155], v0 offset:1024
	ds_read_b128 v[156:159], v0 offset:2048
	ds_read_b128 v[160:163], v0 offset:3072
	ds_read_b128 v[164:167], v0 offset:4096
	ds_read_b128 v[168:171], v0 offset:5120
	ds_read_b128 v[172:175], v0 offset:6144
	ds_read_b128 v[176:179], v0 offset:7168
	global_load_lds_dwordx4 v[180:181], off
	v_lshl_add_u64 v[130:131], v[130:131], 0, s[2:3]
	s_mov_b32 m0, s1
	s_nop 0
	global_load_lds_dwordx4 v[130:131], off
	s_barrier
	s_waitcnt lgkmcnt(0)
	s_setprio 2
	s_waitcnt lgkmcnt(0)
	v_mfma_f32_16x16x32_bf16 v[126:129], v[132:135], v[148:151], v[126:129]
	v_mfma_f32_16x16x32_bf16 v[118:121], v[132:135], v[156:159], v[118:121]
	v_mfma_f32_16x16x32_bf16 v[114:117], v[140:143], v[156:159], v[114:117]
	v_mfma_f32_16x16x32_bf16 v[106:109], v[132:135], v[164:167], v[106:109]
	v_mfma_f32_16x16x32_bf16 v[90:93], v[140:143], v[164:167], v[90:93]
	v_mfma_f32_16x16x32_bf16 v[74:77], v[132:135], v[172:175], v[74:77]
	v_mfma_f32_16x16x32_bf16 v[54:57], v[140:143], v[172:175], v[54:57]
	v_mfma_f32_16x16x32_bf16 v[126:129], v[136:139], v[152:155], v[126:129]
	v_mfma_f32_16x16x32_bf16 v[122:125], v[140:143], v[148:151], v[122:125]
	v_mfma_f32_16x16x32_bf16 v[118:121], v[136:139], v[160:163], v[118:121]
	v_mfma_f32_16x16x32_bf16 v[114:117], v[144:147], v[160:163], v[114:117]
	v_mfma_f32_16x16x32_bf16 v[106:109], v[136:139], v[168:171], v[106:109]
	v_mfma_f32_16x16x32_bf16 v[90:93], v[144:147], v[168:171], v[90:93]
	v_mfma_f32_16x16x32_bf16 v[74:77], v[136:139], v[176:179], v[74:77]
	v_mfma_f32_16x16x32_bf16 v[54:57], v[144:147], v[176:179], v[54:57]
	v_mfma_f32_16x16x32_bf16 v[122:125], v[144:147], v[152:155], v[122:125]
	s_setprio 0
	s_barrier
	ds_read_b128 v[180:183], v212 offset:16384
	ds_read_b128 v[194:197], v212 offset:17408
	ds_read_b128 v[198:201], v212 offset:18432
	ds_read_b128 v[202:205], v212 offset:19456
	s_barrier
; #define WAIT_V(n) asm volatile("s_waitcnt vmcnt(" #n ")" ::: "memory")
; #define WAIT_L(n) asm volatile("s_waitcnt lgkmcnt(" #n ")" ::: "memory")
; #define BAR __builtin_amdgcn_s_barrier()
; #define LDA(dst, b, h) _Pragma("unroll") for (int m = 0; m < 4; ++m) _Pragma("unroll") for (int k = 0; k < 2; ++k) \
;     dst[m][k] = *(const s16x8*)(smem + a_rdo + ((b) * 2 + (h)) * 16384 + m * 2048 + k * 1024)
; #define LDB(dst, b, h) _Pragma("unroll") for (int n = 0; n < 2; ++n) _Pragma("unroll") for (int k = 0; k < 2; ++k) \
;     dst[n][k] = *(const s16x8*)(smem + b_rdo + ((b) * 2 + (h)) * 16384 + n * 2048 + k * 1024)
; #define MMA(ai, bj, Ax, Bx) do { __builtin_amdgcn_s_setprio(1); \
;     _Pragma("unroll") for (int m = 0; m < 4; ++m) _Pragma("unroll") for (int n = 0; n < 2; ++n) _Pragma("unroll") for (int k = 0; k < 2; ++k) \
;       acc[ai][bj][m][n] = MFMA16(Bx[n][k], Ax[m][k], acc[ai][bj][m][n]); \
;     __builtin_amdgcn_s_setprio(0); } while (0)
; template <int EPI>
; __device__ void gemm8(const bf16* A, const bf16* Bt, const int K, const int ntN, const int ntTot, const EpiArgs ea, char* smem) {
;     ...
;       LDB(B1, 0, 1); BAR; WAIT_L(0); MMA(0, 1, At, B1); BAR;
;       LDA(At, 0, 1); WAIT_V(4); BAR; WAIT_L(0); MMA(1, 0, At, B0); MMA(1, 1, At, B1); BAR; }
;     { LDB(B0, 1, 0); LDA(At, 1, 0); WAIT_V(2); BAR; WAIT_L(0); MMA(0, 0, At, B0); BAR;
	s_waitcnt lgkmcnt(0)
	s_setprio 2
	s_waitcnt lgkmcnt(0)
	v_mfma_f32_16x16x32_bf16 v[30:33], v[180:183], v[148:151], v[30:33]
	v_mfma_f32_16x16x32_bf16 v[22:25], v[180:183], v[156:159], v[22:25]
	v_mfma_f32_16x16x32_bf16 v[18:21], v[198:201], v[156:159], v[18:21]
	v_mfma_f32_16x16x32_bf16 v[14:17], v[180:183], v[164:167], v[14:17]
	v_mfma_f32_16x16x32_bf16 v[10:13], v[198:201], v[164:167], v[10:13]
	v_mfma_f32_16x16x32_bf16 v[6:9], v[180:183], v[172:175], v[6:9]
	v_mfma_f32_16x16x32_bf16 v[2:5], v[198:201], v[172:175], v[2:5]
	v_mfma_f32_16x16x32_bf16 v[30:33], v[194:197], v[152:155], v[30:33]
	v_mfma_f32_16x16x32_bf16 v[26:29], v[198:201], v[148:151], v[26:29]
	v_mfma_f32_16x16x32_bf16 v[22:25], v[194:197], v[160:163], v[22:25]
	v_mfma_f32_16x16x32_bf16 v[18:21], v[202:205], v[160:163], v[18:21]
	v_mfma_f32_16x16x32_bf16 v[14:17], v[194:197], v[168:171], v[14:17]
	v_mfma_f32_16x16x32_bf16 v[10:13], v[202:205], v[168:171], v[10:13]
	v_mfma_f32_16x16x32_bf16 v[6:9], v[194:197], v[176:179], v[6:9]
	v_mfma_f32_16x16x32_bf16 v[2:5], v[202:205], v[176:179], v[2:5]
	v_mfma_f32_16x16x32_bf16 v[26:29], v[202:205], v[152:155], v[26:29]
	s_setprio 0
	s_barrier
	ds_read_b128 v[148:151], v0 offset:16384
	ds_read_b128 v[152:155], v0 offset:17408
	ds_read_b128 v[156:159], v0 offset:18432
	ds_read_b128 v[160:163], v0 offset:19456
	ds_read_b128 v[164:167], v0 offset:20480
	ds_read_b128 v[168:171], v0 offset:21504
	ds_read_b128 v[172:175], v0 offset:22528
	ds_read_b128 v[176:179], v0 offset:23552
	s_waitcnt vmcnt(4)
	s_barrier
	s_waitcnt lgkmcnt(0)
	s_setprio 2
	s_waitcnt lgkmcnt(0)
	v_mfma_f32_16x16x32_bf16 v[58:61], v[140:143], v[164:167], v[58:61]
	v_mfma_f32_16x16x32_bf16 v[216:219], v[144:147], v[168:171], v[58:61]
	v_mfma_f32_16x16x32_bf16 v[58:61], v[132:135], v[172:175], v[62:65]
	v_mfma_f32_16x16x32_bf16 v[34:37], v[132:135], v[148:151], v[34:37]
	v_mfma_f32_16x16x32_bf16 v[42:45], v[132:135], v[156:159], v[42:45]
	v_mfma_f32_16x16x32_bf16 v[46:49], v[140:143], v[156:159], v[46:49]
	v_mfma_f32_16x16x32_bf16 v[62:65], v[136:139], v[176:179], v[58:61]
	v_mfma_f32_16x16x32_bf16 v[58:61], v[140:143], v[172:175], v[66:69]
	v_mfma_f32_16x16x32_bf16 v[34:37], v[136:139], v[152:155], v[34:37]
	v_mfma_f32_16x16x32_bf16 v[38:41], v[140:143], v[148:151], v[38:41]
	v_mfma_f32_16x16x32_bf16 v[42:45], v[136:139], v[160:163], v[42:45]
	v_mfma_f32_16x16x32_bf16 v[46:49], v[144:147], v[160:163], v[46:49]
	v_mfma_f32_16x16x32_bf16 v[50:53], v[132:135], v[164:167], v[50:53]
	v_mfma_f32_16x16x32_bf16 v[66:69], v[144:147], v[176:179], v[58:61]
	v_mfma_f32_16x16x32_bf16 v[38:41], v[144:147], v[152:155], v[38:41]
	v_mfma_f32_16x16x32_bf16 v[50:53], v[136:139], v[168:171], v[50:53]
	s_setprio 0
	s_setprio 2
	v_mfma_f32_16x16x32_bf16 v[58:61], v[180:183], v[148:151], v[70:73]
	v_mfma_f32_16x16x32_bf16 v[70:73], v[194:197], v[152:155], v[58:61]
	v_mfma_f32_16x16x32_bf16 v[58:61], v[198:201], v[148:151], v[78:81]
	v_mfma_f32_16x16x32_bf16 v[134:137], v[202:205], v[152:155], v[58:61]
	v_mfma_f32_16x16x32_bf16 v[58:61], v[180:183], v[156:159], v[82:85]
	v_mfma_f32_16x16x32_bf16 v[142:145], v[194:197], v[160:163], v[58:61]
	v_mfma_f32_16x16x32_bf16 v[58:61], v[198:201], v[156:159], v[86:89]
	v_mfma_f32_16x16x32_bf16 v[86:89], v[202:205], v[160:163], v[58:61]
	v_mfma_f32_16x16x32_bf16 v[58:61], v[180:183], v[164:167], v[94:97]
	v_mfma_f32_16x16x32_bf16 v[158:161], v[194:197], v[168:171], v[58:61]
	v_mfma_f32_16x16x32_bf16 v[58:61], v[198:201], v[164:167], v[98:101]
	v_mfma_f32_16x16x32_bf16 v[98:101], v[202:205], v[168:171], v[58:61]
	v_mfma_f32_16x16x32_bf16 v[58:61], v[180:183], v[172:175], v[102:105]
	v_mfma_f32_16x16x32_bf16 v[162:165], v[194:197], v[176:179], v[58:61]
	v_mfma_f32_16x16x32_bf16 v[58:61], v[198:201], v[172:175], v[110:113]
	v_mfma_f32_16x16x32_bf16 v[110:113], v[202:205], v[176:179], v[58:61]
	s_setprio 0
	s_barrier
	ds_read_b128 v[182:185], v212 offset:32768
	ds_read_b128 v[194:197], v212 offset:33792
	ds_read_b128 v[198:201], v212 offset:34816
	ds_read_b128 v[202:205], v212 offset:35840
	s_nop 0
	ds_read_b128 v[58:61], v0 offset:32768
	ds_read_b128 v[78:81], v0 offset:33792
	ds_read_b128 v[82:85], v0 offset:34816
	ds_read_b128 v[94:97], v0 offset:35840
	ds_read_b128 v[220:223], v0 offset:36864
	ds_read_b128 v[238:241], v0 offset:37888
	ds_read_b128 v[242:245], v0 offset:38912
	ds_read_b128 v[246:249], v0 offset:39936
	s_waitcnt vmcnt(2)
	s_barrier
; #define WAIT_V(n) asm volatile("s_waitcnt vmcnt(" #n ")" ::: "memory")
; #define WAIT_L(n) asm volatile("s_waitcnt lgkmcnt(" #n ")" ::: "memory")
; #define BAR __builtin_amdgcn_s_barrier()
; #define LDA(dst, b, h) _Pragma("unroll") for (int m = 0; m < 4; ++m) _Pragma("unroll") for (int k = 0; k < 2; ++k) \
;     dst[m][k] = *(const s16x8*)(smem + a_rdo + ((b) * 2 + (h)) * 16384 + m * 2048 + k * 1024)
; #define LDB(dst, b, h) _Pragma("unroll") for (int n = 0; n < 2; ++n) _Pragma("unroll") for (int k = 0; k < 2; ++k) \
;     dst[n][k] = *(const s16x8*)(smem + b_rdo + ((b) * 2 + (h)) * 16384 + n * 2048 + k * 1024)
; #define MMA(ai, bj, Ax, Bx) do { __builtin_amdgcn_s_setprio(1); \
;     _Pragma("unroll") for (int m = 0; m < 4; ++m) _Pragma("unroll") for (int n = 0; n < 2; ++n) _Pragma("unroll") for (int k = 0; k < 2; ++k) \
;       acc[ai][bj][m][n] = MFMA16(Bx[n][k], Ax[m][k], acc[ai][bj][m][n]); \
;     __builtin_amdgcn_s_setprio(0); } while (0)
; template <int EPI>
; __device__ void gemm8(const bf16* A, const bf16* Bt, const int K, const int ntN, const int ntTot, const EpiArgs ea, char* smem) {
;     ...
;     { LDB(B0, 1, 0); LDA(At, 1, 0); WAIT_V(2); BAR; WAIT_L(0); MMA(0, 0, At, B0); BAR;
;       LDB(B1, 1, 1); WAIT_V(0); BAR; WAIT_L(0); MMA(0, 1, At, B1); BAR;
;       LDA(At, 1, 1); BAR; WAIT_L(0); MMA(1, 0, At, B0); MMA(1, 1, At, B1); BAR; }
;     if (wr == 0) BAR;
	s_waitcnt lgkmcnt(0)
	s_setprio 2
	s_waitcnt lgkmcnt(0)
	v_mfma_f32_16x16x32_bf16 v[102:105], v[182:185], v[58:61], v[126:129]
	v_mfma_f32_16x16x32_bf16 v[178:181], v[194:197], v[78:81], v[102:105]
	v_mfma_f32_16x16x32_bf16 v[102:105], v[198:201], v[58:61], v[122:125]
	v_mfma_f32_16x16x32_bf16 v[174:177], v[202:205], v[78:81], v[102:105]
	v_mfma_f32_16x16x32_bf16 v[102:105], v[182:185], v[82:85], v[118:121]
	v_mfma_f32_16x16x32_bf16 v[154:157], v[194:197], v[94:97], v[102:105]
	v_mfma_f32_16x16x32_bf16 v[102:105], v[198:201], v[82:85], v[114:117]
	v_mfma_f32_16x16x32_bf16 v[150:153], v[202:205], v[94:97], v[102:105]
	v_mfma_f32_16x16x32_bf16 v[102:105], v[182:185], v[220:223], v[106:109]
	v_mfma_f32_16x16x32_bf16 v[90:93], v[198:201], v[220:223], v[90:93]
	v_mfma_f32_16x16x32_bf16 v[74:77], v[182:185], v[242:245], v[74:77]
	v_mfma_f32_16x16x32_bf16 v[54:57], v[198:201], v[242:245], v[54:57]
	v_mfma_f32_16x16x32_bf16 v[130:133], v[194:197], v[238:241], v[102:105]
	v_mfma_f32_16x16x32_bf16 v[126:129], v[202:205], v[238:241], v[90:93]
	v_mfma_f32_16x16x32_bf16 v[106:109], v[194:197], v[246:249], v[74:77]
	v_mfma_f32_16x16x32_bf16 v[102:105], v[202:205], v[246:249], v[54:57]
	s_setprio 0
	s_barrier
	ds_read_b128 v[122:125], v212 offset:49152
	ds_read_b128 v[234:237], v212 offset:50176
	ds_read_b128 v[224:227], v212 offset:51200
	ds_read_b128 v[212:215], v212 offset:52224
	s_waitcnt vmcnt(0)
	s_barrier
	s_waitcnt lgkmcnt(0)
	s_setprio 2
	s_waitcnt lgkmcnt(0)
	v_mfma_f32_16x16x32_bf16 v[30:33], v[122:125], v[58:61], v[30:33]
	v_mfma_f32_16x16x32_bf16 v[26:29], v[224:227], v[58:61], v[26:29]
	v_mfma_f32_16x16x32_bf16 v[22:25], v[122:125], v[82:85], v[22:25]
	v_mfma_f32_16x16x32_bf16 v[18:21], v[224:227], v[82:85], v[18:21]
	v_mfma_f32_16x16x32_bf16 v[14:17], v[122:125], v[220:223], v[14:17]
	v_mfma_f32_16x16x32_bf16 v[10:13], v[224:227], v[220:223], v[10:13]
	v_mfma_f32_16x16x32_bf16 v[6:9], v[122:125], v[242:245], v[6:9]
	v_mfma_f32_16x16x32_bf16 v[2:5], v[224:227], v[242:245], v[2:5]
	v_mfma_f32_16x16x32_bf16 v[170:173], v[234:237], v[78:81], v[30:33]
	v_mfma_f32_16x16x32_bf16 v[166:169], v[212:215], v[78:81], v[26:29]
	v_mfma_f32_16x16x32_bf16 v[146:149], v[234:237], v[94:97], v[22:25]
	v_mfma_f32_16x16x32_bf16 v[138:141], v[212:215], v[94:97], v[18:21]
	v_mfma_f32_16x16x32_bf16 v[118:121], v[234:237], v[238:241], v[14:17]
	v_mfma_f32_16x16x32_bf16 v[114:117], v[212:215], v[238:241], v[10:13]
	v_mfma_f32_16x16x32_bf16 v[94:97], v[234:237], v[246:249], v[6:9]
	v_mfma_f32_16x16x32_bf16 v[90:93], v[212:215], v[246:249], v[2:5]
	s_setprio 0
	s_barrier
	s_nop 0
	ds_read_b128 v[2:5], v0 offset:49152
	ds_read_b128 v[6:9], v0 offset:50176
	ds_read_b128 v[18:21], v0 offset:51200
	ds_read_b128 v[22:25], v0 offset:52224
	ds_read_b128 v[26:29], v0 offset:53248
	ds_read_b128 v[220:223], v0 offset:54272
	ds_read_b128 v[238:241], v0 offset:55296
	ds_read_b128 v[242:245], v0 offset:56320
	s_barrier
	s_waitcnt lgkmcnt(0)
	s_setprio 2
	s_waitcnt lgkmcnt(0)
	v_mfma_f32_16x16x32_bf16 v[10:13], v[182:185], v[2:5], v[34:37]
	v_mfma_f32_16x16x32_bf16 v[82:85], v[194:197], v[6:9], v[10:13]
	v_mfma_f32_16x16x32_bf16 v[10:13], v[198:201], v[2:5], v[38:41]
	v_mfma_f32_16x16x32_bf16 v[78:81], v[202:205], v[6:9], v[10:13]
	v_mfma_f32_16x16x32_bf16 v[10:13], v[182:185], v[18:21], v[42:45]
	v_mfma_f32_16x16x32_bf16 v[58:61], v[194:197], v[22:25], v[10:13]
	v_mfma_f32_16x16x32_bf16 v[10:13], v[198:201], v[18:21], v[46:49]
	v_mfma_f32_16x16x32_bf16 v[54:57], v[202:205], v[22:25], v[10:13]
	v_mfma_f32_16x16x32_bf16 v[10:13], v[182:185], v[26:29], v[50:53]
	v_mfma_f32_16x16x32_bf16 v[34:37], v[194:197], v[220:223], v[10:13]
	v_mfma_f32_16x16x32_bf16 v[10:13], v[198:201], v[26:29], v[216:219]
	v_mfma_f32_16x16x32_bf16 v[30:33], v[202:205], v[220:223], v[10:13]
	v_mfma_f32_16x16x32_bf16 v[10:13], v[182:185], v[238:241], v[62:65]
	v_mfma_f32_16x16x32_bf16 v[14:17], v[194:197], v[242:245], v[10:13]
	v_mfma_f32_16x16x32_bf16 v[10:13], v[198:201], v[238:241], v[66:69]
	v_mfma_f32_16x16x32_bf16 v[10:13], v[202:205], v[242:245], v[10:13]
	s_setprio 0
	s_setprio 2
	v_mfma_f32_16x16x32_bf16 v[38:41], v[122:125], v[2:5], v[70:73]
	v_mfma_f32_16x16x32_bf16 v[2:5], v[224:227], v[2:5], v[134:137]
	v_mfma_f32_16x16x32_bf16 v[66:69], v[212:215], v[6:9], v[2:5]
	v_mfma_f32_16x16x32_bf16 v[2:5], v[122:125], v[18:21], v[142:145]
	v_mfma_f32_16x16x32_bf16 v[46:49], v[234:237], v[22:25], v[2:5]
	v_mfma_f32_16x16x32_bf16 v[2:5], v[224:227], v[18:21], v[86:89]
	v_mfma_f32_16x16x32_bf16 v[42:45], v[212:215], v[22:25], v[2:5]
	v_mfma_f32_16x16x32_bf16 v[2:5], v[122:125], v[26:29], v[158:161]
	v_mfma_f32_16x16x32_bf16 v[22:25], v[234:237], v[220:223], v[2:5]
	v_mfma_f32_16x16x32_bf16 v[2:5], v[224:227], v[26:29], v[98:101]
	v_mfma_f32_16x16x32_bf16 v[18:21], v[212:215], v[220:223], v[2:5]
	v_mfma_f32_16x16x32_bf16 v[2:5], v[122:125], v[238:241], v[162:165]
	v_mfma_f32_16x16x32_bf16 v[74:77], v[234:237], v[6:9], v[38:41]
	v_mfma_f32_16x16x32_bf16 v[6:9], v[234:237], v[242:245], v[2:5]
	v_mfma_f32_16x16x32_bf16 v[2:5], v[224:227], v[238:241], v[110:113]
	v_mfma_f32_16x16x32_bf16 v[2:5], v[212:215], v[242:245], v[2:5]
	s_setprio 0
	s_barrier
	s_and_saveexec_b64 s[0:1], s[36:37]
	s_cbranch_execz .LBB0_803
	s_barrier

; #define WAIT_L(n) asm volatile("s_waitcnt lgkmcnt(" #n ")" ::: "memory")
; #define BAR __builtin_amdgcn_s_barrier()
; #define SCHED __builtin_amdgcn_sched_barrier(0)
; #define STAGEA(P, BASE, kt) do { const size_t SS_ = ssA; STAGE(P, BASE, kt); } while (0)
; #define STAGEB(P, BASE, kt) do { const size_t SS_ = ssB; STAGE(P, BASE, kt); } while (0)
; #define LDA(dst, b, h) _Pragma("unroll") for (int m = 0; m < 4; ++m) _Pragma("unroll") for (int k = 0; k < 2; ++k) \
;     dst[m][k] = *(const s16x8*)(smem + a_rdo + ((b) * 2 + (h)) * 16384 + m * 2048 + k * 1024)
; #define LDB(dst, b, h) _Pragma("unroll") for (int n = 0; n < 2; ++n) _Pragma("unroll") for (int k = 0; k < 2; ++k) \
;     dst[n][k] = *(const s16x8*)(smem + b_rdo + ((b) * 2 + (h)) * 16384 + n * 2048 + k * 1024)
; #define MMA(ai, bj, Ax, Bx) do { __builtin_amdgcn_s_setprio(1); \
;     _Pragma("unroll") for (int m = 0; m < 4; ++m) _Pragma("unroll") for (int n = 0; n < 2; ++n) _Pragma("unroll") for (int k = 0; k < 2; ++k) \
;       acc[ai][bj][m][n] = MFMA16(Bx[n][k], Ax[m][k], acc[ai][bj][m][n]); \
;     __builtin_amdgcn_s_setprio(0); } while (0)
; template <int EPI>
; __device__ void gemm8(const bf16* A, const bf16* Bt, const int K, const int ntN, const int ntTot, const EpiArgs ea, char* smem) {
;     ...
;       LDB(B0, 0, 0); SCHED; LDA(At, 0, 0); STAGEA(SA(1, 1), A1, t + 1);
;       WAIT_L(8); BAR; WAIT_L(0); MMA(0, 0, At, B0); BAR; SCHED;
;       LDB(B1, 0, 1); STAGEB(SB(0, 0), B0g, t + 2);
;       BAR; WAIT_L(0); MMA(0, 1, At, B1); BAR;
;       LDA(At, 0, 1); STAGEA(SA(0, 0), A0, t + 2);
;       BAR; WAIT_L(0); MMA(1, 0, At, B0); BAR; SCHED;
.LBB0_882:
	s_nop 0
	v_add_u32_e32 v145, 0, v137
	ds_read_b128 v[146:149], v145
	ds_read_b128 v[150:153], v145 offset:1024
	ds_read_b128 v[154:157], v145 offset:2048
	ds_read_b128 v[158:161], v145 offset:3072
	v_lshl_add_u64 v[210:211], s[14:15], 0, v[132:133]
	s_add_i32 s2, s23, 0xc000
	v_add_u32_e32 v216, 0, v136
	v_lshl_add_u64 v[194:195], v[210:211], 0, s[72:73]
	s_mov_b32 m0, s2
	s_add_i32 s1, s23, 0xe000
	ds_read_b128 v[162:165], v216
	ds_read_b128 v[166:169], v216 offset:1024
	ds_read_b128 v[170:173], v216 offset:2048
	ds_read_b128 v[174:177], v216 offset:3072
	ds_read_b128 v[178:181], v216 offset:4096
	ds_read_b128 v[182:185], v216 offset:5120
	ds_read_b128 v[186:189], v216 offset:6144
	ds_read_b128 v[190:193], v216 offset:7168
	global_load_lds_dwordx4 v[194:195], off
	v_lshl_add_u64 v[194:195], v[210:211], 0, s[74:75]
	s_mov_b32 m0, s1
	s_nop 0
	global_load_lds_dwordx4 v[194:195], off
	s_waitcnt lgkmcnt(8)
	s_barrier
	s_waitcnt lgkmcnt(0)
	s_setprio 2
	s_waitcnt lgkmcnt(0)
	v_mfma_f32_16x16x32_bf16 v[126:129], v[146:149], v[162:165], v[126:129]
	v_mfma_f32_16x16x32_bf16 v[122:125], v[154:157], v[162:165], v[122:125]
	v_mfma_f32_16x16x32_bf16 v[118:121], v[146:149], v[170:173], v[118:121]
	v_mfma_f32_16x16x32_bf16 v[114:117], v[154:157], v[170:173], v[114:117]
	v_mfma_f32_16x16x32_bf16 v[110:113], v[146:149], v[178:181], v[110:113]
	v_mfma_f32_16x16x32_bf16 v[106:109], v[154:157], v[178:181], v[106:109]
	v_mfma_f32_16x16x32_bf16 v[102:105], v[146:149], v[186:189], v[102:105]
	v_mfma_f32_16x16x32_bf16 v[98:101], v[154:157], v[186:189], v[98:101]
	v_mfma_f32_16x16x32_bf16 v[126:129], v[150:153], v[166:169], v[126:129]
	v_mfma_f32_16x16x32_bf16 v[122:125], v[158:161], v[166:169], v[122:125]
	v_mfma_f32_16x16x32_bf16 v[118:121], v[150:153], v[174:177], v[118:121]
	v_mfma_f32_16x16x32_bf16 v[114:117], v[158:161], v[174:177], v[114:117]
	v_mfma_f32_16x16x32_bf16 v[110:113], v[150:153], v[182:185], v[110:113]
	v_mfma_f32_16x16x32_bf16 v[106:109], v[158:161], v[182:185], v[106:109]
	v_mfma_f32_16x16x32_bf16 v[102:105], v[150:153], v[190:193], v[102:105]
	v_mfma_f32_16x16x32_bf16 v[98:101], v[158:161], v[190:193], v[98:101]
	s_setprio 0
	s_barrier
	v_lshl_add_u64 v[212:213], s[16:17], 0, v[132:133]
	s_mov_b64 s[30:31], 0x1000000
	s_mov_b32 m0, s5
	v_lshl_add_u64 v[214:215], v[212:213], 0, s[30:31]
	s_mov_b64 s[30:31], 0x1002000
	ds_read_b128 v[194:197], v145 offset:16384
	ds_read_b128 v[198:201], v145 offset:17408
	ds_read_b128 v[202:205], v145 offset:18432
	ds_read_b128 v[206:209], v145 offset:19456
	global_load_lds_dwordx4 v[214:215], off
	v_lshl_add_u64 v[214:215], v[212:213], 0, s[30:31]
	s_mov_b32 m0, s9
	s_nop 0
	global_load_lds_dwordx4 v[214:215], off
	s_barrier
	s_waitcnt lgkmcnt(0)
	s_setprio 2
	s_waitcnt lgkmcnt(0)
	v_mfma_f32_16x16x32_bf16 v[94:97], v[194:197], v[162:165], v[94:97]
	v_mfma_f32_16x16x32_bf16 v[90:93], v[202:205], v[162:165], v[90:93]
	v_mfma_f32_16x16x32_bf16 v[86:89], v[194:197], v[170:173], v[86:89]
	v_mfma_f32_16x16x32_bf16 v[82:85], v[202:205], v[170:173], v[82:85]
	v_mfma_f32_16x16x32_bf16 v[78:81], v[194:197], v[178:181], v[78:81]
	v_mfma_f32_16x16x32_bf16 v[74:77], v[202:205], v[178:181], v[74:77]
	v_mfma_f32_16x16x32_bf16 v[70:73], v[194:197], v[186:189], v[70:73]
	v_mfma_f32_16x16x32_bf16 v[66:69], v[202:205], v[186:189], v[66:69]
	v_mfma_f32_16x16x32_bf16 v[94:97], v[198:201], v[166:169], v[94:97]
	v_mfma_f32_16x16x32_bf16 v[90:93], v[206:209], v[166:169], v[90:93]
	v_mfma_f32_16x16x32_bf16 v[86:89], v[198:201], v[174:177], v[86:89]
	v_mfma_f32_16x16x32_bf16 v[82:85], v[206:209], v[174:177], v[82:85]
	v_mfma_f32_16x16x32_bf16 v[78:81], v[198:201], v[182:185], v[78:81]
	v_mfma_f32_16x16x32_bf16 v[74:77], v[206:209], v[182:185], v[74:77]
	v_mfma_f32_16x16x32_bf16 v[70:73], v[198:201], v[190:193], v[70:73]
	v_mfma_f32_16x16x32_bf16 v[66:69], v[206:209], v[190:193], v[66:69]
	s_setprio 0
	s_mov_b32 m0, s23
	v_lshl_add_u64 v[214:215], v[210:211], 0, s[76:77]
	s_barrier
	ds_read_b128 v[162:165], v216 offset:16384
	ds_read_b128 v[166:169], v216 offset:17408
	ds_read_b128 v[170:173], v216 offset:18432
	ds_read_b128 v[174:177], v216 offset:19456
	ds_read_b128 v[178:181], v216 offset:20480
	ds_read_b128 v[182:185], v216 offset:21504
	ds_read_b128 v[186:189], v216 offset:22528
	ds_read_b128 v[190:193], v216 offset:23552
	global_load_lds_dwordx4 v[214:215], off
	v_lshl_add_u64 v[214:215], v[210:211], 0, s[78:79]
	s_mov_b32 m0, s27
	s_nop 0
	global_load_lds_dwordx4 v[214:215], off
	s_barrier
	s_waitcnt lgkmcnt(0)
	s_setprio 2
	s_waitcnt lgkmcnt(0)
	v_mfma_f32_16x16x32_bf16 v[62:65], v[146:149], v[162:165], v[62:65]
	v_mfma_f32_16x16x32_bf16 v[58:61], v[154:157], v[162:165], v[58:61]
	v_mfma_f32_16x16x32_bf16 v[54:57], v[146:149], v[170:173], v[54:57]
	v_mfma_f32_16x16x32_bf16 v[50:53], v[154:157], v[170:173], v[50:53]
	v_mfma_f32_16x16x32_bf16 v[46:49], v[146:149], v[178:181], v[46:49]
	v_mfma_f32_16x16x32_bf16 v[42:45], v[154:157], v[178:181], v[42:45]
	v_mfma_f32_16x16x32_bf16 v[38:41], v[146:149], v[186:189], v[38:41]
	v_mfma_f32_16x16x32_bf16 v[34:37], v[154:157], v[186:189], v[34:37]
	v_mfma_f32_16x16x32_bf16 v[62:65], v[150:153], v[166:169], v[62:65]
	v_mfma_f32_16x16x32_bf16 v[58:61], v[158:161], v[166:169], v[58:61]
	v_mfma_f32_16x16x32_bf16 v[54:57], v[150:153], v[174:177], v[54:57]
	v_mfma_f32_16x16x32_bf16 v[50:53], v[158:161], v[174:177], v[50:53]
	v_mfma_f32_16x16x32_bf16 v[46:49], v[150:153], v[182:185], v[46:49]
	v_mfma_f32_16x16x32_bf16 v[42:45], v[158:161], v[182:185], v[42:45]
	v_mfma_f32_16x16x32_bf16 v[38:41], v[150:153], v[190:193], v[38:41]
	v_mfma_f32_16x16x32_bf16 v[34:37], v[158:161], v[190:193], v[34:37]
	s_setprio 0
	s_barrier
; #define WAIT_V(n) asm volatile("s_waitcnt vmcnt(" #n ")" ::: "memory")
; #define WAIT_L(n) asm volatile("s_waitcnt lgkmcnt(" #n ")" ::: "memory")
; #define BAR __builtin_amdgcn_s_barrier()
; #define SCHED __builtin_amdgcn_sched_barrier(0)
; #define STAGEA(P, BASE, kt) do { const size_t SS_ = ssA; STAGE(P, BASE, kt); } while (0)
; #define STAGEB(P, BASE, kt) do { const size_t SS_ = ssB; STAGE(P, BASE, kt); } while (0)
; #define LDA(dst, b, h) _Pragma("unroll") for (int m = 0; m < 4; ++m) _Pragma("unroll") for (int k = 0; k < 2; ++k) \
;     dst[m][k] = *(const s16x8*)(smem + a_rdo + ((b) * 2 + (h)) * 16384 + m * 2048 + k * 1024)
; #define LDB(dst, b, h) _Pragma("unroll") for (int n = 0; n < 2; ++n) _Pragma("unroll") for (int k = 0; k < 2; ++k) \
;     dst[n][k] = *(const s16x8*)(smem + b_rdo + ((b) * 2 + (h)) * 16384 + n * 2048 + k * 1024)
; #define MMA(ai, bj, Ax, Bx) do { __builtin_amdgcn_s_setprio(1); \
;     _Pragma("unroll") for (int m = 0; m < 4; ++m) _Pragma("unroll") for (int n = 0; n < 2; ++n) _Pragma("unroll") for (int k = 0; k < 2; ++k) \
;       acc[ai][bj][m][n] = MFMA16(Bx[n][k], Ax[m][k], acc[ai][bj][m][n]); \
;     __builtin_amdgcn_s_setprio(0); } while (0)
; template <int EPI>
; __device__ void gemm8(const bf16* A, const bf16* Bt, const int K, const int ntN, const int ntTot, const EpiArgs ea, char* smem) {
;     ...
;       STAGEB(SB(0, 1), B1g, t + 2);
;       WAIT_V(6); BAR; MMA(1, 1, At, B1); BAR;
;       LDB(B0, 1, 0); SCHED; LDA(At, 1, 0); STAGEA(SA(0, 1), A1, t + 2);
;       WAIT_L(8); BAR; WAIT_L(0); MMA(0, 0, At, B0); BAR; SCHED;
;       LDB(B1, 1, 1); STAGEB(SB(1, 0), B0g, t + 3);
;       BAR; WAIT_L(0); MMA(0, 1, At, B1); BAR;
;       LDA(At, 1, 1); STAGEA(SA(1, 0), A0, t + 3);
	s_mov_b64 s[30:31], 0x1004000
	s_mov_b32 m0, s34
	v_lshl_add_u64 v[146:147], v[212:213], 0, s[30:31]
	s_mov_b64 s[30:31], 0x1006000
	global_load_lds_dwordx4 v[146:147], off
	v_lshl_add_u64 v[146:147], v[212:213], 0, s[30:31]
	s_mov_b32 m0, s35
	s_nop 0
	global_load_lds_dwordx4 v[146:147], off
	s_waitcnt vmcnt(6)
	s_barrier
	s_setprio 2
	v_mfma_f32_16x16x32_bf16 v[30:33], v[194:197], v[162:165], v[30:33]
	v_mfma_f32_16x16x32_bf16 v[26:29], v[202:205], v[162:165], v[26:29]
	v_mfma_f32_16x16x32_bf16 v[22:25], v[194:197], v[170:173], v[22:25]
	v_mfma_f32_16x16x32_bf16 v[18:21], v[202:205], v[170:173], v[18:21]
	v_mfma_f32_16x16x32_bf16 v[14:17], v[194:197], v[178:181], v[14:17]
	v_mfma_f32_16x16x32_bf16 v[10:13], v[202:205], v[178:181], v[10:13]
	v_mfma_f32_16x16x32_bf16 v[6:9], v[194:197], v[186:189], v[6:9]
	v_mfma_f32_16x16x32_bf16 v[2:5], v[202:205], v[186:189], v[2:5]
	v_mfma_f32_16x16x32_bf16 v[30:33], v[198:201], v[166:169], v[30:33]
	v_mfma_f32_16x16x32_bf16 v[26:29], v[206:209], v[166:169], v[26:29]
	v_mfma_f32_16x16x32_bf16 v[22:25], v[198:201], v[174:177], v[22:25]
	v_mfma_f32_16x16x32_bf16 v[18:21], v[206:209], v[174:177], v[18:21]
	v_mfma_f32_16x16x32_bf16 v[14:17], v[198:201], v[182:185], v[14:17]
	v_mfma_f32_16x16x32_bf16 v[10:13], v[206:209], v[182:185], v[10:13]
	v_mfma_f32_16x16x32_bf16 v[6:9], v[198:201], v[190:193], v[6:9]
	v_mfma_f32_16x16x32_bf16 v[2:5], v[206:209], v[190:193], v[2:5]
	s_setprio 0
	s_barrier
	ds_read_b128 v[146:149], v145 offset:32768
	ds_read_b128 v[150:153], v145 offset:33792
	ds_read_b128 v[154:157], v145 offset:34816
	ds_read_b128 v[158:161], v145 offset:35840
	s_mov_b32 m0, s42
	v_lshl_add_u64 v[194:195], v[210:211], 0, s[80:81]
	ds_read_b128 v[162:165], v216 offset:32768
	ds_read_b128 v[166:169], v216 offset:33792
	ds_read_b128 v[170:173], v216 offset:34816
	ds_read_b128 v[174:177], v216 offset:35840
	ds_read_b128 v[178:181], v216 offset:36864
	ds_read_b128 v[182:185], v216 offset:37888
	ds_read_b128 v[186:189], v216 offset:38912
	ds_read_b128 v[190:193], v216 offset:39936
	global_load_lds_dwordx4 v[194:195], off
	v_lshl_add_u64 v[194:195], v[210:211], 0, s[82:83]
	s_mov_b32 m0, s43
	s_nop 0
	global_load_lds_dwordx4 v[194:195], off
	s_waitcnt lgkmcnt(8)
	s_barrier
	s_waitcnt lgkmcnt(0)
	s_setprio 2
	s_waitcnt lgkmcnt(0)
	v_mfma_f32_16x16x32_bf16 v[126:129], v[146:149], v[162:165], v[126:129]
	v_mfma_f32_16x16x32_bf16 v[122:125], v[154:157], v[162:165], v[122:125]
	v_mfma_f32_16x16x32_bf16 v[118:121], v[146:149], v[170:173], v[118:121]
	v_mfma_f32_16x16x32_bf16 v[114:117], v[154:157], v[170:173], v[114:117]
	v_mfma_f32_16x16x32_bf16 v[110:113], v[146:149], v[178:181], v[110:113]
	v_mfma_f32_16x16x32_bf16 v[106:109], v[154:157], v[178:181], v[106:109]
	v_mfma_f32_16x16x32_bf16 v[102:105], v[146:149], v[186:189], v[102:105]
	v_mfma_f32_16x16x32_bf16 v[98:101], v[154:157], v[186:189], v[98:101]
	v_mfma_f32_16x16x32_bf16 v[126:129], v[150:153], v[166:169], v[126:129]
	v_mfma_f32_16x16x32_bf16 v[122:125], v[158:161], v[166:169], v[122:125]
	v_mfma_f32_16x16x32_bf16 v[118:121], v[150:153], v[174:177], v[118:121]
	v_mfma_f32_16x16x32_bf16 v[114:117], v[158:161], v[174:177], v[114:117]
	v_mfma_f32_16x16x32_bf16 v[110:113], v[150:153], v[182:185], v[110:113]
	v_mfma_f32_16x16x32_bf16 v[106:109], v[158:161], v[182:185], v[106:109]
	v_mfma_f32_16x16x32_bf16 v[102:105], v[150:153], v[190:193], v[102:105]
	v_mfma_f32_16x16x32_bf16 v[98:101], v[158:161], v[190:193], v[98:101]
	s_setprio 0
	s_barrier
	s_mov_b64 s[30:31], 0x1080000
	s_mov_b32 m0, s10
	v_lshl_add_u64 v[214:215], v[212:213], 0, s[30:31]
	s_mov_b64 s[30:31], 0x1082000
	ds_read_b128 v[194:197], v145 offset:49152
	ds_read_b128 v[198:201], v145 offset:50176
	ds_read_b128 v[202:205], v145 offset:51200
	ds_read_b128 v[206:209], v145 offset:52224
	global_load_lds_dwordx4 v[214:215], off
	v_lshl_add_u64 v[214:215], v[212:213], 0, s[30:31]
	s_mov_b32 m0, s11
	s_nop 0
	global_load_lds_dwordx4 v[214:215], off
	s_barrier
	s_waitcnt lgkmcnt(0)
	s_setprio 2
	s_waitcnt lgkmcnt(0)
	v_mfma_f32_16x16x32_bf16 v[94:97], v[194:197], v[162:165], v[94:97]
	v_mfma_f32_16x16x32_bf16 v[90:93], v[202:205], v[162:165], v[90:93]
	v_mfma_f32_16x16x32_bf16 v[86:89], v[194:197], v[170:173], v[86:89]
	v_mfma_f32_16x16x32_bf16 v[82:85], v[202:205], v[170:173], v[82:85]
	v_mfma_f32_16x16x32_bf16 v[78:81], v[194:197], v[178:181], v[78:81]
	v_mfma_f32_16x16x32_bf16 v[74:77], v[202:205], v[178:181], v[74:77]
	v_mfma_f32_16x16x32_bf16 v[70:73], v[194:197], v[186:189], v[70:73]
	v_mfma_f32_16x16x32_bf16 v[66:69], v[202:205], v[186:189], v[66:69]
	v_mfma_f32_16x16x32_bf16 v[94:97], v[198:201], v[166:169], v[94:97]
	v_mfma_f32_16x16x32_bf16 v[90:93], v[206:209], v[166:169], v[90:93]
	v_mfma_f32_16x16x32_bf16 v[86:89], v[198:201], v[174:177], v[86:89]
	v_mfma_f32_16x16x32_bf16 v[82:85], v[206:209], v[174:177], v[82:85]
	v_mfma_f32_16x16x32_bf16 v[78:81], v[198:201], v[182:185], v[78:81]
	v_mfma_f32_16x16x32_bf16 v[74:77], v[206:209], v[182:185], v[74:77]
	v_mfma_f32_16x16x32_bf16 v[70:73], v[198:201], v[190:193], v[70:73]
	v_mfma_f32_16x16x32_bf16 v[66:69], v[206:209], v[190:193], v[66:69]
	s_setprio 0
	s_mov_b32 m0, s44
	v_lshl_add_u64 v[214:215], v[210:211], 0, s[84:85]
	s_barrier
	ds_read_b128 v[162:165], v216 offset:49152
	ds_read_b128 v[166:169], v216 offset:50176
	ds_read_b128 v[170:173], v216 offset:51200
	ds_read_b128 v[174:177], v216 offset:52224
	ds_read_b128 v[178:181], v216 offset:53248
	ds_read_b128 v[182:185], v216 offset:54272
	ds_read_b128 v[186:189], v216 offset:55296
	ds_read_b128 v[190:193], v216 offset:56320
	global_load_lds_dwordx4 v[214:215], off
	v_lshl_add_u64 v[210:211], v[210:211], 0, s[86:87]
	s_mov_b32 m0, s45
	s_nop 0
	global_load_lds_dwordx4 v[210:211], off
	s_barrier
; #define WAIT_V(n) asm volatile("s_waitcnt vmcnt(" #n ")" ::: "memory")
; #define WAIT_L(n) asm volatile("s_waitcnt lgkmcnt(" #n ")" ::: "memory")
; #define BAR __builtin_amdgcn_s_barrier()
; #define SCHED __builtin_amdgcn_sched_barrier(0)
; #define STAGEA(P, BASE, kt) do { const size_t SS_ = ssA; STAGE(P, BASE, kt); } while (0)
; #define STAGEB(P, BASE, kt) do { const size_t SS_ = ssB; STAGE(P, BASE, kt); } while (0)
; #define LDA(dst, b, h) _Pragma("unroll") for (int m = 0; m < 4; ++m) _Pragma("unroll") for (int k = 0; k < 2; ++k) \
;     dst[m][k] = *(const s16x8*)(smem + a_rdo + ((b) * 2 + (h)) * 16384 + m * 2048 + k * 1024)
; #define LDB(dst, b, h) _Pragma("unroll") for (int n = 0; n < 2; ++n) _Pragma("unroll") for (int k = 0; k < 2; ++k) \
;     dst[n][k] = *(const s16x8*)(smem + b_rdo + ((b) * 2 + (h)) * 16384 + n * 2048 + k * 1024)
; #define MMA(ai, bj, Ax, Bx) do { __builtin_amdgcn_s_setprio(1); \
;     _Pragma("unroll") for (int m = 0; m < 4; ++m) _Pragma("unroll") for (int n = 0; n < 2; ++n) _Pragma("unroll") for (int k = 0; k < 2; ++k) \
;       acc[ai][bj][m][n] = MFMA16(Bx[n][k], Ax[m][k], acc[ai][bj][m][n]); \
;     __builtin_amdgcn_s_setprio(0); } while (0)
; template <int EPI>
; __device__ void gemm8(const bf16* A, const bf16* Bt, const int K, const int ntN, const int ntTot, const EpiArgs ea, char* smem) {
;     ...
;       BAR; WAIT_L(0); MMA(1, 0, At, B0); BAR; SCHED;
;       STAGEB(SB(1, 1), B1g, t + 3);
;       WAIT_V(6); BAR; MMA(1, 1, At, B1); BAR;
;     }
;     asm volatile("" : "+v"(a_rdo), "+v"(b_rdo));
;     { LDB(B0, 0, 0); LDA(At, 0, 0); STAGEA(SA(1, 1), A1, nt - 1);
;       BAR; WAIT_L(0); MMA(0, 0, At, B0); BAR;
;       LDB(B1, 0, 1); BAR; WAIT_L(0); MMA(0, 1, At, B1); BAR;
	s_waitcnt lgkmcnt(0)
	s_setprio 2
	s_waitcnt lgkmcnt(0)
	v_mfma_f32_16x16x32_bf16 v[62:65], v[146:149], v[162:165], v[62:65]
	v_mfma_f32_16x16x32_bf16 v[58:61], v[154:157], v[162:165], v[58:61]
	v_mfma_f32_16x16x32_bf16 v[54:57], v[146:149], v[170:173], v[54:57]
	v_mfma_f32_16x16x32_bf16 v[50:53], v[154:157], v[170:173], v[50:53]
	v_mfma_f32_16x16x32_bf16 v[46:49], v[146:149], v[178:181], v[46:49]
	v_mfma_f32_16x16x32_bf16 v[42:45], v[154:157], v[178:181], v[42:45]
	v_mfma_f32_16x16x32_bf16 v[38:41], v[146:149], v[186:189], v[38:41]
	v_mfma_f32_16x16x32_bf16 v[34:37], v[154:157], v[186:189], v[34:37]
	v_mfma_f32_16x16x32_bf16 v[62:65], v[150:153], v[166:169], v[62:65]
	v_mfma_f32_16x16x32_bf16 v[58:61], v[158:161], v[166:169], v[58:61]
	v_mfma_f32_16x16x32_bf16 v[54:57], v[150:153], v[174:177], v[54:57]
	v_mfma_f32_16x16x32_bf16 v[50:53], v[158:161], v[174:177], v[50:53]
	v_mfma_f32_16x16x32_bf16 v[46:49], v[150:153], v[182:185], v[46:49]
	v_mfma_f32_16x16x32_bf16 v[42:45], v[158:161], v[182:185], v[42:45]
	v_mfma_f32_16x16x32_bf16 v[38:41], v[150:153], v[190:193], v[38:41]
	v_mfma_f32_16x16x32_bf16 v[34:37], v[158:161], v[190:193], v[34:37]
	s_setprio 0
	s_barrier
	s_mov_b64 s[30:31], 0x1084000
	s_mov_b32 m0, s46
	v_lshl_add_u64 v[146:147], v[212:213], 0, s[30:31]
	s_mov_b64 s[30:31], 0x1086000
	global_load_lds_dwordx4 v[146:147], off
	v_lshl_add_u64 v[146:147], v[212:213], 0, s[30:31]
	s_mov_b32 m0, s47
	s_nop 0
	global_load_lds_dwordx4 v[146:147], off
	s_waitcnt vmcnt(6)
	s_barrier
	s_setprio 2
	v_mfma_f32_16x16x32_bf16 v[30:33], v[194:197], v[162:165], v[30:33]
	v_mfma_f32_16x16x32_bf16 v[26:29], v[202:205], v[162:165], v[26:29]
	v_mfma_f32_16x16x32_bf16 v[22:25], v[194:197], v[170:173], v[22:25]
	v_mfma_f32_16x16x32_bf16 v[18:21], v[202:205], v[170:173], v[18:21]
	v_mfma_f32_16x16x32_bf16 v[14:17], v[194:197], v[178:181], v[14:17]
	v_mfma_f32_16x16x32_bf16 v[10:13], v[202:205], v[178:181], v[10:13]
	v_mfma_f32_16x16x32_bf16 v[6:9], v[194:197], v[186:189], v[6:9]
	v_mfma_f32_16x16x32_bf16 v[2:5], v[202:205], v[186:189], v[2:5]
	v_mfma_f32_16x16x32_bf16 v[30:33], v[198:201], v[166:169], v[30:33]
	v_mfma_f32_16x16x32_bf16 v[26:29], v[206:209], v[166:169], v[26:29]
	v_mfma_f32_16x16x32_bf16 v[22:25], v[198:201], v[174:177], v[22:25]
	v_mfma_f32_16x16x32_bf16 v[18:21], v[206:209], v[174:177], v[18:21]
	v_mfma_f32_16x16x32_bf16 v[14:17], v[198:201], v[182:185], v[14:17]
	v_mfma_f32_16x16x32_bf16 v[10:13], v[206:209], v[182:185], v[10:13]
	v_mfma_f32_16x16x32_bf16 v[6:9], v[198:201], v[190:193], v[6:9]
	v_mfma_f32_16x16x32_bf16 v[2:5], v[206:209], v[190:193], v[2:5]
	s_setprio 0
	s_add_i32 s0, s0, 2
	s_add_u32 s14, s14, 0x400000
	s_addc_u32 s15, s15, 0
	s_add_u32 s16, s16, 0x100000
	s_addc_u32 s17, s17, 0
	s_cmp_gt_u32 s0, 11
	s_barrier
	s_cbranch_scc0 .LBB0_882
	s_mov_b32 m0, s2
	s_mov_b64 s[2:3], 0x1e04000
	v_add_u32_e32 v145, 0, v137
	v_add_u32_e32 v222, 0, v136
	v_lshl_add_u64 v[136:137], v[134:135], 0, s[2:3]
	s_mov_b64 s[2:3], 0x1e06000
	ds_read_b128 v[146:149], v145
	ds_read_b128 v[150:153], v145 offset:1024
	ds_read_b128 v[154:157], v145 offset:2048
	ds_read_b128 v[158:161], v145 offset:3072
	ds_read_b128 v[162:165], v222
	ds_read_b128 v[166:169], v222 offset:1024
	ds_read_b128 v[170:173], v222 offset:2048
	ds_read_b128 v[174:177], v222 offset:3072
	ds_read_b128 v[178:181], v222 offset:4096
	ds_read_b128 v[182:185], v222 offset:5120
	ds_read_b128 v[186:189], v222 offset:6144
	ds_read_b128 v[190:193], v222 offset:7168
	global_load_lds_dwordx4 v[136:137], off
	v_lshl_add_u64 v[134:135], v[134:135], 0, s[2:3]
	s_mov_b32 m0, s1
	s_nop 0
	global_load_lds_dwordx4 v[134:135], off
	s_barrier
	s_waitcnt lgkmcnt(0)
	s_setprio 2
	s_waitcnt lgkmcnt(0)
	v_mfma_f32_16x16x32_bf16 v[126:129], v[146:149], v[162:165], v[126:129]
	v_mfma_f32_16x16x32_bf16 v[122:125], v[154:157], v[162:165], v[122:125]
	v_mfma_f32_16x16x32_bf16 v[114:117], v[154:157], v[170:173], v[114:117]
	v_mfma_f32_16x16x32_bf16 v[106:109], v[154:157], v[178:181], v[106:109]
	v_mfma_f32_16x16x32_bf16 v[98:101], v[154:157], v[186:189], v[98:101]
	v_mfma_f32_16x16x32_bf16 v[126:129], v[150:153], v[166:169], v[126:129]
	v_mfma_f32_16x16x32_bf16 v[122:125], v[158:161], v[166:169], v[122:125]
	v_mfma_f32_16x16x32_bf16 v[118:121], v[146:149], v[170:173], v[118:121]
	v_mfma_f32_16x16x32_bf16 v[114:117], v[158:161], v[174:177], v[114:117]
	v_mfma_f32_16x16x32_bf16 v[110:113], v[146:149], v[178:181], v[110:113]
	v_mfma_f32_16x16x32_bf16 v[106:109], v[158:161], v[182:185], v[106:109]
	v_mfma_f32_16x16x32_bf16 v[102:105], v[146:149], v[186:189], v[102:105]
	v_mfma_f32_16x16x32_bf16 v[98:101], v[158:161], v[190:193], v[98:101]
	v_mfma_f32_16x16x32_bf16 v[134:137], v[150:153], v[174:177], v[118:121]
	v_mfma_f32_16x16x32_bf16 v[194:197], v[150:153], v[182:185], v[110:113]
	v_mfma_f32_16x16x32_bf16 v[198:201], v[150:153], v[190:193], v[102:105]
	s_setprio 0
	s_barrier
	s_nop 1
	ds_read_b128 v[102:105], v145 offset:16384
	ds_read_b128 v[110:113], v145 offset:17408
	ds_read_b128 v[118:121], v145 offset:18432
	ds_read_b128 v[202:205], v145 offset:19456
	s_barrier
; #define WAIT_V(n) asm volatile("s_waitcnt vmcnt(" #n ")" ::: "memory")
; #define WAIT_L(n) asm volatile("s_waitcnt lgkmcnt(" #n ")" ::: "memory")
; #define BAR __builtin_amdgcn_s_barrier()
; #define LDA(dst, b, h) _Pragma("unroll") for (int m = 0; m < 4; ++m) _Pragma("unroll") for (int k = 0; k < 2; ++k) \
;     dst[m][k] = *(const s16x8*)(smem + a_rdo + ((b) * 2 + (h)) * 16384 + m * 2048 + k * 1024)
; #define LDB(dst, b, h) _Pragma("unroll") for (int n = 0; n < 2; ++n) _Pragma("unroll") for (int k = 0; k < 2; ++k) \
;     dst[n][k] = *(const s16x8*)(smem + b_rdo + ((b) * 2 + (h)) * 16384 + n * 2048 + k * 1024)
; #define MMA(ai, bj, Ax, Bx) do { __builtin_amdgcn_s_setprio(1); \
;     _Pragma("unroll") for (int m = 0; m < 4; ++m) _Pragma("unroll") for (int n = 0; n < 2; ++n) _Pragma("unroll") for (int k = 0; k < 2; ++k) \
;       acc[ai][bj][m][n] = MFMA16(Bx[n][k], Ax[m][k], acc[ai][bj][m][n]); \
;     __builtin_amdgcn_s_setprio(0); } while (0)
; template <int EPI>
; __device__ void gemm8(const bf16* A, const bf16* Bt, const int K, const int ntN, const int ntTot, const EpiArgs ea, char* smem) {
;     ...
;       LDB(B1, 0, 1); BAR; WAIT_L(0); MMA(0, 1, At, B1); BAR;
;       LDA(At, 0, 1); WAIT_V(4); BAR; WAIT_L(0); MMA(1, 0, At, B0); MMA(1, 1, At, B1); BAR; }
;     { LDB(B0, 1, 0); LDA(At, 1, 0); WAIT_V(2); BAR; WAIT_L(0); MMA(0, 0, At, B0); BAR;
	s_waitcnt lgkmcnt(0)
	s_setprio 2
	s_waitcnt lgkmcnt(0)
	v_mfma_f32_16x16x32_bf16 v[90:93], v[118:121], v[162:165], v[90:93]
	v_mfma_f32_16x16x32_bf16 v[82:85], v[118:121], v[170:173], v[82:85]
	v_mfma_f32_16x16x32_bf16 v[74:77], v[118:121], v[178:181], v[74:77]
	v_mfma_f32_16x16x32_bf16 v[66:69], v[118:121], v[186:189], v[66:69]
	v_mfma_f32_16x16x32_bf16 v[94:97], v[102:105], v[162:165], v[94:97]
	v_mfma_f32_16x16x32_bf16 v[90:93], v[202:205], v[166:169], v[90:93]
	v_mfma_f32_16x16x32_bf16 v[86:89], v[102:105], v[170:173], v[86:89]
	v_mfma_f32_16x16x32_bf16 v[82:85], v[202:205], v[174:177], v[82:85]
	v_mfma_f32_16x16x32_bf16 v[78:81], v[102:105], v[178:181], v[78:81]
	v_mfma_f32_16x16x32_bf16 v[74:77], v[202:205], v[182:185], v[74:77]
	v_mfma_f32_16x16x32_bf16 v[70:73], v[102:105], v[186:189], v[70:73]
	v_mfma_f32_16x16x32_bf16 v[66:69], v[202:205], v[190:193], v[66:69]
	v_mfma_f32_16x16x32_bf16 v[206:209], v[110:113], v[166:169], v[94:97]
	v_mfma_f32_16x16x32_bf16 v[162:165], v[110:113], v[174:177], v[86:89]
	v_mfma_f32_16x16x32_bf16 v[166:169], v[110:113], v[182:185], v[78:81]
	v_mfma_f32_16x16x32_bf16 v[170:173], v[110:113], v[190:193], v[70:73]
	s_setprio 0
	s_barrier
	s_nop 0
	ds_read_b128 v[70:73], v222 offset:16384
	ds_read_b128 v[78:81], v222 offset:17408
	ds_read_b128 v[86:89], v222 offset:18432
	ds_read_b128 v[94:97], v222 offset:19456
	ds_read_b128 v[174:177], v222 offset:20480
	ds_read_b128 v[178:181], v222 offset:21504
	ds_read_b128 v[182:185], v222 offset:22528
	ds_read_b128 v[186:189], v222 offset:23552
	s_waitcnt vmcnt(4)
	s_barrier
	s_waitcnt lgkmcnt(0)
	s_setprio 2
	s_waitcnt lgkmcnt(0)
	v_mfma_f32_16x16x32_bf16 v[62:65], v[146:149], v[70:73], v[62:65]
	v_mfma_f32_16x16x32_bf16 v[58:61], v[154:157], v[70:73], v[58:61]
	v_mfma_f32_16x16x32_bf16 v[54:57], v[146:149], v[86:89], v[54:57]
	v_mfma_f32_16x16x32_bf16 v[50:53], v[154:157], v[86:89], v[50:53]
	v_mfma_f32_16x16x32_bf16 v[38:41], v[146:149], v[182:185], v[38:41]
	v_mfma_f32_16x16x32_bf16 v[34:37], v[154:157], v[182:185], v[34:37]
	v_mfma_f32_16x16x32_bf16 v[62:65], v[150:153], v[78:81], v[62:65]
	v_mfma_f32_16x16x32_bf16 v[58:61], v[158:161], v[78:81], v[58:61]
	v_mfma_f32_16x16x32_bf16 v[54:57], v[150:153], v[94:97], v[54:57]
	v_mfma_f32_16x16x32_bf16 v[50:53], v[158:161], v[94:97], v[50:53]
	v_mfma_f32_16x16x32_bf16 v[46:49], v[146:149], v[174:177], v[46:49]
	v_mfma_f32_16x16x32_bf16 v[42:45], v[154:157], v[174:177], v[42:45]
	v_mfma_f32_16x16x32_bf16 v[38:41], v[150:153], v[186:189], v[38:41]
	v_mfma_f32_16x16x32_bf16 v[34:37], v[158:161], v[186:189], v[34:37]
	v_mfma_f32_16x16x32_bf16 v[190:193], v[150:153], v[178:181], v[46:49]
	v_mfma_f32_16x16x32_bf16 v[210:213], v[158:161], v[178:181], v[42:45]
	s_setprio 0
	s_setprio 2
	v_mfma_f32_16x16x32_bf16 v[22:25], v[102:105], v[86:89], v[22:25]
	v_mfma_f32_16x16x32_bf16 v[18:21], v[118:121], v[86:89], v[18:21]
	v_mfma_f32_16x16x32_bf16 v[6:9], v[102:105], v[182:185], v[6:9]
	v_mfma_f32_16x16x32_bf16 v[2:5], v[118:121], v[182:185], v[2:5]
	v_mfma_f32_16x16x32_bf16 v[30:33], v[102:105], v[70:73], v[30:33]
	v_mfma_f32_16x16x32_bf16 v[26:29], v[118:121], v[70:73], v[26:29]
	v_mfma_f32_16x16x32_bf16 v[22:25], v[110:113], v[94:97], v[22:25]
	v_mfma_f32_16x16x32_bf16 v[18:21], v[202:205], v[94:97], v[18:21]
	v_mfma_f32_16x16x32_bf16 v[14:17], v[102:105], v[174:177], v[14:17]
	v_mfma_f32_16x16x32_bf16 v[10:13], v[118:121], v[174:177], v[10:13]
	v_mfma_f32_16x16x32_bf16 v[6:9], v[110:113], v[186:189], v[6:9]
	v_mfma_f32_16x16x32_bf16 v[2:5], v[202:205], v[186:189], v[2:5]
	v_mfma_f32_16x16x32_bf16 v[146:149], v[110:113], v[78:81], v[30:33]
	v_mfma_f32_16x16x32_bf16 v[150:153], v[202:205], v[78:81], v[26:29]
	v_mfma_f32_16x16x32_bf16 v[154:157], v[110:113], v[178:181], v[14:17]
	v_mfma_f32_16x16x32_bf16 v[158:161], v[202:205], v[178:181], v[10:13]
	s_setprio 0
	s_barrier
	s_nop 0
	ds_read_b128 v[10:13], v145 offset:32768
	ds_read_b128 v[14:17], v145 offset:33792
	ds_read_b128 v[174:177], v145 offset:34816
	ds_read_b128 v[178:181], v145 offset:35840
	ds_read_b128 v[26:29], v222 offset:32768
	ds_read_b128 v[30:33], v222 offset:33792
	ds_read_b128 v[42:45], v222 offset:34816
	ds_read_b128 v[46:49], v222 offset:35840
	ds_read_b128 v[182:185], v222 offset:36864
	ds_read_b128 v[186:189], v222 offset:37888
	ds_read_b128 v[202:205], v222 offset:38912
	ds_read_b128 v[214:217], v222 offset:39936
	s_waitcnt vmcnt(2)
	s_barrier
; #define WAIT_V(n) asm volatile("s_waitcnt vmcnt(" #n ")" ::: "memory")
; #define WAIT_L(n) asm volatile("s_waitcnt lgkmcnt(" #n ")" ::: "memory")
; #define BAR __builtin_amdgcn_s_barrier()
; #define LDA(dst, b, h) _Pragma("unroll") for (int m = 0; m < 4; ++m) _Pragma("unroll") for (int k = 0; k < 2; ++k) \
;     dst[m][k] = *(const s16x8*)(smem + a_rdo + ((b) * 2 + (h)) * 16384 + m * 2048 + k * 1024)
; #define LDB(dst, b, h) _Pragma("unroll") for (int n = 0; n < 2; ++n) _Pragma("unroll") for (int k = 0; k < 2; ++k) \
;     dst[n][k] = *(const s16x8*)(smem + b_rdo + ((b) * 2 + (h)) * 16384 + n * 2048 + k * 1024)
; #define MMA(ai, bj, Ax, Bx) do { __builtin_amdgcn_s_setprio(1); \
;     _Pragma("unroll") for (int m = 0; m < 4; ++m) _Pragma("unroll") for (int n = 0; n < 2; ++n) _Pragma("unroll") for (int k = 0; k < 2; ++k) \
;       acc[ai][bj][m][n] = MFMA16(Bx[n][k], Ax[m][k], acc[ai][bj][m][n]); \
;     __builtin_amdgcn_s_setprio(0); } while (0)
; template <int EPI>
; __device__ void gemm8(const bf16* A, const bf16* Bt, const int K, const int ntN, const int ntTot, const EpiArgs ea, char* smem) {
;     ...
;     { LDB(B0, 1, 0); LDA(At, 1, 0); WAIT_V(2); BAR; WAIT_L(0); MMA(0, 0, At, B0); BAR;
;       LDB(B1, 1, 1); WAIT_V(0); BAR; WAIT_L(0); MMA(0, 1, At, B1); BAR;
;       LDA(At, 1, 1); BAR; WAIT_L(0); MMA(1, 0, At, B0); MMA(1, 1, At, B1); BAR; }
;     if (wr == 0) BAR;
	s_waitcnt lgkmcnt(0)
	s_setprio 2
	s_waitcnt lgkmcnt(0)
	v_mfma_f32_16x16x32_bf16 v[70:73], v[10:13], v[26:29], v[126:129]
	v_mfma_f32_16x16x32_bf16 v[126:129], v[14:17], v[30:33], v[70:73]
	v_mfma_f32_16x16x32_bf16 v[70:73], v[174:177], v[26:29], v[122:125]
	v_mfma_f32_16x16x32_bf16 v[118:121], v[178:181], v[30:33], v[70:73]
	v_mfma_f32_16x16x32_bf16 v[70:73], v[10:13], v[42:45], v[134:137]
	v_mfma_f32_16x16x32_bf16 v[110:113], v[14:17], v[46:49], v[70:73]
	v_mfma_f32_16x16x32_bf16 v[70:73], v[174:177], v[42:45], v[114:117]
	v_mfma_f32_16x16x32_bf16 v[102:105], v[178:181], v[46:49], v[70:73]
	v_mfma_f32_16x16x32_bf16 v[70:73], v[10:13], v[182:185], v[194:197]
	v_mfma_f32_16x16x32_bf16 v[94:97], v[14:17], v[186:189], v[70:73]
	v_mfma_f32_16x16x32_bf16 v[70:73], v[174:177], v[182:185], v[106:109]
	v_mfma_f32_16x16x32_bf16 v[86:89], v[178:181], v[186:189], v[70:73]
	v_mfma_f32_16x16x32_bf16 v[70:73], v[10:13], v[202:205], v[198:201]
	v_mfma_f32_16x16x32_bf16 v[78:81], v[14:17], v[214:217], v[70:73]
	v_mfma_f32_16x16x32_bf16 v[70:73], v[174:177], v[202:205], v[98:101]
	v_mfma_f32_16x16x32_bf16 v[70:73], v[178:181], v[214:217], v[70:73]
	s_setprio 0
	s_barrier
	ds_read_b128 v[134:137], v145 offset:49152
	ds_read_b128 v[194:197], v145 offset:50176
	ds_read_b128 v[198:201], v145 offset:51200
	ds_read_b128 v[218:221], v145 offset:52224
	s_waitcnt vmcnt(0)
	s_barrier
	s_waitcnt lgkmcnt(0)
	s_setprio 2
	s_waitcnt lgkmcnt(0)
	v_mfma_f32_16x16x32_bf16 v[98:101], v[134:137], v[26:29], v[206:209]
	v_mfma_f32_16x16x32_bf16 v[26:29], v[198:201], v[26:29], v[90:93]
	v_mfma_f32_16x16x32_bf16 v[114:117], v[218:221], v[30:33], v[26:29]
	v_mfma_f32_16x16x32_bf16 v[26:29], v[134:137], v[42:45], v[162:165]
	v_mfma_f32_16x16x32_bf16 v[106:109], v[194:197], v[46:49], v[26:29]
	v_mfma_f32_16x16x32_bf16 v[26:29], v[198:201], v[42:45], v[82:85]
	v_mfma_f32_16x16x32_bf16 v[122:125], v[194:197], v[30:33], v[98:101]
	v_mfma_f32_16x16x32_bf16 v[98:101], v[218:221], v[46:49], v[26:29]
	v_mfma_f32_16x16x32_bf16 v[26:29], v[134:137], v[182:185], v[166:169]
	v_mfma_f32_16x16x32_bf16 v[90:93], v[194:197], v[186:189], v[26:29]
	v_mfma_f32_16x16x32_bf16 v[26:29], v[198:201], v[182:185], v[74:77]
	v_mfma_f32_16x16x32_bf16 v[82:85], v[218:221], v[186:189], v[26:29]
	v_mfma_f32_16x16x32_bf16 v[26:29], v[134:137], v[202:205], v[170:173]
	v_mfma_f32_16x16x32_bf16 v[74:77], v[194:197], v[214:217], v[26:29]
	v_mfma_f32_16x16x32_bf16 v[26:29], v[198:201], v[202:205], v[66:69]
	v_mfma_f32_16x16x32_bf16 v[66:69], v[218:221], v[214:217], v[26:29]
	s_setprio 0
	s_barrier
	ds_read_b128 v[162:165], v222 offset:49152
	ds_read_b128 v[166:169], v222 offset:50176
	ds_read_b128 v[170:173], v222 offset:51200
	ds_read_b128 v[182:185], v222 offset:52224
	ds_read_b128 v[186:189], v222 offset:53248
	ds_read_b128 v[202:205], v222 offset:54272
	ds_read_b128 v[206:209], v222 offset:55296
	ds_read_b128 v[214:217], v222 offset:56320
	s_barrier
	s_waitcnt lgkmcnt(0)
	s_setprio 2
	s_waitcnt lgkmcnt(0)
	v_mfma_f32_16x16x32_bf16 v[26:29], v[10:13], v[162:165], v[62:65]
	v_mfma_f32_16x16x32_bf16 v[62:65], v[14:17], v[166:169], v[26:29]
	v_mfma_f32_16x16x32_bf16 v[26:29], v[174:177], v[162:165], v[58:61]
	v_mfma_f32_16x16x32_bf16 v[58:61], v[178:181], v[166:169], v[26:29]
	v_mfma_f32_16x16x32_bf16 v[26:29], v[10:13], v[170:173], v[54:57]
	v_mfma_f32_16x16x32_bf16 v[46:49], v[14:17], v[182:185], v[26:29]
	v_mfma_f32_16x16x32_bf16 v[26:29], v[174:177], v[170:173], v[50:53]
	v_mfma_f32_16x16x32_bf16 v[42:45], v[178:181], v[182:185], v[26:29]
	v_mfma_f32_16x16x32_bf16 v[26:29], v[10:13], v[186:189], v[190:193]
	v_mfma_f32_16x16x32_bf16 v[10:13], v[10:13], v[206:209], v[38:41]
	v_mfma_f32_16x16x32_bf16 v[30:33], v[14:17], v[202:205], v[26:29]
	v_mfma_f32_16x16x32_bf16 v[26:29], v[174:177], v[186:189], v[210:213]
	v_mfma_f32_16x16x32_bf16 v[14:17], v[14:17], v[214:217], v[10:13]
	v_mfma_f32_16x16x32_bf16 v[10:13], v[174:177], v[206:209], v[34:37]
	v_mfma_f32_16x16x32_bf16 v[26:29], v[178:181], v[202:205], v[26:29]
	v_mfma_f32_16x16x32_bf16 v[10:13], v[178:181], v[214:217], v[10:13]
	s_setprio 0
	s_setprio 2
	v_mfma_f32_16x16x32_bf16 v[34:37], v[134:137], v[162:165], v[146:149]
	v_mfma_f32_16x16x32_bf16 v[54:57], v[194:197], v[166:169], v[34:37]
	v_mfma_f32_16x16x32_bf16 v[34:37], v[198:201], v[162:165], v[150:153]
	v_mfma_f32_16x16x32_bf16 v[18:21], v[198:201], v[170:173], v[18:21]
	v_mfma_f32_16x16x32_bf16 v[50:53], v[218:221], v[166:169], v[34:37]
	v_mfma_f32_16x16x32_bf16 v[22:25], v[134:137], v[170:173], v[22:25]
	v_mfma_f32_16x16x32_bf16 v[34:37], v[218:221], v[182:185], v[18:21]
	v_mfma_f32_16x16x32_bf16 v[18:21], v[134:137], v[186:189], v[154:157]
	v_mfma_f32_16x16x32_bf16 v[38:41], v[194:197], v[182:185], v[22:25]
	v_mfma_f32_16x16x32_bf16 v[22:25], v[194:197], v[202:205], v[18:21]
	v_mfma_f32_16x16x32_bf16 v[18:21], v[198:201], v[186:189], v[158:161]
	v_mfma_f32_16x16x32_bf16 v[6:9], v[134:137], v[206:209], v[6:9]
	v_mfma_f32_16x16x32_bf16 v[2:5], v[198:201], v[206:209], v[2:5]
	v_mfma_f32_16x16x32_bf16 v[18:21], v[218:221], v[202:205], v[18:21]
	v_mfma_f32_16x16x32_bf16 v[6:9], v[194:197], v[214:217], v[6:9]
	v_mfma_f32_16x16x32_bf16 v[2:5], v[218:221], v[214:217], v[2:5]
	s_setprio 0
	s_barrier
	s_and_saveexec_b64 s[0:1], s[40:41]
	s_cbranch_execz .LBB0_876
	s_barrier
	s_branch .LBB0_876

; #define WAIT_L(n) asm volatile("s_waitcnt lgkmcnt(" #n ")" ::: "memory")
; #define BAR __builtin_amdgcn_s_barrier()
; #define SCHED __builtin_amdgcn_sched_barrier(0)
; #define STAGEA(P, BASE, kt) do { const size_t SS_ = ssA; STAGE(P, BASE, kt); } while (0)
; #define STAGEB(P, BASE, kt) do { const size_t SS_ = ssB; STAGE(P, BASE, kt); } while (0)
; #define LDA(dst, b, h) _Pragma("unroll") for (int m = 0; m < 4; ++m) _Pragma("unroll") for (int k = 0; k < 2; ++k) \
;     dst[m][k] = *(const s16x8*)(smem + a_rdo + ((b) * 2 + (h)) * 16384 + m * 2048 + k * 1024)
; #define LDB(dst, b, h) _Pragma("unroll") for (int n = 0; n < 2; ++n) _Pragma("unroll") for (int k = 0; k < 2; ++k) \
;     dst[n][k] = *(const s16x8*)(smem + b_rdo + ((b) * 2 + (h)) * 16384 + n * 2048 + k * 1024)
; #define MMA(ai, bj, Ax, Bx) do { __builtin_amdgcn_s_setprio(1); \
;     _Pragma("unroll") for (int m = 0; m < 4; ++m) _Pragma("unroll") for (int n = 0; n < 2; ++n) _Pragma("unroll") for (int k = 0; k < 2; ++k) \
;       acc[ai][bj][m][n] = MFMA16(Bx[n][k], Ax[m][k], acc[ai][bj][m][n]); \
;     __builtin_amdgcn_s_setprio(0); } while (0)
; template <int EPI>
; __device__ void gemm8(const bf16* A, const bf16* Bt, const int K, const int ntN, const int ntTot, const EpiArgs ea, char* smem) {
;     ...
;       LDB(B0, 0, 0); SCHED; LDA(At, 0, 0); STAGEA(SA(1, 1), A1, t + 1);
;       WAIT_L(8); BAR; WAIT_L(0); MMA(0, 0, At, B0); BAR; SCHED;
;       LDB(B1, 0, 1); STAGEB(SB(0, 0), B0g, t + 2);
;       BAR; WAIT_L(0); MMA(0, 1, At, B1); BAR;
;       LDA(At, 0, 1); STAGEA(SA(0, 0), A0, t + 2);
;       BAR; WAIT_L(0); MMA(1, 0, At, B0); BAR; SCHED;
.LBB0_944:
	s_nop 0
	v_add_u32_e32 v133, 0, v132
	ds_read_b128 v[134:137], v133
	ds_read_b128 v[138:141], v133 offset:1024
	ds_read_b128 v[142:145], v133 offset:2048
	ds_read_b128 v[146:149], v133 offset:3072
	v_lshl_add_u64 v[206:207], s[16:17], 0, v[196:197]
	s_mov_b64 s[2:3], 0x53d4000
	v_lshl_add_u64 v[182:183], v[206:207], 0, s[2:3]
	s_add_i32 s2, s27, 0xc000
	v_add_u32_e32 v212, 0, v0
	s_mov_b32 m0, s2
	s_mov_b64 s[30:31], 0x53d6000
	s_add_i32 s1, s27, 0xe000
	ds_read_b128 v[150:153], v212
	ds_read_b128 v[154:157], v212 offset:1024
	ds_read_b128 v[158:161], v212 offset:2048
	ds_read_b128 v[162:165], v212 offset:3072
	ds_read_b128 v[166:169], v212 offset:4096
	ds_read_b128 v[170:173], v212 offset:5120
	ds_read_b128 v[174:177], v212 offset:6144
	ds_read_b128 v[178:181], v212 offset:7168
	global_load_lds_dwordx4 v[182:183], off
	v_lshl_add_u64 v[182:183], v[206:207], 0, s[30:31]
	s_mov_b32 m0, s1
	s_nop 0
	global_load_lds_dwordx4 v[182:183], off
	s_waitcnt lgkmcnt(8)
	s_barrier
	s_waitcnt lgkmcnt(0)
	s_setprio 2
	s_waitcnt lgkmcnt(0)
	v_mfma_f32_16x16x32_bf16 v[126:129], v[134:137], v[150:153], v[126:129]
	v_mfma_f32_16x16x32_bf16 v[122:125], v[142:145], v[150:153], v[122:125]
	v_mfma_f32_16x16x32_bf16 v[118:121], v[134:137], v[158:161], v[118:121]
	v_mfma_f32_16x16x32_bf16 v[114:117], v[142:145], v[158:161], v[114:117]
	v_mfma_f32_16x16x32_bf16 v[106:109], v[134:137], v[166:169], v[106:109]
	v_mfma_f32_16x16x32_bf16 v[90:93], v[142:145], v[166:169], v[90:93]
	v_mfma_f32_16x16x32_bf16 v[74:77], v[134:137], v[174:177], v[74:77]
	v_mfma_f32_16x16x32_bf16 v[54:57], v[142:145], v[174:177], v[54:57]
	v_mfma_f32_16x16x32_bf16 v[126:129], v[138:141], v[154:157], v[126:129]
	v_mfma_f32_16x16x32_bf16 v[122:125], v[146:149], v[154:157], v[122:125]
	v_mfma_f32_16x16x32_bf16 v[118:121], v[138:141], v[162:165], v[118:121]
	v_mfma_f32_16x16x32_bf16 v[114:117], v[146:149], v[162:165], v[114:117]
	v_mfma_f32_16x16x32_bf16 v[106:109], v[138:141], v[170:173], v[106:109]
	v_mfma_f32_16x16x32_bf16 v[90:93], v[146:149], v[170:173], v[90:93]
	v_mfma_f32_16x16x32_bf16 v[74:77], v[138:141], v[178:181], v[74:77]
	v_mfma_f32_16x16x32_bf16 v[54:57], v[146:149], v[178:181], v[54:57]
	s_setprio 0
	s_barrier
	v_lshl_add_u64 v[208:209], s[20:21], 0, v[196:197]
	s_mov_b64 s[30:31], 0x1f40000
	s_mov_b32 m0, s7
	v_lshl_add_u64 v[210:211], v[208:209], 0, s[30:31]
	s_mov_b64 s[30:31], 0x1f42000
	ds_read_b128 v[182:185], v133 offset:16384
	ds_read_b128 v[186:189], v133 offset:17408
	ds_read_b128 v[198:201], v133 offset:18432
	ds_read_b128 v[202:205], v133 offset:19456
	global_load_lds_dwordx4 v[210:211], off
	v_lshl_add_u64 v[210:211], v[208:209], 0, s[30:31]
	s_mov_b32 m0, s9
	s_nop 0
	global_load_lds_dwordx4 v[210:211], off
	s_barrier
	s_waitcnt lgkmcnt(0)
	s_setprio 2
	s_waitcnt lgkmcnt(0)
	v_mfma_f32_16x16x32_bf16 v[30:33], v[182:185], v[150:153], v[30:33]
	v_mfma_f32_16x16x32_bf16 v[26:29], v[198:201], v[150:153], v[26:29]
	v_mfma_f32_16x16x32_bf16 v[22:25], v[182:185], v[158:161], v[22:25]
	v_mfma_f32_16x16x32_bf16 v[18:21], v[198:201], v[158:161], v[18:21]
	v_mfma_f32_16x16x32_bf16 v[14:17], v[182:185], v[166:169], v[14:17]
	v_mfma_f32_16x16x32_bf16 v[10:13], v[198:201], v[166:169], v[10:13]
	v_mfma_f32_16x16x32_bf16 v[6:9], v[182:185], v[174:177], v[6:9]
	v_mfma_f32_16x16x32_bf16 v[2:5], v[198:201], v[174:177], v[2:5]
	v_mfma_f32_16x16x32_bf16 v[30:33], v[186:189], v[154:157], v[30:33]
	v_mfma_f32_16x16x32_bf16 v[26:29], v[202:205], v[154:157], v[26:29]
	v_mfma_f32_16x16x32_bf16 v[22:25], v[186:189], v[162:165], v[22:25]
	v_mfma_f32_16x16x32_bf16 v[18:21], v[202:205], v[162:165], v[18:21]
	v_mfma_f32_16x16x32_bf16 v[14:17], v[186:189], v[170:173], v[14:17]
	v_mfma_f32_16x16x32_bf16 v[10:13], v[202:205], v[170:173], v[10:13]
	v_mfma_f32_16x16x32_bf16 v[6:9], v[186:189], v[178:181], v[6:9]
	v_mfma_f32_16x16x32_bf16 v[2:5], v[202:205], v[178:181], v[2:5]
	s_setprio 0
	s_mov_b64 s[30:31], 0x55d0000
	s_mov_b32 m0, s27
	v_lshl_add_u64 v[210:211], v[206:207], 0, s[30:31]
	s_mov_b64 s[30:31], 0x55d2000
	s_barrier
	ds_read_b128 v[150:153], v212 offset:16384
	ds_read_b128 v[154:157], v212 offset:17408
	ds_read_b128 v[158:161], v212 offset:18432
	ds_read_b128 v[162:165], v212 offset:19456
	ds_read_b128 v[166:169], v212 offset:20480
	ds_read_b128 v[170:173], v212 offset:21504
	ds_read_b128 v[174:177], v212 offset:22528
	ds_read_b128 v[178:181], v212 offset:23552
	global_load_lds_dwordx4 v[210:211], off
	v_lshl_add_u64 v[210:211], v[206:207], 0, s[30:31]
	s_mov_b32 m0, s15
	s_nop 0
	global_load_lds_dwordx4 v[210:211], off
	s_barrier
	s_waitcnt lgkmcnt(0)
	s_setprio 2
	s_waitcnt lgkmcnt(0)
	v_mfma_f32_16x16x32_bf16 v[34:37], v[134:137], v[150:153], v[34:37]
	v_mfma_f32_16x16x32_bf16 v[38:41], v[142:145], v[150:153], v[38:41]
	v_mfma_f32_16x16x32_bf16 v[42:45], v[134:137], v[158:161], v[42:45]
	v_mfma_f32_16x16x32_bf16 v[46:49], v[142:145], v[158:161], v[46:49]
	v_mfma_f32_16x16x32_bf16 v[50:53], v[134:137], v[166:169], v[50:53]
	v_mfma_f32_16x16x32_bf16 v[58:61], v[142:145], v[166:169], v[58:61]
	v_mfma_f32_16x16x32_bf16 v[62:65], v[134:137], v[174:177], v[62:65]
	v_mfma_f32_16x16x32_bf16 v[66:69], v[142:145], v[174:177], v[66:69]
	v_mfma_f32_16x16x32_bf16 v[34:37], v[138:141], v[154:157], v[34:37]
	v_mfma_f32_16x16x32_bf16 v[38:41], v[146:149], v[154:157], v[38:41]
	v_mfma_f32_16x16x32_bf16 v[42:45], v[138:141], v[162:165], v[42:45]
	v_mfma_f32_16x16x32_bf16 v[46:49], v[146:149], v[162:165], v[46:49]
	v_mfma_f32_16x16x32_bf16 v[50:53], v[138:141], v[170:173], v[50:53]
	v_mfma_f32_16x16x32_bf16 v[58:61], v[146:149], v[170:173], v[58:61]
	v_mfma_f32_16x16x32_bf16 v[62:65], v[138:141], v[178:181], v[62:65]
	v_mfma_f32_16x16x32_bf16 v[66:69], v[146:149], v[178:181], v[66:69]
	s_setprio 0
	s_barrier
; #define WAIT_V(n) asm volatile("s_waitcnt vmcnt(" #n ")" ::: "memory")
; #define WAIT_L(n) asm volatile("s_waitcnt lgkmcnt(" #n ")" ::: "memory")
; #define BAR __builtin_amdgcn_s_barrier()
; #define SCHED __builtin_amdgcn_sched_barrier(0)
; #define STAGEA(P, BASE, kt) do { const size_t SS_ = ssA; STAGE(P, BASE, kt); } while (0)
; #define STAGEB(P, BASE, kt) do { const size_t SS_ = ssB; STAGE(P, BASE, kt); } while (0)
; #define LDA(dst, b, h) _Pragma("unroll") for (int m = 0; m < 4; ++m) _Pragma("unroll") for (int k = 0; k < 2; ++k) \
;     dst[m][k] = *(const s16x8*)(smem + a_rdo + ((b) * 2 + (h)) * 16384 + m * 2048 + k * 1024)
; #define LDB(dst, b, h) _Pragma("unroll") for (int n = 0; n < 2; ++n) _Pragma("unroll") for (int k = 0; k < 2; ++k) \
;     dst[n][k] = *(const s16x8*)(smem + b_rdo + ((b) * 2 + (h)) * 16384 + n * 2048 + k * 1024)
; #define MMA(ai, bj, Ax, Bx) do { __builtin_amdgcn_s_setprio(1); \
;     _Pragma("unroll") for (int m = 0; m < 4; ++m) _Pragma("unroll") for (int n = 0; n < 2; ++n) _Pragma("unroll") for (int k = 0; k < 2; ++k) \
;       acc[ai][bj][m][n] = MFMA16(Bx[n][k], Ax[m][k], acc[ai][bj][m][n]); \
;     __builtin_amdgcn_s_setprio(0); } while (0)
; template <int EPI>
; __device__ void gemm8(const bf16* A, const bf16* Bt, const int K, const int ntN, const int ntTot, const EpiArgs ea, char* smem) {
;     ...
;       STAGEB(SB(0, 1), B1g, t + 2);
;       WAIT_V(6); BAR; MMA(1, 1, At, B1); BAR;
;       LDB(B0, 1, 0); SCHED; LDA(At, 1, 0); STAGEA(SA(0, 1), A1, t + 2);
;       WAIT_L(8); BAR; WAIT_L(0); MMA(0, 0, At, B0); BAR; SCHED;
;       LDB(B1, 1, 1); STAGEB(SB(1, 0), B0g, t + 3);
;       BAR; WAIT_L(0); MMA(0, 1, At, B1); BAR;
;       LDA(At, 1, 1); STAGEA(SA(1, 0), A0, t + 3);
;       BAR; WAIT_L(0); MMA(1, 0, At, B0); BAR; SCHED;
	s_mov_b64 s[30:31], 0x1f44000
	s_mov_b32 m0, s35
	v_lshl_add_u64 v[134:135], v[208:209], 0, s[30:31]
	s_mov_b64 s[30:31], 0x1f46000
	global_load_lds_dwordx4 v[134:135], off
	v_lshl_add_u64 v[134:135], v[208:209], 0, s[30:31]
	s_mov_b32 m0, s44
	s_nop 0
	global_load_lds_dwordx4 v[134:135], off
	s_waitcnt vmcnt(6)
	s_barrier
	s_setprio 2
	v_mfma_f32_16x16x32_bf16 v[70:73], v[182:185], v[150:153], v[70:73]
	v_mfma_f32_16x16x32_bf16 v[78:81], v[198:201], v[150:153], v[78:81]
	v_mfma_f32_16x16x32_bf16 v[82:85], v[182:185], v[158:161], v[82:85]
	v_mfma_f32_16x16x32_bf16 v[86:89], v[198:201], v[158:161], v[86:89]
	v_mfma_f32_16x16x32_bf16 v[94:97], v[182:185], v[166:169], v[94:97]
	v_mfma_f32_16x16x32_bf16 v[98:101], v[198:201], v[166:169], v[98:101]
	v_mfma_f32_16x16x32_bf16 v[102:105], v[182:185], v[174:177], v[102:105]
	v_mfma_f32_16x16x32_bf16 v[110:113], v[198:201], v[174:177], v[110:113]
	v_mfma_f32_16x16x32_bf16 v[70:73], v[186:189], v[154:157], v[70:73]
	v_mfma_f32_16x16x32_bf16 v[78:81], v[202:205], v[154:157], v[78:81]
	v_mfma_f32_16x16x32_bf16 v[82:85], v[186:189], v[162:165], v[82:85]
	v_mfma_f32_16x16x32_bf16 v[86:89], v[202:205], v[162:165], v[86:89]
	v_mfma_f32_16x16x32_bf16 v[94:97], v[186:189], v[170:173], v[94:97]
	v_mfma_f32_16x16x32_bf16 v[98:101], v[202:205], v[170:173], v[98:101]
	v_mfma_f32_16x16x32_bf16 v[102:105], v[186:189], v[178:181], v[102:105]
	v_mfma_f32_16x16x32_bf16 v[110:113], v[202:205], v[178:181], v[110:113]
	s_setprio 0
	s_barrier
	ds_read_b128 v[134:137], v133 offset:32768
	ds_read_b128 v[138:141], v133 offset:33792
	ds_read_b128 v[142:145], v133 offset:34816
	ds_read_b128 v[146:149], v133 offset:35840
	s_mov_b64 s[30:31], 0x55d4000
	s_mov_b32 m0, s45
	v_lshl_add_u64 v[182:183], v[206:207], 0, s[30:31]
	s_mov_b64 s[30:31], 0x55d6000
	ds_read_b128 v[150:153], v212 offset:32768
	ds_read_b128 v[154:157], v212 offset:33792
	ds_read_b128 v[158:161], v212 offset:34816
	ds_read_b128 v[162:165], v212 offset:35840
	ds_read_b128 v[166:169], v212 offset:36864
	ds_read_b128 v[170:173], v212 offset:37888
	ds_read_b128 v[174:177], v212 offset:38912
	ds_read_b128 v[178:181], v212 offset:39936
	global_load_lds_dwordx4 v[182:183], off
	v_lshl_add_u64 v[182:183], v[206:207], 0, s[30:31]
	s_mov_b32 m0, s46
	s_nop 0
	global_load_lds_dwordx4 v[182:183], off
	s_waitcnt lgkmcnt(8)
	s_barrier
	s_waitcnt lgkmcnt(0)
	s_setprio 2
	s_waitcnt lgkmcnt(0)
	v_mfma_f32_16x16x32_bf16 v[126:129], v[134:137], v[150:153], v[126:129]
	v_mfma_f32_16x16x32_bf16 v[122:125], v[142:145], v[150:153], v[122:125]
	v_mfma_f32_16x16x32_bf16 v[118:121], v[134:137], v[158:161], v[118:121]
	v_mfma_f32_16x16x32_bf16 v[114:117], v[142:145], v[158:161], v[114:117]
	v_mfma_f32_16x16x32_bf16 v[106:109], v[134:137], v[166:169], v[106:109]
	v_mfma_f32_16x16x32_bf16 v[90:93], v[142:145], v[166:169], v[90:93]
	v_mfma_f32_16x16x32_bf16 v[74:77], v[134:137], v[174:177], v[74:77]
	v_mfma_f32_16x16x32_bf16 v[54:57], v[142:145], v[174:177], v[54:57]
	v_mfma_f32_16x16x32_bf16 v[126:129], v[138:141], v[154:157], v[126:129]
	v_mfma_f32_16x16x32_bf16 v[122:125], v[146:149], v[154:157], v[122:125]
	v_mfma_f32_16x16x32_bf16 v[118:121], v[138:141], v[162:165], v[118:121]
	v_mfma_f32_16x16x32_bf16 v[114:117], v[146:149], v[162:165], v[114:117]
	v_mfma_f32_16x16x32_bf16 v[106:109], v[138:141], v[170:173], v[106:109]
	v_mfma_f32_16x16x32_bf16 v[90:93], v[146:149], v[170:173], v[90:93]
	v_mfma_f32_16x16x32_bf16 v[74:77], v[138:141], v[178:181], v[74:77]
	v_mfma_f32_16x16x32_bf16 v[54:57], v[146:149], v[178:181], v[54:57]
	s_setprio 0
	s_barrier
	s_mov_b64 s[30:31], 0x1f60000
	s_mov_b32 m0, s10
	v_lshl_add_u64 v[210:211], v[208:209], 0, s[30:31]
	s_mov_b64 s[30:31], 0x1f62000
	ds_read_b128 v[182:185], v133 offset:49152
	ds_read_b128 v[186:189], v133 offset:50176
	ds_read_b128 v[198:201], v133 offset:51200
	ds_read_b128 v[202:205], v133 offset:52224
	global_load_lds_dwordx4 v[210:211], off
	v_lshl_add_u64 v[210:211], v[208:209], 0, s[30:31]
	s_mov_b32 m0, s11
	s_nop 0
	global_load_lds_dwordx4 v[210:211], off
	s_barrier
	s_waitcnt lgkmcnt(0)
	s_setprio 2
	s_waitcnt lgkmcnt(0)
	v_mfma_f32_16x16x32_bf16 v[30:33], v[182:185], v[150:153], v[30:33]
	v_mfma_f32_16x16x32_bf16 v[26:29], v[198:201], v[150:153], v[26:29]
	v_mfma_f32_16x16x32_bf16 v[22:25], v[182:185], v[158:161], v[22:25]
	v_mfma_f32_16x16x32_bf16 v[18:21], v[198:201], v[158:161], v[18:21]
	v_mfma_f32_16x16x32_bf16 v[14:17], v[182:185], v[166:169], v[14:17]
	v_mfma_f32_16x16x32_bf16 v[10:13], v[198:201], v[166:169], v[10:13]
	v_mfma_f32_16x16x32_bf16 v[6:9], v[182:185], v[174:177], v[6:9]
	v_mfma_f32_16x16x32_bf16 v[2:5], v[198:201], v[174:177], v[2:5]
	v_mfma_f32_16x16x32_bf16 v[30:33], v[186:189], v[154:157], v[30:33]
	v_mfma_f32_16x16x32_bf16 v[26:29], v[202:205], v[154:157], v[26:29]
	v_mfma_f32_16x16x32_bf16 v[22:25], v[186:189], v[162:165], v[22:25]
	v_mfma_f32_16x16x32_bf16 v[18:21], v[202:205], v[162:165], v[18:21]
	v_mfma_f32_16x16x32_bf16 v[14:17], v[186:189], v[170:173], v[14:17]
	v_mfma_f32_16x16x32_bf16 v[10:13], v[202:205], v[170:173], v[10:13]
	v_mfma_f32_16x16x32_bf16 v[6:9], v[186:189], v[178:181], v[6:9]
	v_mfma_f32_16x16x32_bf16 v[2:5], v[202:205], v[178:181], v[2:5]
	s_setprio 0
	s_mov_b64 s[30:31], 0x57d0000
	s_mov_b32 m0, s47
	v_lshl_add_u64 v[210:211], v[206:207], 0, s[30:31]
	s_mov_b64 s[30:31], 0x57d2000
	s_barrier
	ds_read_b128 v[150:153], v212 offset:49152
	ds_read_b128 v[154:157], v212 offset:50176
	ds_read_b128 v[158:161], v212 offset:51200
	ds_read_b128 v[162:165], v212 offset:52224
	ds_read_b128 v[166:169], v212 offset:53248
	ds_read_b128 v[170:173], v212 offset:54272
	ds_read_b128 v[174:177], v212 offset:55296
	ds_read_b128 v[178:181], v212 offset:56320
	global_load_lds_dwordx4 v[210:211], off
	v_lshl_add_u64 v[206:207], v[206:207], 0, s[30:31]
	s_mov_b32 m0, s48
	s_nop 0
	global_load_lds_dwordx4 v[206:207], off
	s_barrier
; #define WAIT_V(n) asm volatile("s_waitcnt vmcnt(" #n ")" ::: "memory")
; #define WAIT_L(n) asm volatile("s_waitcnt lgkmcnt(" #n ")" ::: "memory")
; #define BAR __builtin_amdgcn_s_barrier()
; #define SCHED __builtin_amdgcn_sched_barrier(0)
; #define STAGEA(P, BASE, kt) do { const size_t SS_ = ssA; STAGE(P, BASE, kt); } while (0)
; #define STAGEB(P, BASE, kt) do { const size_t SS_ = ssB; STAGE(P, BASE, kt); } while (0)
; #define LDA(dst, b, h) _Pragma("unroll") for (int m = 0; m < 4; ++m) _Pragma("unroll") for (int k = 0; k < 2; ++k) \
;     dst[m][k] = *(const s16x8*)(smem + a_rdo + ((b) * 2 + (h)) * 16384 + m * 2048 + k * 1024)
; #define LDB(dst, b, h) _Pragma("unroll") for (int n = 0; n < 2; ++n) _Pragma("unroll") for (int k = 0; k < 2; ++k) \
;     dst[n][k] = *(const s16x8*)(smem + b_rdo + ((b) * 2 + (h)) * 16384 + n * 2048 + k * 1024)
; #define MMA(ai, bj, Ax, Bx) do { __builtin_amdgcn_s_setprio(1); \
;     _Pragma("unroll") for (int m = 0; m < 4; ++m) _Pragma("unroll") for (int n = 0; n < 2; ++n) _Pragma("unroll") for (int k = 0; k < 2; ++k) \
;       acc[ai][bj][m][n] = MFMA16(Bx[n][k], Ax[m][k], acc[ai][bj][m][n]); \
;     __builtin_amdgcn_s_setprio(0); } while (0)
; template <int EPI>
; __device__ void gemm8(const bf16* A, const bf16* Bt, const int K, const int ntN, const int ntTot, const EpiArgs ea, char* smem) {
;     ...
;       BAR; WAIT_L(0); MMA(1, 0, At, B0); BAR; SCHED;
;       STAGEB(SB(1, 1), B1g, t + 3);
;       WAIT_V(6); BAR; MMA(1, 1, At, B1); BAR;
;     }
;     asm volatile("" : "+v"(a_rdo), "+v"(b_rdo));
;     { LDB(B0, 0, 0); LDA(At, 0, 0); STAGEA(SA(1, 1), A1, nt - 1);
;       BAR; WAIT_L(0); MMA(0, 0, At, B0); BAR;
;       LDB(B1, 0, 1); BAR; WAIT_L(0); MMA(0, 1, At, B1); BAR;
	s_waitcnt lgkmcnt(0)
	s_setprio 2
	s_waitcnt lgkmcnt(0)
	v_mfma_f32_16x16x32_bf16 v[34:37], v[134:137], v[150:153], v[34:37]
	v_mfma_f32_16x16x32_bf16 v[38:41], v[142:145], v[150:153], v[38:41]
	v_mfma_f32_16x16x32_bf16 v[42:45], v[134:137], v[158:161], v[42:45]
	v_mfma_f32_16x16x32_bf16 v[46:49], v[142:145], v[158:161], v[46:49]
	v_mfma_f32_16x16x32_bf16 v[50:53], v[134:137], v[166:169], v[50:53]
	v_mfma_f32_16x16x32_bf16 v[58:61], v[142:145], v[166:169], v[58:61]
	v_mfma_f32_16x16x32_bf16 v[62:65], v[134:137], v[174:177], v[62:65]
	v_mfma_f32_16x16x32_bf16 v[66:69], v[142:145], v[174:177], v[66:69]
	v_mfma_f32_16x16x32_bf16 v[34:37], v[138:141], v[154:157], v[34:37]
	v_mfma_f32_16x16x32_bf16 v[38:41], v[146:149], v[154:157], v[38:41]
	v_mfma_f32_16x16x32_bf16 v[42:45], v[138:141], v[162:165], v[42:45]
	v_mfma_f32_16x16x32_bf16 v[46:49], v[146:149], v[162:165], v[46:49]
	v_mfma_f32_16x16x32_bf16 v[50:53], v[138:141], v[170:173], v[50:53]
	v_mfma_f32_16x16x32_bf16 v[58:61], v[146:149], v[170:173], v[58:61]
	v_mfma_f32_16x16x32_bf16 v[62:65], v[138:141], v[178:181], v[62:65]
	v_mfma_f32_16x16x32_bf16 v[66:69], v[146:149], v[178:181], v[66:69]
	s_setprio 0
	s_barrier
	s_mov_b64 s[30:31], 0x1f64000
	s_mov_b32 m0, s49
	v_lshl_add_u64 v[134:135], v[208:209], 0, s[30:31]
	s_mov_b64 s[30:31], 0x1f66000
	global_load_lds_dwordx4 v[134:135], off
	v_lshl_add_u64 v[134:135], v[208:209], 0, s[30:31]
	s_mov_b32 m0, s50
	s_nop 0
	global_load_lds_dwordx4 v[134:135], off
	s_waitcnt vmcnt(6)
	s_barrier
	s_setprio 2
	v_mfma_f32_16x16x32_bf16 v[70:73], v[182:185], v[150:153], v[70:73]
	v_mfma_f32_16x16x32_bf16 v[78:81], v[198:201], v[150:153], v[78:81]
	v_mfma_f32_16x16x32_bf16 v[82:85], v[182:185], v[158:161], v[82:85]
	v_mfma_f32_16x16x32_bf16 v[86:89], v[198:201], v[158:161], v[86:89]
	v_mfma_f32_16x16x32_bf16 v[94:97], v[182:185], v[166:169], v[94:97]
	v_mfma_f32_16x16x32_bf16 v[98:101], v[198:201], v[166:169], v[98:101]
	v_mfma_f32_16x16x32_bf16 v[102:105], v[182:185], v[174:177], v[102:105]
	v_mfma_f32_16x16x32_bf16 v[110:113], v[198:201], v[174:177], v[110:113]
	v_mfma_f32_16x16x32_bf16 v[70:73], v[186:189], v[154:157], v[70:73]
	v_mfma_f32_16x16x32_bf16 v[78:81], v[202:205], v[154:157], v[78:81]
	v_mfma_f32_16x16x32_bf16 v[82:85], v[186:189], v[162:165], v[82:85]
	v_mfma_f32_16x16x32_bf16 v[86:89], v[202:205], v[162:165], v[86:89]
	v_mfma_f32_16x16x32_bf16 v[94:97], v[186:189], v[170:173], v[94:97]
	v_mfma_f32_16x16x32_bf16 v[98:101], v[202:205], v[170:173], v[98:101]
	v_mfma_f32_16x16x32_bf16 v[102:105], v[186:189], v[178:181], v[102:105]
	v_mfma_f32_16x16x32_bf16 v[110:113], v[202:205], v[178:181], v[110:113]
	s_setprio 0
	s_add_i32 s0, s0, 2
	s_add_u32 s16, s16, 0x400000
	s_addc_u32 s17, s17, 0
	s_add_u32 s20, s20, 0x40000
	s_addc_u32 s21, s21, 0
	s_cmp_gt_u32 s0, 59
	s_barrier
	s_cbranch_scc0 .LBB0_944
	s_mov_b32 m0, s2
	s_mov_b64 s[2:3], 0x7e04000
	v_add_u32_e32 v232, 0, v132
	v_add_u32_e32 v0, 0, v0
	v_lshl_add_u64 v[180:181], v[130:131], 0, s[2:3]
	s_mov_b64 s[2:3], 0x7e06000
	ds_read_b128 v[132:135], v232
	ds_read_b128 v[136:139], v232 offset:1024
	ds_read_b128 v[140:143], v232 offset:2048
	ds_read_b128 v[144:147], v232 offset:3072
	ds_read_b128 v[148:151], v0
	ds_read_b128 v[152:155], v0 offset:1024
	ds_read_b128 v[156:159], v0 offset:2048
	ds_read_b128 v[160:163], v0 offset:3072
	ds_read_b128 v[164:167], v0 offset:4096
	ds_read_b128 v[168:171], v0 offset:5120
	ds_read_b128 v[172:175], v0 offset:6144
	ds_read_b128 v[176:179], v0 offset:7168
	global_load_lds_dwordx4 v[180:181], off
	v_lshl_add_u64 v[130:131], v[130:131], 0, s[2:3]
	s_mov_b32 m0, s1
	s_nop 0
	global_load_lds_dwordx4 v[130:131], off
	s_barrier
	s_waitcnt lgkmcnt(0)
	s_setprio 2
	s_waitcnt lgkmcnt(0)
	v_mfma_f32_16x16x32_bf16 v[126:129], v[132:135], v[148:151], v[126:129]
	v_mfma_f32_16x16x32_bf16 v[122:125], v[140:143], v[148:151], v[122:125]
	v_mfma_f32_16x16x32_bf16 v[106:109], v[132:135], v[164:167], v[106:109]
	v_mfma_f32_16x16x32_bf16 v[74:77], v[132:135], v[172:175], v[74:77]
	v_mfma_f32_16x16x32_bf16 v[54:57], v[140:143], v[172:175], v[54:57]
	v_mfma_f32_16x16x32_bf16 v[126:129], v[136:139], v[152:155], v[126:129]
	v_mfma_f32_16x16x32_bf16 v[122:125], v[144:147], v[152:155], v[122:125]
	v_mfma_f32_16x16x32_bf16 v[118:121], v[132:135], v[156:159], v[118:121]
	v_mfma_f32_16x16x32_bf16 v[114:117], v[140:143], v[156:159], v[114:117]
	v_mfma_f32_16x16x32_bf16 v[106:109], v[136:139], v[168:171], v[106:109]
	v_mfma_f32_16x16x32_bf16 v[90:93], v[140:143], v[164:167], v[90:93]
	v_mfma_f32_16x16x32_bf16 v[74:77], v[136:139], v[176:179], v[74:77]
	v_mfma_f32_16x16x32_bf16 v[54:57], v[144:147], v[176:179], v[54:57]
	v_mfma_f32_16x16x32_bf16 v[118:121], v[136:139], v[160:163], v[118:121]
	v_mfma_f32_16x16x32_bf16 v[114:117], v[144:147], v[160:163], v[114:117]
	v_mfma_f32_16x16x32_bf16 v[90:93], v[144:147], v[168:171], v[90:93]
	s_setprio 0
	s_barrier
	ds_read_b128 v[180:183], v232 offset:16384
	ds_read_b128 v[184:187], v232 offset:17408
	ds_read_b128 v[198:201], v232 offset:18432
	ds_read_b128 v[202:205], v232 offset:19456
	s_barrier
; #define WAIT_V(n) asm volatile("s_waitcnt vmcnt(" #n ")" ::: "memory")
; #define WAIT_L(n) asm volatile("s_waitcnt lgkmcnt(" #n ")" ::: "memory")
; #define BAR __builtin_amdgcn_s_barrier()
; #define LDA(dst, b, h) _Pragma("unroll") for (int m = 0; m < 4; ++m) _Pragma("unroll") for (int k = 0; k < 2; ++k) \
;     dst[m][k] = *(const s16x8*)(smem + a_rdo + ((b) * 2 + (h)) * 16384 + m * 2048 + k * 1024)
; #define LDB(dst, b, h) _Pragma("unroll") for (int n = 0; n < 2; ++n) _Pragma("unroll") for (int k = 0; k < 2; ++k) \
;     dst[n][k] = *(const s16x8*)(smem + b_rdo + ((b) * 2 + (h)) * 16384 + n * 2048 + k * 1024)
; #define MMA(ai, bj, Ax, Bx) do { __builtin_amdgcn_s_setprio(1); \
;     _Pragma("unroll") for (int m = 0; m < 4; ++m) _Pragma("unroll") for (int n = 0; n < 2; ++n) _Pragma("unroll") for (int k = 0; k < 2; ++k) \
;       acc[ai][bj][m][n] = MFMA16(Bx[n][k], Ax[m][k], acc[ai][bj][m][n]); \
;     __builtin_amdgcn_s_setprio(0); } while (0)
; template <int EPI>
; __device__ void gemm8(const bf16* A, const bf16* Bt, const int K, const int ntN, const int ntTot, const EpiArgs ea, char* smem) {
;     ...
;       LDB(B1, 0, 1); BAR; WAIT_L(0); MMA(0, 1, At, B1); BAR;
;       LDA(At, 0, 1); WAIT_V(4); BAR; WAIT_L(0); MMA(1, 0, At, B0); MMA(1, 1, At, B1); BAR; }
;     { LDB(B0, 1, 0); LDA(At, 1, 0); WAIT_V(2); BAR; WAIT_L(0); MMA(0, 0, At, B0); BAR;
	s_waitcnt lgkmcnt(0)
	s_setprio 2
	s_waitcnt lgkmcnt(0)
	v_mfma_f32_16x16x32_bf16 v[30:33], v[180:183], v[148:151], v[30:33]
	v_mfma_f32_16x16x32_bf16 v[26:29], v[198:201], v[148:151], v[26:29]
	v_mfma_f32_16x16x32_bf16 v[14:17], v[180:183], v[164:167], v[14:17]
	v_mfma_f32_16x16x32_bf16 v[10:13], v[198:201], v[164:167], v[10:13]
	v_mfma_f32_16x16x32_bf16 v[6:9], v[180:183], v[172:175], v[6:9]
	v_mfma_f32_16x16x32_bf16 v[2:5], v[198:201], v[172:175], v[2:5]
	v_mfma_f32_16x16x32_bf16 v[30:33], v[184:187], v[152:155], v[30:33]
	v_mfma_f32_16x16x32_bf16 v[26:29], v[202:205], v[152:155], v[26:29]
	v_mfma_f32_16x16x32_bf16 v[22:25], v[180:183], v[156:159], v[22:25]
	v_mfma_f32_16x16x32_bf16 v[18:21], v[198:201], v[156:159], v[18:21]
	v_mfma_f32_16x16x32_bf16 v[14:17], v[184:187], v[168:171], v[14:17]
	v_mfma_f32_16x16x32_bf16 v[10:13], v[202:205], v[168:171], v[10:13]
	v_mfma_f32_16x16x32_bf16 v[6:9], v[184:187], v[176:179], v[6:9]
	v_mfma_f32_16x16x32_bf16 v[2:5], v[202:205], v[176:179], v[2:5]
	v_mfma_f32_16x16x32_bf16 v[22:25], v[184:187], v[160:163], v[22:25]
	v_mfma_f32_16x16x32_bf16 v[18:21], v[202:205], v[160:163], v[18:21]
	s_setprio 0
	s_barrier
	ds_read_b128 v[148:151], v0 offset:16384
	ds_read_b128 v[152:155], v0 offset:17408
	ds_read_b128 v[156:159], v0 offset:18432
	ds_read_b128 v[160:163], v0 offset:19456
	ds_read_b128 v[164:167], v0 offset:20480
	ds_read_b128 v[168:171], v0 offset:21504
	ds_read_b128 v[172:175], v0 offset:22528
	ds_read_b128 v[176:179], v0 offset:23552
	s_waitcnt vmcnt(4)
	s_barrier
	s_waitcnt lgkmcnt(0)
	s_setprio 2
	s_waitcnt lgkmcnt(0)
	v_mfma_f32_16x16x32_bf16 v[58:61], v[140:143], v[164:167], v[58:61]
	v_mfma_f32_16x16x32_bf16 v[34:37], v[132:135], v[148:151], v[34:37]
	v_mfma_f32_16x16x32_bf16 v[38:41], v[140:143], v[148:151], v[38:41]
	v_mfma_f32_16x16x32_bf16 v[50:53], v[132:135], v[164:167], v[50:53]
	v_mfma_f32_16x16x32_bf16 v[206:209], v[144:147], v[168:171], v[58:61]
	v_mfma_f32_16x16x32_bf16 v[58:61], v[132:135], v[172:175], v[62:65]
	v_mfma_f32_16x16x32_bf16 v[34:37], v[136:139], v[152:155], v[34:37]
	v_mfma_f32_16x16x32_bf16 v[38:41], v[144:147], v[152:155], v[38:41]
	v_mfma_f32_16x16x32_bf16 v[42:45], v[132:135], v[156:159], v[42:45]
	v_mfma_f32_16x16x32_bf16 v[46:49], v[140:143], v[156:159], v[46:49]
	v_mfma_f32_16x16x32_bf16 v[50:53], v[136:139], v[168:171], v[50:53]
	v_mfma_f32_16x16x32_bf16 v[210:213], v[136:139], v[176:179], v[58:61]
	v_mfma_f32_16x16x32_bf16 v[58:61], v[140:143], v[172:175], v[66:69]
	v_mfma_f32_16x16x32_bf16 v[42:45], v[136:139], v[160:163], v[42:45]
	v_mfma_f32_16x16x32_bf16 v[46:49], v[144:147], v[160:163], v[46:49]
	v_mfma_f32_16x16x32_bf16 v[66:69], v[144:147], v[176:179], v[58:61]
	s_setprio 0
	s_setprio 2
	v_mfma_f32_16x16x32_bf16 v[58:61], v[180:183], v[148:151], v[70:73]
	v_mfma_f32_16x16x32_bf16 v[70:73], v[184:187], v[152:155], v[58:61]
	v_mfma_f32_16x16x32_bf16 v[58:61], v[198:201], v[148:151], v[78:81]
	v_mfma_f32_16x16x32_bf16 v[138:141], v[202:205], v[152:155], v[58:61]
	v_mfma_f32_16x16x32_bf16 v[58:61], v[180:183], v[156:159], v[82:85]
	v_mfma_f32_16x16x32_bf16 v[142:145], v[184:187], v[160:163], v[58:61]
	v_mfma_f32_16x16x32_bf16 v[58:61], v[198:201], v[156:159], v[86:89]
	v_mfma_f32_16x16x32_bf16 v[214:217], v[202:205], v[160:163], v[58:61]
	v_mfma_f32_16x16x32_bf16 v[58:61], v[180:183], v[164:167], v[94:97]
	v_mfma_f32_16x16x32_bf16 v[94:97], v[184:187], v[168:171], v[58:61]
	v_mfma_f32_16x16x32_bf16 v[58:61], v[198:201], v[164:167], v[98:101]
	v_mfma_f32_16x16x32_bf16 v[162:165], v[202:205], v[168:171], v[58:61]
	v_mfma_f32_16x16x32_bf16 v[58:61], v[180:183], v[172:175], v[102:105]
	v_mfma_f32_16x16x32_bf16 v[166:169], v[184:187], v[176:179], v[58:61]
	v_mfma_f32_16x16x32_bf16 v[58:61], v[198:201], v[172:175], v[110:113]
	v_mfma_f32_16x16x32_bf16 v[186:189], v[202:205], v[176:179], v[58:61]
	s_setprio 0
	s_barrier
	ds_read_b128 v[78:81], v232 offset:32768
	ds_read_b128 v[198:201], v232 offset:33792
	ds_read_b128 v[202:205], v232 offset:34816
	ds_read_b128 v[218:221], v232 offset:35840
	s_nop 0
	ds_read_b128 v[58:61], v0 offset:32768
	ds_read_b128 v[62:65], v0 offset:33792
	ds_read_b128 v[82:85], v0 offset:34816
	ds_read_b128 v[86:89], v0 offset:35840
	ds_read_b128 v[98:101], v0 offset:36864
	ds_read_b128 v[102:105], v0 offset:37888
	ds_read_b128 v[222:225], v0 offset:38912
	ds_read_b128 v[248:251], v0 offset:39936
	s_waitcnt vmcnt(2)
	s_barrier
; #define WAIT_V(n) asm volatile("s_waitcnt vmcnt(" #n ")" ::: "memory")
; #define WAIT_L(n) asm volatile("s_waitcnt lgkmcnt(" #n ")" ::: "memory")
; #define BAR __builtin_amdgcn_s_barrier()
; #define LDA(dst, b, h) _Pragma("unroll") for (int m = 0; m < 4; ++m) _Pragma("unroll") for (int k = 0; k < 2; ++k) \
;     dst[m][k] = *(const s16x8*)(smem + a_rdo + ((b) * 2 + (h)) * 16384 + m * 2048 + k * 1024)
; #define LDB(dst, b, h) _Pragma("unroll") for (int n = 0; n < 2; ++n) _Pragma("unroll") for (int k = 0; k < 2; ++k) \
;     dst[n][k] = *(const s16x8*)(smem + b_rdo + ((b) * 2 + (h)) * 16384 + n * 2048 + k * 1024)
; #define MMA(ai, bj, Ax, Bx) do { __builtin_amdgcn_s_setprio(1); \
;     _Pragma("unroll") for (int m = 0; m < 4; ++m) _Pragma("unroll") for (int n = 0; n < 2; ++n) _Pragma("unroll") for (int k = 0; k < 2; ++k) \
;       acc[ai][bj][m][n] = MFMA16(Bx[n][k], Ax[m][k], acc[ai][bj][m][n]); \
;     __builtin_amdgcn_s_setprio(0); } while (0)
; template <int EPI>
; __device__ void gemm8(const bf16* A, const bf16* Bt, const int K, const int ntN, const int ntTot, const EpiArgs ea, char* smem) {
;     ...
;     { LDB(B0, 1, 0); LDA(At, 1, 0); WAIT_V(2); BAR; WAIT_L(0); MMA(0, 0, At, B0); BAR;
;       LDB(B1, 1, 1); WAIT_V(0); BAR; WAIT_L(0); MMA(0, 1, At, B1); BAR;
;       LDA(At, 1, 1); BAR; WAIT_L(0); MMA(1, 0, At, B0); MMA(1, 1, At, B1); BAR; }
;     if (wr == 0) BAR;
	s_waitcnt lgkmcnt(0)
	s_setprio 2
	s_waitcnt lgkmcnt(0)
	v_mfma_f32_16x16x32_bf16 v[110:113], v[78:81], v[58:61], v[126:129]
	v_mfma_f32_16x16x32_bf16 v[182:185], v[198:201], v[62:65], v[110:113]
	v_mfma_f32_16x16x32_bf16 v[110:113], v[202:205], v[58:61], v[122:125]
	v_mfma_f32_16x16x32_bf16 v[178:181], v[218:221], v[62:65], v[110:113]
	v_mfma_f32_16x16x32_bf16 v[110:113], v[78:81], v[82:85], v[118:121]
	v_mfma_f32_16x16x32_bf16 v[158:161], v[198:201], v[86:89], v[110:113]
	v_mfma_f32_16x16x32_bf16 v[110:113], v[202:205], v[82:85], v[114:117]
	v_mfma_f32_16x16x32_bf16 v[106:109], v[78:81], v[98:101], v[106:109]
	v_mfma_f32_16x16x32_bf16 v[90:93], v[202:205], v[98:101], v[90:93]
	v_mfma_f32_16x16x32_bf16 v[74:77], v[78:81], v[222:225], v[74:77]
	v_mfma_f32_16x16x32_bf16 v[54:57], v[202:205], v[222:225], v[54:57]
	v_mfma_f32_16x16x32_bf16 v[154:157], v[218:221], v[86:89], v[110:113]
	v_mfma_f32_16x16x32_bf16 v[134:137], v[198:201], v[102:105], v[106:109]
	v_mfma_f32_16x16x32_bf16 v[130:133], v[218:221], v[102:105], v[90:93]
	v_mfma_f32_16x16x32_bf16 v[110:113], v[198:201], v[248:251], v[74:77]
	v_mfma_f32_16x16x32_bf16 v[106:109], v[218:221], v[248:251], v[54:57]
	s_setprio 0
	s_barrier
	ds_read_b128 v[90:93], v232 offset:49152
	ds_read_b128 v[114:117], v232 offset:50176
	ds_read_b128 v[118:121], v232 offset:51200
	ds_read_b128 v[232:235], v232 offset:52224
	s_waitcnt vmcnt(0)
	s_barrier
	s_waitcnt lgkmcnt(0)
	s_setprio 2
	s_waitcnt lgkmcnt(0)
	v_mfma_f32_16x16x32_bf16 v[30:33], v[90:93], v[58:61], v[30:33]
	v_mfma_f32_16x16x32_bf16 v[26:29], v[118:121], v[58:61], v[26:29]
	v_mfma_f32_16x16x32_bf16 v[22:25], v[90:93], v[82:85], v[22:25]
	v_mfma_f32_16x16x32_bf16 v[18:21], v[118:121], v[82:85], v[18:21]
	v_mfma_f32_16x16x32_bf16 v[14:17], v[90:93], v[98:101], v[14:17]
	v_mfma_f32_16x16x32_bf16 v[10:13], v[118:121], v[98:101], v[10:13]
	v_mfma_f32_16x16x32_bf16 v[6:9], v[90:93], v[222:225], v[6:9]
	v_mfma_f32_16x16x32_bf16 v[2:5], v[118:121], v[222:225], v[2:5]
	v_mfma_f32_16x16x32_bf16 v[174:177], v[114:117], v[62:65], v[30:33]
	v_mfma_f32_16x16x32_bf16 v[170:173], v[232:235], v[62:65], v[26:29]
	v_mfma_f32_16x16x32_bf16 v[150:153], v[114:117], v[86:89], v[22:25]
	v_mfma_f32_16x16x32_bf16 v[146:149], v[232:235], v[86:89], v[18:21]
	v_mfma_f32_16x16x32_bf16 v[126:129], v[114:117], v[102:105], v[14:17]
	v_mfma_f32_16x16x32_bf16 v[122:125], v[232:235], v[102:105], v[10:13]
	v_mfma_f32_16x16x32_bf16 v[102:105], v[114:117], v[248:251], v[6:9]
	v_mfma_f32_16x16x32_bf16 v[98:101], v[232:235], v[248:251], v[2:5]
	s_setprio 0
	s_barrier
	s_nop 0
	ds_read_b128 v[2:5], v0 offset:49152
	ds_read_b128 v[6:9], v0 offset:50176
	ds_read_b128 v[18:21], v0 offset:51200
	ds_read_b128 v[22:25], v0 offset:52224
	ds_read_b128 v[26:29], v0 offset:53248
	ds_read_b128 v[222:225], v0 offset:54272
	ds_read_b128 v[248:251], v0 offset:55296
	ds_read_b128 v[244:247], v0 offset:56320
	s_barrier
	s_waitcnt lgkmcnt(0)
	s_setprio 2
	s_waitcnt lgkmcnt(0)
	v_mfma_f32_16x16x32_bf16 v[10:13], v[78:81], v[2:5], v[34:37]
	v_mfma_f32_16x16x32_bf16 v[86:89], v[198:201], v[6:9], v[10:13]
	v_mfma_f32_16x16x32_bf16 v[10:13], v[202:205], v[2:5], v[38:41]
	v_mfma_f32_16x16x32_bf16 v[82:85], v[218:221], v[6:9], v[10:13]
	v_mfma_f32_16x16x32_bf16 v[10:13], v[78:81], v[18:21], v[42:45]
	v_mfma_f32_16x16x32_bf16 v[62:65], v[198:201], v[22:25], v[10:13]
	v_mfma_f32_16x16x32_bf16 v[10:13], v[202:205], v[18:21], v[46:49]
	v_mfma_f32_16x16x32_bf16 v[58:61], v[218:221], v[22:25], v[10:13]
	v_mfma_f32_16x16x32_bf16 v[10:13], v[78:81], v[26:29], v[50:53]
	v_mfma_f32_16x16x32_bf16 v[38:41], v[198:201], v[222:225], v[10:13]
	v_mfma_f32_16x16x32_bf16 v[10:13], v[202:205], v[26:29], v[206:209]
	v_mfma_f32_16x16x32_bf16 v[34:37], v[218:221], v[222:225], v[10:13]
	v_mfma_f32_16x16x32_bf16 v[10:13], v[78:81], v[248:251], v[210:213]
	v_mfma_f32_16x16x32_bf16 v[14:17], v[198:201], v[244:247], v[10:13]
	v_mfma_f32_16x16x32_bf16 v[10:13], v[202:205], v[248:251], v[66:69]
	v_mfma_f32_16x16x32_bf16 v[10:13], v[218:221], v[244:247], v[10:13]
	s_setprio 0
	s_setprio 2
	v_mfma_f32_16x16x32_bf16 v[30:33], v[90:93], v[2:5], v[70:73]
	v_mfma_f32_16x16x32_bf16 v[2:5], v[118:121], v[2:5], v[138:141]
	v_mfma_f32_16x16x32_bf16 v[74:77], v[232:235], v[6:9], v[2:5]
	v_mfma_f32_16x16x32_bf16 v[2:5], v[90:93], v[18:21], v[142:145]
	v_mfma_f32_16x16x32_bf16 v[54:57], v[114:117], v[22:25], v[2:5]
	v_mfma_f32_16x16x32_bf16 v[2:5], v[118:121], v[18:21], v[214:217]
	v_mfma_f32_16x16x32_bf16 v[50:53], v[232:235], v[22:25], v[2:5]
	v_mfma_f32_16x16x32_bf16 v[2:5], v[90:93], v[26:29], v[94:97]
	v_mfma_f32_16x16x32_bf16 v[78:81], v[114:117], v[6:9], v[30:33]
	v_mfma_f32_16x16x32_bf16 v[30:33], v[114:117], v[222:225], v[2:5]
	v_mfma_f32_16x16x32_bf16 v[2:5], v[118:121], v[26:29], v[162:165]
	v_mfma_f32_16x16x32_bf16 v[26:29], v[232:235], v[222:225], v[2:5]
	v_mfma_f32_16x16x32_bf16 v[2:5], v[90:93], v[248:251], v[166:169]
	v_mfma_f32_16x16x32_bf16 v[6:9], v[114:117], v[244:247], v[2:5]
	v_mfma_f32_16x16x32_bf16 v[2:5], v[118:121], v[248:251], v[186:189]
	v_mfma_f32_16x16x32_bf16 v[2:5], v[232:235], v[244:247], v[2:5]
	s_setprio 0
	s_barrier
	s_and_saveexec_b64 s[0:1], s[38:39]
	s_cbranch_execz .LBB0_947
	s_barrier
